# mix_state gate softplus: removed the never-taken denormal-range scaling around log(1+exp(-|x|)) (argument is in [1,2]); bit-identical
# speedup vs baseline: 1.0060x; 1.0006x over previous
.LBB0_656:
	s_cmp_lg_u32 s14, 0
	s_cbranch_scc0 .LBB0_695
	s_waitcnt vmcnt(11)
	ds_write_b16 v199, v0
	ds_write_b16_d16_hi v199, v0 offset:144
	ds_write_b16 v199, v1 offset:288
	ds_write_b16_d16_hi v199, v1 offset:432
	ds_write_b16 v199, v2 offset:576
	ds_write_b16_d16_hi v199, v2 offset:720
	ds_write_b16 v199, v3 offset:864
	ds_write_b16_d16_hi v199, v3 offset:1008
	s_waitcnt vmcnt(10)
	ds_write_b16 v199, v4 offset:9216
	ds_write_b16_d16_hi v199, v4 offset:9360
	ds_write_b16 v199, v5 offset:9504
	ds_write_b16_d16_hi v199, v5 offset:9648
	ds_write_b16 v199, v6 offset:9792
	ds_write_b16_d16_hi v199, v6 offset:9936
	ds_write_b16 v199, v7 offset:10080
	ds_write_b16_d16_hi v199, v7 offset:10224
	s_waitcnt vmcnt(9)
	ds_write_b16 v199, v8 offset:18432
	ds_write_b16_d16_hi v199, v8 offset:18576
	ds_write_b16 v199, v9 offset:18720
	ds_write_b16_d16_hi v199, v9 offset:18864
	ds_write_b16 v199, v10 offset:19008
	ds_write_b16_d16_hi v199, v10 offset:19152
	ds_write_b16 v199, v11 offset:19296
	ds_write_b16_d16_hi v199, v11 offset:19440
	s_waitcnt vmcnt(8)
	ds_write_b16 v199, v12 offset:27648
	ds_write_b16_d16_hi v199, v12 offset:27792
	ds_write_b16 v199, v13 offset:27936
	ds_write_b16_d16_hi v199, v13 offset:28080
	global_load_dwordx4 v[106:109], v49, s[26:27]
	global_load_dwordx4 v[110:113], v49, s[24:25]
	global_load_dwordx4 v[114:117], v49, s[24:25] offset:768
	global_load_dwordx4 v[126:129], v49, s[24:25] offset:1536
	global_load_dwordx4 v[134:137], v49, s[24:25] offset:2304
	global_load_dwordx4 v[138:141], v49, s[24:25] offset:3072
	v_readlane_b32 s6, v254, 23
	global_load_dwordx4 v[142:145], v49, s[24:25] offset:3840
	v_readlane_b32 s7, v254, 24
	v_readlane_b32 s18, v254, 25
	v_readlane_b32 s19, v254, 26
	v_readlane_b32 s20, v254, 27
	v_readlane_b32 s21, v254, 28
	v_readlane_b32 s28, v254, 29
	global_load_dwordx4 v[154:157], v49, s[6:7]
	v_readlane_b32 s29, v254, 30
	global_load_dwordx4 v[158:161], v49, s[18:19]
	v_readlane_b32 vcc_lo, v254, 31
	global_load_dwordx4 v[162:165], v49, s[20:21]
	v_readlane_b32 s30, v254, 33
	v_readlane_b32 s34, v254, 35
	v_readlane_b32 s36, v254, 37
	global_load_dwordx4 v[166:169], v49, s[28:29]
	v_readlane_b32 vcc_hi, v254, 32
	v_readlane_b32 s31, v254, 34
	v_readlane_b32 s35, v254, 36
	v_readlane_b32 s37, v254, 38
	v_readlane_b32 s38, v254, 39
	v_readlane_b32 s40, v254, 41
	global_load_dwordx4 v[170:173], v49, vcc
	global_load_dwordx4 v[174:177], v49, s[30:31]
	global_load_dwordx4 v[178:181], v49, s[34:35]
	global_load_dwordx4 v[182:185], v49, s[36:37]
	ds_write_b16 v199, v14 offset:28224
	ds_write_b16_d16_hi v199, v14 offset:28368
	ds_write_b16 v199, v15 offset:28512
	ds_write_b16_d16_hi v199, v15 offset:28656
	s_waitcnt vmcnt(22)
	ds_write_b16 v199, v16 offset:36864
	ds_write_b16_d16_hi v199, v16 offset:37008
	ds_write_b16 v199, v17 offset:37152
	ds_write_b16_d16_hi v199, v17 offset:37296
	ds_write_b16 v199, v18 offset:37440
	ds_write_b16_d16_hi v199, v18 offset:37584
	ds_write_b16 v199, v19 offset:37728
	ds_write_b16_d16_hi v199, v19 offset:37872
	s_waitcnt vmcnt(21)
	ds_write_b16 v199, v20 offset:46080
	v_readlane_b32 s39, v254, 40
	v_readlane_b32 s41, v254, 42
	s_lshl_b32 s0, s12, 6
	s_ashr_i32 s1, s0, 31
	s_mul_i32 s5, s13, 0x900
	s_mul_hi_i32 s4, s13, 0x900
	global_load_dwordx4 v[186:189], v49, s[38:39]
	global_load_dwordx4 v[190:193], v49, s[40:41]
	s_add_u32 s0, s5, s0
	s_addc_u32 s1, s4, s1
	s_lshr_b64 s[4:5], s[0:1], 6
	s_lshr_b32 s0, s1, 6
	s_mul_i32 s0, s0, 48
	s_mul_hi_u32 s1, s4, 48
	s_add_i32 s15, s1, s0
	v_lshlrev_b32_e32 v48, 4, v198
	v_readlane_b32 s0, v253, 58
	v_lshlrev_b32_e32 v242, 16, v24
	v_and_b32_e32 v48, 0x3f0, v48
	v_readlane_b32 s1, v253, 59
	v_and_b32_e32 v223, 0xffff0000, v24
	v_lshlrev_b32_e32 v222, 16, v25
	v_lshl_add_u64 v[202:203], s[0:1], 0, v[48:49]
	v_and_b32_e32 v221, 0xffff0000, v25
	v_lshlrev_b32_e32 v220, 16, v26
	v_and_b32_e32 v219, 0xffff0000, v26
	v_lshlrev_b32_e32 v218, 16, v27
	v_and_b32_e32 v217, 0xffff0000, v27
	v_lshlrev_b32_e32 v216, 16, v28
	v_and_b32_e32 v215, 0xffff0000, v28
	v_lshlrev_b32_e32 v214, 16, v29
	v_and_b32_e32 v213, 0xffff0000, v29
	v_lshlrev_b32_e32 v206, 16, v30
	v_and_b32_e32 v207, 0xffff0000, v30
	v_lshlrev_b32_e32 v204, 16, v31
	v_and_b32_e32 v205, 0xffff0000, v31
	ds_write_b16_d16_hi v199, v20 offset:46224
	ds_write_b16 v199, v21 offset:46368
	ds_write_b16_d16_hi v199, v21 offset:46512
	ds_write_b16 v199, v22 offset:46656
	ds_write_b16_d16_hi v199, v22 offset:46800
	ds_write_b16 v199, v23 offset:46944
	ds_write_b16_d16_hi v199, v23 offset:47088
	s_waitcnt vmcnt(15)
	v_fma_f32 v48, v110, v242, v106
	s_waitcnt vmcnt(14)
	v_fmac_f32_e32 v48, v114, v223
	s_waitcnt vmcnt(13)
	v_fmac_f32_e32 v48, v126, v222
	s_waitcnt vmcnt(12)
	v_fmac_f32_e32 v48, v134, v221
	s_waitcnt vmcnt(11)
	v_fmac_f32_e32 v48, v138, v220
	global_load_dwordx4 v[58:61], v49, s[26:27] offset:16
	global_load_dwordx4 v[62:65], v49, s[24:25] offset:16
	s_waitcnt vmcnt(12)
	v_fmac_f32_e32 v48, v142, v219
	global_load_dwordx4 v[86:89], v49, s[6:7] offset:16
	global_load_dwordx4 v[102:105], v49, vcc offset:16
	s_add_i32 s0, s13, 32
	s_mul_i32 s90, s4, 48
	s_mul_hi_i32 s1, s0, 36
	s_mul_i32 s0, s0, 36
	s_waitcnt vmcnt(13)
	v_fmac_f32_e32 v48, v154, v218
	s_ashr_i32 s4, s12, 31
	s_waitcnt vmcnt(12)
	v_fmac_f32_e32 v48, v158, v217
	s_add_u32 s0, s0, s12
	s_waitcnt vmcnt(11)
	v_fmac_f32_e32 v48, v162, v216
	s_addc_u32 s1, s1, s4
	s_lshl_b64 s[0:1], s[0:1], 3
	s_add_u32 s0, s0, s22
	s_waitcnt vmcnt(10)
	v_fmac_f32_e32 v48, v166, v215
	s_addc_u32 s1, s1, s23
	s_mulk_i32 s1, 0xc0
	s_mul_hi_u32 s4, s0, 0xc0
	s_add_i32 s89, s4, s1
	s_mul_i32 s88, s0, 0xc0
	v_fma_f32 v111, v111, v242, v107
	s_waitcnt vmcnt(9)
	v_fmac_f32_e32 v48, v170, v214
	s_waitcnt vmcnt(8)
	v_fmac_f32_e32 v48, v174, v213
	s_waitcnt vmcnt(7)
	v_mov_b32_e32 v118, v178
	s_waitcnt vmcnt(6)
	v_mov_b32_e32 v119, v182
	v_pk_mul_f32 v[118:119], v[118:119], v[206:207]
	v_fmac_f32_e32 v111, v115, v223
	v_add_f32_e32 v48, v48, v118
	v_add_f32_e32 v48, v48, v119
	v_fmac_f32_e32 v111, v127, v222
	v_fmac_f32_e32 v111, v135, v221
	v_fmac_f32_e32 v111, v139, v220
	v_fmac_f32_e32 v111, v143, v219
	v_fmac_f32_e32 v111, v155, v218
	v_fmac_f32_e32 v111, v159, v217
	v_fmac_f32_e32 v111, v163, v216
	v_fmac_f32_e32 v111, v167, v215
	v_fmac_f32_e32 v111, v171, v214
	v_mov_b32_e32 v182, v179
	v_fmac_f32_e32 v111, v175, v213
	global_load_dwordx4 v[66:69], v49, s[24:25] offset:784
	global_load_dwordx4 v[70:73], v49, s[24:25] offset:1552
	s_waitcnt vmcnt(7)
	v_mov_b32_e32 v118, v186
	s_waitcnt vmcnt(6)
	v_mov_b32_e32 v119, v190
	v_pk_mul_f32 v[118:119], v[118:119], v[204:205]
	v_mov_b32_e32 v190, v187
	v_add_f32_e32 v48, v48, v118
	v_add_f32_e32 v48, v48, v119
	v_mul_f32_e64 v106, |v48|, s93
	v_exp_f32_e32 v106, v106
	v_max_f32_e64 v48, -v48, 0
	v_mov_b32_e32 v114, v49
	global_load_dwordx4 v[74:77], v49, s[24:25] offset:2320
	global_load_dwordx4 v[78:81], v49, s[24:25] offset:3088
	v_add_f32_e32 v106, 1.0, v106
	s_nop 0
	global_load_dwordx4 v[82:85], v49, s[24:25] offset:3856
	global_load_dwordx4 v[98:101], v49, s[28:29] offset:16
	s_nop 0
	s_nop 0
	v_log_f32_e32 v106, v106
	global_load_dwordx4 v[90:93], v49, s[18:19] offset:16
	global_load_dwordx4 v[94:97], v49, s[20:21] offset:16
	global_load_dwordx4 v[118:121], v49, s[30:31] offset:16
	global_load_dwordx4 v[122:125], v49, s[34:35] offset:16
	global_load_dwordx4 v[130:133], v49, s[36:37] offset:16
	v_mul_f32_e32 v110, 0x3f317217, v106
	v_fma_f32 v110, v106, s94, -v110
	v_fmac_f32_e32 v110, 0x3377d1cf, v106
	v_fmac_f32_e32 v110, 0x3f317217, v106
	v_cmp_lt_f32_e64 s[0:1], |v106|, s95
	global_load_dwordx4 v[146:149], v49, s[38:39] offset:16
	global_load_dwordx4 v[150:153], v49, s[40:41] offset:16
	v_cndmask_b32_e64 v106, v106, v110, s[0:1]
	s_nop 0
	s_nop 0
	v_add_f32_e32 v48, v48, v106
	v_mul_f32_e32 v106, 0xbd800000, v48
	v_mov_b32_e32 v110, v49
	v_fma_f32 v108, v112, v242, v108
	v_fmac_f32_e32 v108, v116, v223
	v_mov_b32_dpp v110, v106 row_shr:1 row_mask:0xf bank_mask:0xf
	v_fmac_f32_e32 v110, 0xbd800000, v48
	v_fmac_f32_e32 v108, v128, v222
	v_fmac_f32_e32 v108, v136, v221
	v_add_f32_dpp v106, v110, v110 row_shr:2 row_mask:0xf bank_mask:0xf bound_ctrl:1
	v_mov_b32_e32 v110, v49
	v_fmac_f32_e32 v108, v140, v220
	v_add_f32_dpp v106, v106, v106 row_shr:4 row_mask:0xf bank_mask:0xf bound_ctrl:1
	v_fmac_f32_e32 v108, v144, v219
	v_fmac_f32_e32 v108, v156, v218
	v_add_f32_dpp v106, v106, v106 row_shr:8 row_mask:0xf bank_mask:0xf bound_ctrl:1
	v_fmac_f32_e32 v108, v160, v217
	v_fmac_f32_e32 v108, v164, v216
	v_mov_b32_dpp v110, v106 row_bcast:15 row_mask:0xa bank_mask:0xf
	v_add_f32_e32 v110, v106, v110
	v_pk_mul_f32 v[106:107], v[182:183], v[206:207]
	v_fmac_f32_e32 v108, v168, v215
	v_add_f32_e32 v106, v111, v106
	v_add_f32_e32 v111, v106, v107
	v_pk_mul_f32 v[106:107], v[190:191], v[204:205]
	v_mov_b32_dpp v114, v110 row_bcast:31 row_mask:0xc bank_mask:0xf
	v_add_f32_e32 v106, v111, v106
	v_add_f32_e32 v106, v106, v107
	v_mul_f32_e64 v107, |v106|, s93
	v_exp_f32_e32 v107, v107
	v_add_f32_e32 v110, v110, v114
	v_max_f32_e64 v106, -v106, 0
	v_readlane_b32 s4, v110, 63
	v_add_f32_e32 v107, 1.0, v107
	s_nop 0
	v_sub_f32_e32 v111, s4, v110
	v_fmac_f32_e32 v110, 0x3d800000, v48
	s_nop 0
	s_nop 0
	v_log_f32_e32 v107, v107
	v_cndmask_b32_e64 v48, v110, v111, s[8:9]
	v_fmac_f32_e32 v108, v172, v214
	v_fmac_f32_e32 v108, v176, v213
	v_mul_f32_e32 v110, 0x3f317217, v107
	v_fma_f32 v110, v107, s94, -v110
	v_fmac_f32_e32 v110, 0x3377d1cf, v107
	v_fmac_f32_e32 v110, 0x3f317217, v107
	v_cmp_lt_f32_e64 s[0:1], |v107|, s95
	v_mov_b32_e32 v114, v49
	v_fmac_f32_e32 v109, v113, v242
	v_cndmask_b32_e64 v107, v107, v110, s[0:1]
	s_nop 0
	s_nop 0
	v_add_f32_e32 v110, v106, v107
	v_mul_f32_e32 v106, 0xbd800000, v110
	v_mov_b32_e32 v107, v49
	v_fmac_f32_e32 v109, v117, v223
	v_fmac_f32_e32 v109, v129, v222
	v_mov_b32_dpp v107, v106 row_shr:1 row_mask:0xf bank_mask:0xf
	v_fmac_f32_e32 v107, 0xbd800000, v110
	v_fmac_f32_e32 v109, v137, v221
	v_fmac_f32_e32 v109, v141, v220
	v_add_f32_dpp v106, v107, v107 row_shr:2 row_mask:0xf bank_mask:0xf bound_ctrl:1
	v_mov_b32_e32 v107, v49
	v_fmac_f32_e32 v109, v145, v219
	v_add_f32_dpp v106, v106, v106 row_shr:4 row_mask:0xf bank_mask:0xf bound_ctrl:1
	v_fmac_f32_e32 v109, v157, v218
	v_fmac_f32_e32 v109, v161, v217
	v_add_f32_dpp v106, v106, v106 row_shr:8 row_mask:0xf bank_mask:0xf bound_ctrl:1
	v_fmac_f32_e32 v109, v165, v216
	v_fmac_f32_e32 v109, v169, v215
	v_mov_b32_dpp v107, v106 row_bcast:15 row_mask:0xa bank_mask:0xf
	v_add_f32_e32 v111, v106, v107
	v_mov_b32_e32 v106, v180
	v_mov_b32_e32 v107, v184
	v_pk_mul_f32 v[106:107], v[106:107], v[206:207]
	v_mov_b32_dpp v114, v111 row_bcast:31 row_mask:0xc bank_mask:0xf
	v_add_f32_e32 v106, v108, v106
	v_add_f32_e32 v108, v106, v107
	v_mov_b32_e32 v106, v188
	v_mov_b32_e32 v107, v192
	v_pk_mul_f32 v[106:107], v[106:107], v[204:205]
	v_fmac_f32_e32 v109, v173, v214
	v_add_f32_e32 v106, v108, v106
	v_add_f32_e32 v106, v106, v107
	v_mul_f32_e64 v107, |v106|, s93
	v_exp_f32_e32 v107, v107
	v_add_f32_e32 v108, v111, v114
	v_max_f32_e64 v106, -v106, 0
	v_readlane_b32 s5, v108, 63
	v_add_f32_e32 v107, 1.0, v107
	s_nop 0
	v_sub_f32_e32 v111, s5, v108
	v_fmac_f32_e32 v108, 0x3d800000, v110
	s_nop 0
	s_nop 0
	v_log_f32_e32 v107, v107
	v_mov_b32_e32 v184, v181
	v_cndmask_b32_e64 v108, v108, v111, s[8:9]
	v_fmac_f32_e32 v109, v177, v213
	v_mul_f32_e32 v110, 0x3f317217, v107
	v_fma_f32 v110, v107, s94, -v110
	v_fmac_f32_e32 v110, 0x3377d1cf, v107
	v_fmac_f32_e32 v110, 0x3f317217, v107
	v_cmp_lt_f32_e64 s[0:1], |v107|, s95
	v_mov_b32_e32 v192, v189
	v_mov_b32_e32 v112, v49
	v_cndmask_b32_e64 v107, v107, v110, s[0:1]
	s_nop 0
	s_nop 0
	v_add_f32_e32 v110, v106, v107
	v_mul_f32_e32 v106, 0xbd800000, v110
	v_mov_b32_e32 v107, v49
	s_waitcnt vmcnt(15)
	v_fma_f32 v58, v62, v242, v58
	s_waitcnt vmcnt(12)
	v_fmac_f32_e32 v58, v66, v223
	v_mov_b32_dpp v107, v106 row_shr:1 row_mask:0xf bank_mask:0xf
	v_fmac_f32_e32 v107, 0xbd800000, v110
	s_waitcnt vmcnt(11)
	v_fmac_f32_e32 v58, v70, v222
	s_waitcnt vmcnt(10)
	v_fmac_f32_e32 v58, v74, v221
	v_add_f32_dpp v106, v107, v107 row_shr:2 row_mask:0xf bank_mask:0xf bound_ctrl:1
	v_mov_b32_e32 v107, v49
	s_waitcnt vmcnt(9)
	v_fmac_f32_e32 v58, v78, v220
	v_add_f32_dpp v106, v106, v106 row_shr:4 row_mask:0xf bank_mask:0xf bound_ctrl:1
	s_waitcnt vmcnt(8)
	v_fmac_f32_e32 v58, v82, v219
	v_fmac_f32_e32 v58, v86, v218
	v_add_f32_dpp v106, v106, v106 row_shr:8 row_mask:0xf bank_mask:0xf bound_ctrl:1
	s_waitcnt vmcnt(6)
	v_fmac_f32_e32 v58, v90, v217
	s_waitcnt vmcnt(5)
	v_fmac_f32_e32 v58, v94, v216
	v_mov_b32_dpp v107, v106 row_bcast:15 row_mask:0xa bank_mask:0xf
	v_add_f32_e32 v111, v106, v107
	v_pk_mul_f32 v[106:107], v[184:185], v[206:207]
	v_fmac_f32_e32 v58, v98, v215
	v_add_f32_e32 v106, v109, v106
	v_add_f32_e32 v109, v106, v107
	v_pk_mul_f32 v[106:107], v[192:193], v[204:205]
	v_mov_b32_dpp v112, v111 row_bcast:31 row_mask:0xc bank_mask:0xf
	v_add_f32_e32 v106, v109, v106
	v_add_f32_e32 v106, v106, v107
	v_mul_f32_e64 v107, |v106|, s93
	v_exp_f32_e32 v107, v107
	v_add_f32_e32 v109, v111, v112
	v_max_f32_e64 v106, -v106, 0
	v_readlane_b32 s6, v109, 63
	v_add_f32_e32 v107, 1.0, v107
	s_nop 0
	v_sub_f32_e32 v111, s6, v109
	v_fmac_f32_e32 v109, 0x3d800000, v110
	s_nop 0
	s_nop 0
	v_log_f32_e32 v107, v107
	v_cndmask_b32_e64 v109, v109, v111, s[8:9]
	v_fmac_f32_e32 v58, v102, v214
	s_waitcnt vmcnt(4)
	v_fmac_f32_e32 v58, v118, v213
	v_mul_f32_e32 v110, 0x3f317217, v107
	v_fma_f32 v110, v107, s94, -v110
	v_fmac_f32_e32 v110, 0x3377d1cf, v107
	v_fmac_f32_e32 v110, 0x3f317217, v107
	v_cmp_lt_f32_e64 s[0:1], |v107|, s95
	v_mov_b32_e32 v112, v49
	v_fma_f32 v63, v63, v242, v59
	v_cndmask_b32_e64 v107, v107, v110, s[0:1]
	s_nop 0
	s_nop 0
	v_add_f32_e32 v110, v106, v107
	v_mul_f32_e32 v106, 0xbd800000, v110
	v_mov_b32_e32 v107, v49
	v_fmac_f32_e32 v63, v67, v223
	v_fmac_f32_e32 v63, v71, v222
	v_mov_b32_dpp v107, v106 row_shr:1 row_mask:0xf bank_mask:0xf
	v_fmac_f32_e32 v107, 0xbd800000, v110
	v_fmac_f32_e32 v63, v75, v221
	v_fmac_f32_e32 v63, v79, v220
	v_add_f32_dpp v106, v107, v107 row_shr:2 row_mask:0xf bank_mask:0xf bound_ctrl:1
	v_mov_b32_e32 v107, v49
	v_fmac_f32_e32 v63, v83, v219
	v_add_f32_dpp v106, v106, v106 row_shr:4 row_mask:0xf bank_mask:0xf bound_ctrl:1
	v_fmac_f32_e32 v63, v87, v218
	v_fmac_f32_e32 v63, v91, v217
	v_add_f32_dpp v106, v106, v106 row_shr:8 row_mask:0xf bank_mask:0xf bound_ctrl:1
	v_fmac_f32_e32 v63, v95, v216
	v_fmac_f32_e32 v63, v99, v215
	v_mov_b32_dpp v107, v106 row_bcast:15 row_mask:0xa bank_mask:0xf
	v_add_f32_e32 v111, v106, v107
	s_waitcnt vmcnt(3)
	v_mov_b32_e32 v106, v122
	s_waitcnt vmcnt(2)
	v_mov_b32_e32 v107, v130
	v_pk_mul_f32 v[106:107], v[106:107], v[206:207]
	v_mov_b32_dpp v112, v111 row_bcast:31 row_mask:0xc bank_mask:0xf
	v_add_f32_e32 v58, v58, v106
	v_add_f32_e32 v58, v58, v107
	s_waitcnt vmcnt(1)
	v_mov_b32_e32 v106, v146
	s_waitcnt vmcnt(0)
	v_mov_b32_e32 v107, v150
	v_pk_mul_f32 v[106:107], v[106:107], v[204:205]
	v_add_f32_e32 v66, v111, v112
	v_add_f32_e32 v58, v58, v106
	v_add_f32_e32 v58, v58, v107
	v_mul_f32_e64 v62, |v58|, s93
	v_exp_f32_e32 v62, v62
	v_readlane_b32 s7, v66, 63
	v_max_f32_e64 v58, -v58, 0
	v_fmac_f32_e32 v63, v103, v214
	v_add_f32_e32 v62, 1.0, v62
	s_nop 0
	v_sub_f32_e32 v70, s7, v66
	v_fmac_f32_e32 v66, 0x3d800000, v110
	s_nop 0
	s_nop 0
	v_log_f32_e32 v62, v62
	v_cndmask_b32_e64 v66, v66, v70, s[8:9]
	v_mov_b32_e32 v130, v123
	v_fmac_f32_e32 v63, v119, v213
	v_mul_f32_e32 v70, 0x3f317217, v62
	v_fma_f32 v70, v62, s94, -v70
	v_fmac_f32_e32 v70, 0x3377d1cf, v62
	v_fmac_f32_e32 v70, 0x3f317217, v62
	v_cmp_lt_f32_e64 s[0:1], |v62|, s95
	v_mov_b32_e32 v150, v147
	v_mov_b32_e32 v74, v49
	v_cndmask_b32_e64 v62, v62, v70, s[0:1]
	s_nop 0
	s_nop 0
	v_add_f32_e32 v62, v58, v62
	v_mul_f32_e32 v58, 0xbd800000, v62
	v_mov_b32_e32 v70, v49
	v_fma_f32 v60, v64, v242, v60
	v_fmac_f32_e32 v60, v68, v223
	v_mov_b32_dpp v70, v58 row_shr:1 row_mask:0xf bank_mask:0xf
	v_fmac_f32_e32 v70, 0xbd800000, v62
	v_fmac_f32_e32 v60, v72, v222
	v_fmac_f32_e32 v60, v76, v221
	v_add_f32_dpp v58, v70, v70 row_shr:2 row_mask:0xf bank_mask:0xf bound_ctrl:1
	v_mov_b32_e32 v70, v49
	v_fmac_f32_e32 v60, v80, v220
	v_add_f32_dpp v58, v58, v58 row_shr:4 row_mask:0xf bank_mask:0xf bound_ctrl:1
	v_fmac_f32_e32 v60, v84, v219
	v_fmac_f32_e32 v60, v88, v218
	v_add_f32_dpp v58, v58, v58 row_shr:8 row_mask:0xf bank_mask:0xf bound_ctrl:1
	v_fmac_f32_e32 v60, v92, v217
	v_fmac_f32_e32 v60, v96, v216
	v_mov_b32_dpp v70, v58 row_bcast:15 row_mask:0xa bank_mask:0xf
	v_add_f32_e32 v70, v58, v70
	v_pk_mul_f32 v[58:59], v[130:131], v[206:207]
	v_fmac_f32_e32 v60, v100, v215
	v_add_f32_e32 v58, v63, v58
	v_add_f32_e32 v63, v58, v59
	v_pk_mul_f32 v[58:59], v[150:151], v[204:205]
	v_mov_b32_dpp v74, v70 row_bcast:31 row_mask:0xc bank_mask:0xf
	v_add_f32_e32 v58, v63, v58
	v_add_f32_e32 v58, v58, v59
	v_mul_f32_e64 v59, |v58|, s93
	v_exp_f32_e32 v59, v59
	v_add_f32_e32 v63, v70, v74
	v_max_f32_e64 v58, -v58, 0
	v_readlane_b32 s20, v63, 63
	v_add_f32_e32 v59, 1.0, v59
	s_nop 0
	v_sub_f32_e32 v67, s20, v63
	v_fmac_f32_e32 v63, 0x3d800000, v62
	s_nop 0
	s_nop 0
	v_log_f32_e32 v59, v59
	v_cndmask_b32_e64 v62, v63, v67, s[8:9]
	v_fmac_f32_e32 v60, v104, v214
	v_fmac_f32_e32 v60, v120, v213
	v_mul_f32_e32 v63, 0x3f317217, v59
	v_fma_f32 v63, v59, s94, -v63
	v_fmac_f32_e32 v63, 0x3377d1cf, v59
	v_fmac_f32_e32 v63, 0x3f317217, v59
	v_cmp_lt_f32_e64 s[0:1], |v59|, s95
	v_mov_b32_e32 v70, v49
	v_fmac_f32_e32 v61, v65, v242
	v_cndmask_b32_e64 v59, v59, v63, s[0:1]
	s_nop 0
	s_nop 0
	v_add_f32_e32 v63, v58, v59
	v_mul_f32_e32 v58, 0xbd800000, v63
	v_mov_b32_e32 v59, v49
	v_fmac_f32_e32 v61, v69, v223
	v_fmac_f32_e32 v61, v73, v222
	v_mov_b32_dpp v59, v58 row_shr:1 row_mask:0xf bank_mask:0xf
	v_fmac_f32_e32 v59, 0xbd800000, v63
	v_fmac_f32_e32 v61, v77, v221
	v_fmac_f32_e32 v61, v81, v220
	v_add_f32_dpp v58, v59, v59 row_shr:2 row_mask:0xf bank_mask:0xf bound_ctrl:1
	v_mov_b32_e32 v59, v49
	v_fmac_f32_e32 v61, v85, v219
	v_add_f32_dpp v58, v58, v58 row_shr:4 row_mask:0xf bank_mask:0xf bound_ctrl:1
	v_fmac_f32_e32 v61, v89, v218
	v_fmac_f32_e32 v61, v93, v217
	v_add_f32_dpp v58, v58, v58 row_shr:8 row_mask:0xf bank_mask:0xf bound_ctrl:1
	v_fmac_f32_e32 v61, v97, v216
	v_fmac_f32_e32 v61, v101, v215
	v_mov_b32_dpp v59, v58 row_bcast:15 row_mask:0xa bank_mask:0xf
	v_add_f32_e32 v67, v58, v59
	v_mov_b32_e32 v58, v124
	v_mov_b32_e32 v59, v132
	v_pk_mul_f32 v[58:59], v[58:59], v[206:207]
	v_mov_b32_dpp v70, v67 row_bcast:31 row_mask:0xc bank_mask:0xf
	v_add_f32_e32 v58, v60, v58
	v_add_f32_e32 v60, v58, v59
	v_mov_b32_e32 v58, v148
	v_mov_b32_e32 v59, v152
	v_pk_mul_f32 v[58:59], v[58:59], v[204:205]
	v_fmac_f32_e32 v61, v105, v214
	v_add_f32_e32 v58, v60, v58
	v_add_f32_e32 v58, v58, v59
	v_mul_f32_e64 v59, |v58|, s93
	v_exp_f32_e32 v59, v59
	v_add_f32_e32 v60, v67, v70
	v_max_f32_e64 v58, -v58, 0
	v_readlane_b32 s21, v60, 63
	v_add_f32_e32 v59, 1.0, v59
	s_nop 0
	v_sub_f32_e32 v64, s21, v60
	v_fmac_f32_e32 v60, 0x3d800000, v63
	s_nop 0
	s_nop 0
	v_log_f32_e32 v59, v59
	v_mov_b32_e32 v132, v125
	v_cndmask_b32_e64 v60, v60, v64, s[8:9]
	v_fmac_f32_e32 v61, v121, v213
	v_mul_f32_e32 v63, 0x3f317217, v59
	v_fma_f32 v63, v59, s94, -v63
	v_fmac_f32_e32 v63, 0x3377d1cf, v59
	v_fmac_f32_e32 v63, 0x3f317217, v59
	v_cmp_lt_f32_e64 s[0:1], |v59|, s95
	v_mov_b32_e32 v152, v149
	v_mov_b32_e32 v67, v49
	v_cndmask_b32_e64 v59, v59, v63, s[0:1]
	s_nop 0
	s_nop 0
	v_add_f32_e32 v63, v58, v59
	v_mul_f32_e32 v58, 0xbd800000, v63
	v_mov_b32_e32 v59, v49
	v_mul_f32_e32 v48, 0x3fb8aa3b, v48
	v_exp_f32_e32 v48, v48
	v_mov_b32_dpp v59, v58 row_shr:1 row_mask:0xf bank_mask:0xf
	v_fmac_f32_e32 v59, 0xbd800000, v63
	v_and_b32_e32 v68, 0xffff0000, v33
	v_lshlrev_b32_e32 v69, 16, v34
	v_add_f32_dpp v58, v59, v59 row_shr:2 row_mask:0xf bank_mask:0xf bound_ctrl:1
	v_mov_b32_e32 v59, v49
	v_and_b32_e32 v70, 0xffff0000, v34
	v_add_f32_dpp v58, v58, v58 row_shr:4 row_mask:0xf bank_mask:0xf bound_ctrl:1
	v_lshlrev_b32_e32 v71, 16, v35
	v_and_b32_e32 v72, 0xffff0000, v35
	v_add_f32_dpp v58, v58, v58 row_shr:8 row_mask:0xf bank_mask:0xf bound_ctrl:1
	s_nop 1
	v_mov_b32_dpp v59, v58 row_bcast:15 row_mask:0xa bank_mask:0xf
	v_add_f32_e32 v64, v58, v59
	v_pk_mul_f32 v[58:59], v[132:133], v[206:207]
	s_nop 0
	v_add_f32_e32 v58, v61, v58
	v_add_f32_e32 v61, v58, v59
	v_pk_mul_f32 v[58:59], v[152:153], v[204:205]
	v_mov_b32_dpp v67, v64 row_bcast:31 row_mask:0xc bank_mask:0xf
	v_add_f32_e32 v58, v61, v58
	v_add_f32_e32 v58, v58, v59
	v_mul_f32_e64 v59, |v58|, s93
	v_exp_f32_e32 v59, v59
	v_add_f32_e32 v61, v64, v67
	v_max_f32_e64 v58, -v58, 0
	v_readlane_b32 s18, v61, 63
	v_add_f32_e32 v59, 1.0, v59
	s_nop 0
	v_sub_f32_e32 v64, s18, v61
	v_fmac_f32_e32 v61, 0x3d800000, v63
	s_nop 0
	s_nop 0
	v_log_f32_e32 v59, v59
	v_cndmask_b32_e64 v61, v61, v64, s[8:9]
	v_lshlrev_b32_e32 v64, 16, v32
	v_and_b32_e32 v65, 0xffff0000, v32
	v_mul_f32_e32 v63, 0x3f317217, v59
	v_fma_f32 v63, v59, s94, -v63
	v_fmac_f32_e32 v63, 0x3377d1cf, v59
	v_fmac_f32_e32 v63, 0x3f317217, v59
	v_cmp_lt_f32_e64 s[0:1], |v59|, s95
	v_lshlrev_b32_e32 v67, 16, v33
	s_nop 0
	v_cndmask_b32_e64 v59, v59, v63, s[0:1]
	s_nop 0
	s_nop 0
	v_add_f32_e32 v58, v58, v59
	v_mul_f32_e32 v59, 0xbd800000, v58
	v_mov_b32_e32 v63, v49
	v_readlane_b32 s0, v253, 63
	s_add_u32 s0, s90, s0
	v_mov_b32_dpp v63, v59 row_shr:1 row_mask:0xf bank_mask:0xf
	v_fmac_f32_e32 v63, 0xbd800000, v58
	v_readlane_b32 s1, v253, 62
	s_addc_u32 s1, s15, s1
	v_add_f32_dpp v59, v63, v63 row_shr:2 row_mask:0xf bank_mask:0xf bound_ctrl:1
	v_mov_b32_e32 v63, v49
	s_lshl_b64 s[0:1], s[0:1], 10
	v_add_f32_dpp v59, v59, v59 row_shr:4 row_mask:0xf bank_mask:0xf bound_ctrl:1
	s_nop 1
	v_add_f32_dpp v59, v59, v59 row_shr:8 row_mask:0xf bank_mask:0xf bound_ctrl:1
	s_nop 1
	v_mov_b32_dpp v63, v59 row_bcast:15 row_mask:0xa bank_mask:0xf
	v_add_f32_e32 v59, v59, v63
	v_mov_b32_e32 v63, v49
	s_nop 1
	v_mov_b32_dpp v63, v59 row_bcast:31 row_mask:0xc bank_mask:0xf
	v_add_f32_e32 v59, v59, v63
	s_nop 0
	v_readlane_b32 s19, v59, 63
	s_nop 1
	v_sub_f32_e32 v63, s19, v59
	v_fmac_f32_e32 v59, 0x3d800000, v58
	v_cndmask_b32_e64 v58, v59, v63, s[8:9]
	v_mul_f32_e32 v59, 0x3fb8aa3b, v108
	v_exp_f32_e32 v73, v59
	v_mul_f32_e32 v59, 0x3fb8aa3b, v109
	v_mul_f32_e32 v58, 0x3fb8aa3b, v58
	v_exp_f32_e32 v74, v59
	v_exp_f32_e32 v78, v58
	v_cvt_pk_bf16_f32 v58, v48, v73
	v_mul_f32_e32 v48, v48, v64
	v_mul_f32_e32 v59, 0x3fb8aa3b, v66
	v_cvt_pk_bf16_f32 v48, v48, s0
	v_exp_f32_e32 v66, v59
	ds_write_b16 v208, v48 offset:55296
	v_mul_f32_e32 v48, v73, v65
	v_mul_f32_e32 v59, 0x3fb8aa3b, v62
	v_cvt_pk_bf16_f32 v48, v48, s0
	v_exp_f32_e32 v75, v59
	ds_write_b16 v208, v48 offset:55440
	v_mul_f32_e32 v48, v74, v67
	v_mul_f32_e32 v59, 0x3fb8aa3b, v60
	v_cvt_pk_bf16_f32 v48, v48, s0
	v_exp_f32_e32 v76, v59
	ds_write_b16 v208, v48 offset:55584
	v_mul_f32_e32 v48, v66, v68
	v_mul_f32_e32 v59, 0x3fb8aa3b, v61
	v_cvt_pk_bf16_f32 v48, v48, s0
	v_exp_f32_e32 v77, v59
	ds_write_b16 v208, v48 offset:55728
	v_mul_f32_e32 v48, v75, v69
	v_cvt_pk_bf16_f32 v48, v48, s0
	ds_write_b16 v208, v48 offset:55872
	v_mul_f32_e32 v48, v76, v70
	v_cvt_pk_bf16_f32 v48, v48, s0
	ds_write_b16 v208, v48 offset:56016
	v_mul_f32_e32 v48, v77, v71
	v_cvt_pk_bf16_f32 v48, v48, s0
	ds_write_b16 v208, v48 offset:56160
	v_mul_f32_e32 v48, v78, v72
	v_cvt_pk_bf16_f32 v59, v74, v66
	v_cvt_pk_bf16_f32 v60, v75, v76
	v_cvt_pk_bf16_f32 v61, v77, v78
	v_lshl_add_u64 v[62:63], v[202:203], 0, s[0:1]
	v_cvt_pk_bf16_f32 v48, v48, s0
	global_store_dwordx4 v[62:63], v[58:61], off
	ds_write_b16 v208, v48 offset:56304
	s_and_saveexec_b64 s[0:1], s[10:11]
	s_cbranch_execz .LBB0_659
	v_mul_f32_e32 v48, s4, v240
	v_exp_f32_e32 v58, v48
	v_mul_f32_e32 v48, s5, v240
	v_exp_f32_e32 v59, v48
	v_mul_f32_e32 v48, s6, v240
	v_exp_f32_e32 v60, v48
	v_mul_f32_e32 v48, s7, v240
	v_exp_f32_e32 v61, v48
	v_mul_f32_e32 v48, s20, v240
	v_exp_f32_e32 v62, v48
	v_mul_f32_e32 v48, s21, v240
	v_exp_f32_e32 v63, v48
	v_mul_f32_e32 v48, s18, v240
	v_exp_f32_e32 v64, v48
	v_mul_f32_e32 v48, s19, v240
	v_exp_f32_e32 v65, v48
	s_add_u32 s4, s16, s88
	s_addc_u32 s5, s17, s89
	global_store_dwordx4 v49, v[58:61], s[4:5]
	global_store_dwordx4 v49, v[62:65], s[4:5] offset:16
.LBB0_659:
	s_or_b64 exec, exec, s[0:1]
	v_readlane_b32 s0, v254, 43
	v_readlane_b32 s1, v254, 44
	v_lshrrev_b32_e32 v182, 6, v198
	v_and_b32_e32 v183, 1, v182
	v_lshrrev_b32_e32 v182, 1, v182
	v_mul_u32_u24_e32 v183, 0x3000, v183
	v_lshl_add_u32 v183, v182, 7, v183
	v_lshl_add_u32 v182, v182, 6, v183
	v_add_u32_e32 v182, 0x1b000, v182
	ds_read_b128 v[58:61], v182 offset:24624
	ds_read_b128 v[126:129], v182 offset:24608
	ds_read_b128 v[62:65], v182 offset:48
	ds_read_b128 v[130:133], v182 offset:32
	ds_read_b128 v[66:69], v182 offset:816
	ds_read_b128 v[134:137], v182 offset:800
	ds_read_b128 v[70:73], v182 offset:1584
	ds_read_b128 v[138:141], v182 offset:1568
	ds_read_b128 v[74:77], v182 offset:2352
	ds_read_b128 v[142:145], v182 offset:2336
	ds_read_b128 v[78:81], v182 offset:3120
	ds_read_b128 v[146:149], v182 offset:3104
	s_waitcnt lgkmcnt(8)
	ds_read_b128 v[82:85], v182 offset:3888
	ds_read_b128 v[150:153], v182 offset:3872
	ds_read_b128 v[86:89], v182 offset:4656
	ds_read_b128 v[154:157], v182 offset:4640
	s_waitcnt lgkmcnt(8)
	v_readlane_b32 s0, v254, 45
	v_readlane_b32 s1, v254, 46
	s_nop 4
	ds_read_b128 v[90:93], v182 offset:5424
	ds_read_b128 v[158:161], v182 offset:5408
	v_readlane_b32 s0, v254, 47
	v_readlane_b32 s1, v254, 48
	s_nop 4
	ds_read_b128 v[94:97], v182 offset:6192
	ds_read_b128 v[162:165], v182 offset:6176
	s_waitcnt lgkmcnt(8)
	v_readlane_b32 s0, v254, 49
	v_readlane_b32 s1, v254, 50
	s_nop 4
	ds_read_b128 v[98:101], v182 offset:6960
	ds_read_b128 v[166:169], v182 offset:6944
	v_readlane_b32 s0, v254, 51
	v_readlane_b32 s1, v254, 52
	s_nop 4
	ds_read_b128 v[102:105], v182 offset:7728
	ds_read_b128 v[170:173], v182 offset:7712
	s_waitcnt lgkmcnt(8)
	v_readlane_b32 s0, v254, 53
	v_readlane_b32 s1, v254, 54
	s_nop 4
	ds_read_b128 v[106:109], v182 offset:8496
	ds_read_b128 v[174:177], v182 offset:8480
	v_readlane_b32 s0, v254, 55
	v_readlane_b32 s1, v254, 56
	s_nop 4
	ds_read_b128 v[110:113], v182 offset:9264
	ds_read_b128 v[178:181], v182 offset:9248
	s_waitcnt lgkmcnt(8)
	v_readlane_b32 s0, v254, 57
	v_readlane_b32 s1, v254, 58
	s_nop 4
	ds_read_b128 v[114:117], v182 offset:10032
	ds_read_b128 v[182:185], v182 offset:10016
	v_readlane_b32 s0, v254, 59
	v_readlane_b32 s1, v254, 60
	s_waitcnt lgkmcnt(14)
	v_fma_f32 v58, v62, v242, v58
	s_waitcnt lgkmcnt(14)
	v_fma_f32 v48, v130, v242, v126
	s_waitcnt lgkmcnt(14)
	v_fmac_f32_e32 v48, v134, v223
	s_waitcnt lgkmcnt(14)
	v_fmac_f32_e32 v48, v138, v222
	s_waitcnt lgkmcnt(14)
	v_fmac_f32_e32 v48, v142, v221
	s_waitcnt lgkmcnt(14)
	v_fmac_f32_e32 v48, v146, v220
	s_waitcnt lgkmcnt(14)
	v_fmac_f32_e32 v48, v150, v219
	s_waitcnt lgkmcnt(14)
	v_fmac_f32_e32 v48, v154, v218
	v_fmac_f32_e32 v129, v133, v242
	v_fmac_f32_e32 v129, v137, v223
	s_waitcnt lgkmcnt(12)
	v_fmac_f32_e32 v48, v158, v217
	v_fmac_f32_e32 v129, v141, v222
	v_fmac_f32_e32 v129, v145, v221
	s_waitcnt lgkmcnt(10)
	v_fmac_f32_e32 v48, v162, v216
	v_fmac_f32_e32 v129, v149, v220
	v_fmac_f32_e32 v129, v153, v219
	s_waitcnt lgkmcnt(8)
	v_fmac_f32_e32 v48, v166, v215
	v_fmac_f32_e32 v129, v157, v218
	v_fmac_f32_e32 v129, v161, v217
	s_waitcnt lgkmcnt(6)
	v_fmac_f32_e32 v48, v170, v214
	v_fmac_f32_e32 v129, v165, v216
	v_fmac_f32_e32 v129, v169, v215
	s_waitcnt lgkmcnt(4)
	v_fmac_f32_e32 v48, v174, v213
	v_fmac_f32_e32 v129, v173, v214
	v_fmac_f32_e32 v129, v177, v213
	s_waitcnt lgkmcnt(2)
	v_mov_b32_e32 v118, v178
	v_fmac_f32_e32 v58, v66, v223
	v_fmac_f32_e32 v58, v70, v222
	s_waitcnt lgkmcnt(0)
	v_mov_b32_e32 v119, v182
	v_pk_mul_f32 v[118:119], v[118:119], v[206:207]
	v_mov_b32_e32 v182, v179
	v_add_f32_e32 v48, v48, v118
	v_add_f32_e32 v48, v48, v119
	v_lshrrev_b32_e32 v190, 6, v198
	v_and_b32_e32 v191, 1, v190
	v_lshrrev_b32_e32 v190, 1, v190
	v_mul_u32_u24_e32 v191, 0x3000, v191
	v_lshl_add_u32 v191, v190, 7, v191
	v_lshl_add_u32 v190, v190, 6, v191
	v_add_u32_e32 v190, 0x1b000, v190
	ds_read_b128 v[118:121], v190 offset:10800
	ds_read_b128 v[186:189], v190 offset:10784
	v_readlane_b32 s0, v254, 61
	v_readlane_b32 s1, v254, 62
	s_nop 4
	ds_read_b128 v[122:125], v190 offset:11568
	ds_read_b128 v[190:193], v190 offset:11552
	v_fmac_f32_e32 v58, v74, v221
	v_fmac_f32_e32 v58, v78, v220
	v_fmac_f32_e32 v58, v82, v219
	v_fmac_f32_e32 v58, v86, v218
	v_fmac_f32_e32 v58, v90, v217
	v_fmac_f32_e32 v58, v94, v216
	v_fmac_f32_e32 v58, v98, v215
	v_fmac_f32_e32 v58, v102, v214
	v_fmac_f32_e32 v58, v106, v213
	v_fma_f32 v63, v63, v242, v59
	v_fmac_f32_e32 v63, v67, v223
	v_fmac_f32_e32 v63, v71, v222
	v_fmac_f32_e32 v63, v75, v221
	v_fmac_f32_e32 v63, v79, v220
	v_fmac_f32_e32 v63, v83, v219
	v_fmac_f32_e32 v63, v87, v218
	v_fmac_f32_e32 v63, v91, v217
	v_fmac_f32_e32 v63, v95, v216
	v_fmac_f32_e32 v63, v99, v215
	v_fmac_f32_e32 v63, v103, v214
	v_fmac_f32_e32 v63, v107, v213
	v_fma_f32 v60, v64, v242, v60
	v_fmac_f32_e32 v60, v68, v223
	v_fmac_f32_e32 v60, v72, v222
	v_fmac_f32_e32 v60, v76, v221
	v_fmac_f32_e32 v60, v80, v220
	v_fmac_f32_e32 v60, v84, v219
	v_fmac_f32_e32 v60, v88, v218
	v_fmac_f32_e32 v60, v92, v217
	v_fmac_f32_e32 v60, v96, v216
	v_fmac_f32_e32 v60, v100, v215
	v_fmac_f32_e32 v60, v104, v214
	v_fmac_f32_e32 v60, v108, v213
	v_fmac_f32_e32 v61, v65, v242
	v_fmac_f32_e32 v61, v69, v223
	v_fmac_f32_e32 v61, v73, v222
	v_fmac_f32_e32 v61, v77, v221
	v_fmac_f32_e32 v61, v81, v220
	v_fmac_f32_e32 v61, v85, v219
	v_fmac_f32_e32 v61, v89, v218
	v_fmac_f32_e32 v61, v93, v217
	v_fmac_f32_e32 v61, v97, v216
	v_fmac_f32_e32 v61, v101, v215
	v_fmac_f32_e32 v61, v105, v214
	v_fmac_f32_e32 v61, v109, v213
	v_lshlrev_b32_e32 v64, 16, v36
	v_and_b32_e32 v65, 0xffff0000, v36
	v_and_b32_e32 v67, 0xffff0000, v37
	v_lshlrev_b32_e32 v68, 16, v38
	v_and_b32_e32 v69, 0xffff0000, v38
	v_lshlrev_b32_e32 v70, 16, v39
	v_and_b32_e32 v71, 0xffff0000, v39
	s_waitcnt lgkmcnt(2)
	v_mov_b32_e32 v244, v186
	s_waitcnt lgkmcnt(0)
	v_mov_b32_e32 v245, v190
	v_pk_mul_f32 v[244:245], v[244:245], v[204:205]
	v_mov_b32_e32 v190, v187
	v_add_f32_e32 v48, v48, v244
	v_add_f32_e32 v48, v48, v245
	v_max_f32_e64 v126, -v48, 0
	v_mul_f32_e64 v48, |v48|, s93
	v_exp_f32_e32 v48, v48
	s_nop 0
	v_add_f32_e32 v48, 1.0, v48
	s_nop 0
	s_nop 1
	s_nop 0
	s_nop 0
	v_log_f32_e32 v48, v48
	s_nop 0
	v_mul_f32_e32 v130, 0x3f317217, v48
	v_fma_f32 v130, v48, s94, -v130
	v_fmac_f32_e32 v130, 0x3377d1cf, v48
	v_fmac_f32_e32 v130, 0x3f317217, v48
	v_cmp_lt_f32_e64 s[0:1], |v48|, s95
	s_nop 1
	v_cndmask_b32_e64 v48, v48, v130, s[0:1]
	s_nop 0
	s_nop 0
	v_add_f32_e32 v48, v126, v48
	v_mul_f32_e32 v126, 0xbd800000, v48
	v_mov_b32_e32 v130, v49
	s_nop 1
	v_mov_b32_dpp v130, v126 row_shr:1 row_mask:0xf bank_mask:0xf
	v_fmac_f32_e32 v130, 0xbd800000, v48
	s_nop 1
	v_add_f32_dpp v126, v130, v130 row_shr:2 row_mask:0xf bank_mask:0xf bound_ctrl:1
	v_mov_b32_e32 v130, v49
	s_nop 0
	v_add_f32_dpp v126, v126, v126 row_shr:4 row_mask:0xf bank_mask:0xf bound_ctrl:1
	s_nop 1
	v_add_f32_dpp v126, v126, v126 row_shr:8 row_mask:0xf bank_mask:0xf bound_ctrl:1
	s_nop 1
	v_mov_b32_dpp v130, v126 row_bcast:15 row_mask:0xa bank_mask:0xf
	v_add_f32_e32 v126, v126, v130
	v_mov_b32_e32 v130, v49
	s_nop 1
	v_mov_b32_dpp v130, v126 row_bcast:31 row_mask:0xc bank_mask:0xf
	v_add_f32_e32 v126, v126, v130
	s_nop 0
	v_readlane_b32 s4, v126, 63
	s_nop 1
	v_sub_f32_e32 v130, s4, v126
	v_fmac_f32_e32 v126, 0x3d800000, v48
	v_cndmask_b32_e64 v48, v126, v130, s[8:9]
	v_fma_f32 v130, v131, v242, v127
	v_fmac_f32_e32 v130, v135, v223
	v_fmac_f32_e32 v130, v139, v222
	v_fmac_f32_e32 v130, v143, v221
	v_fmac_f32_e32 v130, v147, v220
	v_fmac_f32_e32 v130, v151, v219
	v_fmac_f32_e32 v130, v155, v218
	v_fmac_f32_e32 v130, v159, v217
	v_fmac_f32_e32 v130, v163, v216
	v_fmac_f32_e32 v130, v167, v215
	v_fmac_f32_e32 v130, v171, v214
	v_fmac_f32_e32 v130, v175, v213
	v_pk_mul_f32 v[126:127], v[182:183], v[206:207]
	v_mov_b32_e32 v131, v184
	v_add_f32_e32 v126, v130, v126
	v_add_f32_e32 v130, v126, v127
	v_pk_mul_f32 v[126:127], v[190:191], v[204:205]
	v_mov_b32_e32 v184, v181
	v_add_f32_e32 v126, v130, v126
	v_add_f32_e32 v126, v126, v127
	v_max_f32_e64 v127, -v126, 0
	v_mul_f32_e64 v126, |v126|, s93
	v_exp_f32_e32 v126, v126
	v_mul_f32_e32 v48, 0x3fb8aa3b, v48
	v_exp_f32_e32 v48, v48
	v_add_f32_e32 v126, 1.0, v126
	s_nop 0
	s_nop 1
	s_nop 0
	s_nop 0
	v_log_f32_e32 v126, v126
	s_nop 0
	v_mul_f32_e32 v130, 0x3f317217, v126
	v_fma_f32 v130, v126, s94, -v130
	v_fmac_f32_e32 v130, 0x3377d1cf, v126
	v_fmac_f32_e32 v130, 0x3f317217, v126
	v_cmp_lt_f32_e64 s[0:1], |v126|, s95
	s_nop 1
	v_cndmask_b32_e64 v126, v126, v130, s[0:1]
	s_nop 0
	s_nop 0
	v_add_f32_e32 v126, v127, v126
	v_mul_f32_e32 v127, 0xbd800000, v126
	v_mov_b32_e32 v130, v49
	s_nop 1
	v_mov_b32_dpp v130, v127 row_shr:1 row_mask:0xf bank_mask:0xf
	v_fmac_f32_e32 v130, 0xbd800000, v126
	s_nop 1
	v_add_f32_dpp v127, v130, v130 row_shr:2 row_mask:0xf bank_mask:0xf bound_ctrl:1
	v_mov_b32_e32 v130, v49
	s_nop 0
	v_add_f32_dpp v127, v127, v127 row_shr:4 row_mask:0xf bank_mask:0xf bound_ctrl:1
	s_nop 1
	v_add_f32_dpp v127, v127, v127 row_shr:8 row_mask:0xf bank_mask:0xf bound_ctrl:1
	s_nop 1
	v_mov_b32_dpp v130, v127 row_bcast:15 row_mask:0xa bank_mask:0xf
	v_add_f32_e32 v127, v127, v130
	v_mov_b32_e32 v130, v49
	s_nop 1
	v_mov_b32_dpp v130, v127 row_bcast:31 row_mask:0xc bank_mask:0xf
	v_add_f32_e32 v127, v127, v130
	s_nop 0
	v_readlane_b32 s5, v127, 63
	s_nop 1
	v_sub_f32_e32 v130, s5, v127
	v_fmac_f32_e32 v127, 0x3d800000, v126
	v_cndmask_b32_e64 v126, v127, v130, s[8:9]
	v_fma_f32 v127, v132, v242, v128
	v_fmac_f32_e32 v127, v136, v223
	v_fmac_f32_e32 v127, v140, v222
	v_fmac_f32_e32 v127, v144, v221
	v_fmac_f32_e32 v127, v148, v220
	v_fmac_f32_e32 v127, v152, v219
	v_fmac_f32_e32 v127, v156, v218
	v_fmac_f32_e32 v127, v160, v217
	v_fmac_f32_e32 v127, v164, v216
	v_fmac_f32_e32 v127, v168, v215
	v_fmac_f32_e32 v127, v172, v214
	v_mov_b32_e32 v130, v180
	v_fmac_f32_e32 v127, v176, v213
	v_pk_mul_f32 v[130:131], v[130:131], v[206:207]
	s_nop 0
	v_add_f32_e32 v127, v127, v130
	v_add_f32_e32 v127, v127, v131
	v_mov_b32_e32 v130, v188
	v_mov_b32_e32 v131, v192
	v_pk_mul_f32 v[130:131], v[130:131], v[204:205]
	v_mov_b32_e32 v192, v189
	v_add_f32_e32 v127, v127, v130
	v_add_f32_e32 v127, v127, v131
	v_max_f32_e64 v128, -v127, 0
	v_mul_f32_e64 v127, |v127|, s93
	v_exp_f32_e32 v127, v127
	s_nop 0
	v_add_f32_e32 v127, 1.0, v127
	s_nop 0
	s_nop 1
	s_nop 0
	s_nop 0
	v_log_f32_e32 v127, v127
	s_nop 0
	v_mul_f32_e32 v130, 0x3f317217, v127
	v_fma_f32 v130, v127, s94, -v130
	v_fmac_f32_e32 v130, 0x3377d1cf, v127
	v_fmac_f32_e32 v130, 0x3f317217, v127
	v_cmp_lt_f32_e64 s[0:1], |v127|, s95
	s_nop 1
	v_cndmask_b32_e64 v127, v127, v130, s[0:1]
	s_nop 0
	s_nop 0
	v_add_f32_e32 v127, v128, v127
	v_mul_f32_e32 v128, 0xbd800000, v127
	v_mov_b32_e32 v130, v49
	s_nop 1
	v_mov_b32_dpp v130, v128 row_shr:1 row_mask:0xf bank_mask:0xf
	v_fmac_f32_e32 v130, 0xbd800000, v127
	s_nop 1
	v_add_f32_dpp v128, v130, v130 row_shr:2 row_mask:0xf bank_mask:0xf bound_ctrl:1
	v_mov_b32_e32 v130, v49
	s_nop 0
	v_add_f32_dpp v128, v128, v128 row_shr:4 row_mask:0xf bank_mask:0xf bound_ctrl:1
	s_nop 1
	v_add_f32_dpp v128, v128, v128 row_shr:8 row_mask:0xf bank_mask:0xf bound_ctrl:1
	s_nop 1
	v_mov_b32_dpp v130, v128 row_bcast:15 row_mask:0xa bank_mask:0xf
	v_add_f32_e32 v128, v128, v130
	v_mov_b32_e32 v130, v49
	s_nop 1
	v_mov_b32_dpp v130, v128 row_bcast:31 row_mask:0xc bank_mask:0xf
	v_add_f32_e32 v128, v128, v130
	s_nop 0
	v_readlane_b32 s6, v128, 63
	s_nop 1
	v_sub_f32_e32 v130, s6, v128
	v_fmac_f32_e32 v128, 0x3d800000, v127
	v_cndmask_b32_e64 v127, v128, v130, s[8:9]
	v_pk_mul_f32 v[130:131], v[184:185], v[206:207]
	s_nop 0
	v_add_f32_e32 v128, v129, v130
	v_add_f32_e32 v130, v128, v131
	v_pk_mul_f32 v[128:129], v[192:193], v[204:205]
	s_nop 0
	v_add_f32_e32 v128, v130, v128
	v_add_f32_e32 v128, v128, v129
	v_max_f32_e64 v129, -v128, 0
	v_mul_f32_e64 v128, |v128|, s93
	v_exp_f32_e32 v128, v128
	s_nop 0
	v_add_f32_e32 v128, 1.0, v128
	s_nop 0
	s_nop 1
	s_nop 0
	s_nop 0
	v_log_f32_e32 v128, v128
	s_nop 0
	v_mul_f32_e32 v130, 0x3f317217, v128
	v_fma_f32 v130, v128, s94, -v130
	v_fmac_f32_e32 v130, 0x3377d1cf, v128
	v_fmac_f32_e32 v130, 0x3f317217, v128
	v_cmp_lt_f32_e64 s[0:1], |v128|, s95
	s_nop 1
	v_cndmask_b32_e64 v128, v128, v130, s[0:1]
	s_nop 0
	s_nop 0
	v_add_f32_e32 v128, v129, v128
	v_mul_f32_e32 v129, 0xbd800000, v128
	v_mov_b32_e32 v130, v49
	s_nop 1
	v_mov_b32_dpp v130, v129 row_shr:1 row_mask:0xf bank_mask:0xf
	v_fmac_f32_e32 v130, 0xbd800000, v128
	s_nop 1
	v_add_f32_dpp v129, v130, v130 row_shr:2 row_mask:0xf bank_mask:0xf bound_ctrl:1
	v_mov_b32_e32 v130, v49
	s_nop 0
	v_add_f32_dpp v129, v129, v129 row_shr:4 row_mask:0xf bank_mask:0xf bound_ctrl:1
	s_nop 1
	v_add_f32_dpp v129, v129, v129 row_shr:8 row_mask:0xf bank_mask:0xf bound_ctrl:1
	s_nop 1
	v_mov_b32_dpp v130, v129 row_bcast:15 row_mask:0xa bank_mask:0xf
	v_add_f32_e32 v129, v129, v130
	v_mov_b32_e32 v130, v49
	s_nop 1
	v_mov_b32_dpp v130, v129 row_bcast:31 row_mask:0xc bank_mask:0xf
	v_add_f32_e32 v129, v129, v130
	s_nop 0
	v_readlane_b32 s7, v129, 63
	s_nop 1
	v_sub_f32_e32 v130, s7, v129
	v_fmac_f32_e32 v129, 0x3d800000, v128
	v_cndmask_b32_e64 v130, v129, v130, s[8:9]
	v_mov_b32_e32 v128, v110
	v_mov_b32_e32 v129, v114
	v_pk_mul_f32 v[128:129], v[128:129], v[206:207]
	v_mov_b32_e32 v114, v111
	v_add_f32_e32 v58, v58, v128
	v_add_f32_e32 v58, v58, v129
	v_mov_b32_e32 v128, v118
	v_mov_b32_e32 v129, v122
	v_pk_mul_f32 v[128:129], v[128:129], v[204:205]
	v_mov_b32_e32 v122, v119
	v_add_f32_e32 v58, v58, v128
	v_add_f32_e32 v58, v58, v129
	v_max_f32_e64 v62, -v58, 0
	v_mul_f32_e64 v58, |v58|, s93
	v_exp_f32_e32 v58, v58
	s_nop 0
	v_add_f32_e32 v58, 1.0, v58
	s_nop 0
	s_nop 1
	s_nop 0
	s_nop 0
	v_log_f32_e32 v58, v58
	s_nop 0
	v_mul_f32_e32 v66, 0x3f317217, v58
	v_fma_f32 v66, v58, s94, -v66
	v_fmac_f32_e32 v66, 0x3377d1cf, v58
	v_fmac_f32_e32 v66, 0x3f317217, v58
	v_cmp_lt_f32_e64 s[0:1], |v58|, s95
	s_nop 1
	v_cndmask_b32_e64 v58, v58, v66, s[0:1]
	s_nop 0
	s_nop 0
	v_add_f32_e32 v58, v62, v58
	v_mul_f32_e32 v62, 0xbd800000, v58
	v_mov_b32_e32 v66, v49
	s_nop 1
	v_mov_b32_dpp v66, v62 row_shr:1 row_mask:0xf bank_mask:0xf
	v_fmac_f32_e32 v66, 0xbd800000, v58
	s_nop 1
	v_add_f32_dpp v62, v66, v66 row_shr:2 row_mask:0xf bank_mask:0xf bound_ctrl:1
	v_mov_b32_e32 v66, v49
	s_nop 0
	v_add_f32_dpp v62, v62, v62 row_shr:4 row_mask:0xf bank_mask:0xf bound_ctrl:1
	s_nop 1
	v_add_f32_dpp v62, v62, v62 row_shr:8 row_mask:0xf bank_mask:0xf bound_ctrl:1
	s_nop 1
	v_mov_b32_dpp v66, v62 row_bcast:15 row_mask:0xa bank_mask:0xf
	v_add_f32_e32 v62, v62, v66
	v_mov_b32_e32 v66, v49
	s_nop 1
	v_mov_b32_dpp v66, v62 row_bcast:31 row_mask:0xc bank_mask:0xf
	v_add_f32_e32 v62, v62, v66
	s_nop 0
	v_readlane_b32 s91, v62, 63
	s_nop 1
	v_sub_f32_e32 v66, s91, v62
	v_fmac_f32_e32 v62, 0x3d800000, v58
	v_pk_mul_f32 v[58:59], v[114:115], v[206:207]
	v_cndmask_b32_e64 v62, v62, v66, s[8:9]
	v_add_f32_e32 v58, v63, v58
	v_add_f32_e32 v63, v58, v59
	v_pk_mul_f32 v[58:59], v[122:123], v[204:205]
	v_lshlrev_b32_e32 v66, 16, v37
	v_add_f32_e32 v58, v63, v58
	v_add_f32_e32 v58, v58, v59
	v_max_f32_e64 v59, -v58, 0
	v_mul_f32_e64 v58, |v58|, s93
	v_exp_f32_e32 v58, v58
	s_nop 0
	v_add_f32_e32 v58, 1.0, v58
	s_nop 0
	s_nop 1
	s_nop 0
	s_nop 0
	v_log_f32_e32 v58, v58
	s_nop 0
	v_mul_f32_e32 v63, 0x3f317217, v58
	v_fma_f32 v63, v58, s94, -v63
	v_fmac_f32_e32 v63, 0x3377d1cf, v58
	v_fmac_f32_e32 v63, 0x3f317217, v58
	v_cmp_lt_f32_e64 s[0:1], |v58|, s95
	s_nop 1
	v_cndmask_b32_e64 v58, v58, v63, s[0:1]
	s_nop 0
	s_nop 0
	v_add_f32_e32 v58, v59, v58
	v_mul_f32_e32 v59, 0xbd800000, v58
	v_mov_b32_e32 v63, v49
	s_nop 1
	v_mov_b32_dpp v63, v59 row_shr:1 row_mask:0xf bank_mask:0xf
	v_fmac_f32_e32 v63, 0xbd800000, v58
	s_nop 1
	v_add_f32_dpp v59, v63, v63 row_shr:2 row_mask:0xf bank_mask:0xf bound_ctrl:1
	v_mov_b32_e32 v63, v49
	s_nop 0
	v_add_f32_dpp v59, v59, v59 row_shr:4 row_mask:0xf bank_mask:0xf bound_ctrl:1
	s_nop 1
	v_add_f32_dpp v59, v59, v59 row_shr:8 row_mask:0xf bank_mask:0xf bound_ctrl:1
	s_nop 1
	v_mov_b32_dpp v63, v59 row_bcast:15 row_mask:0xa bank_mask:0xf
	v_add_f32_e32 v59, v59, v63
	v_mov_b32_e32 v63, v49
	s_nop 1
	v_mov_b32_dpp v63, v59 row_bcast:31 row_mask:0xc bank_mask:0xf
	v_add_f32_e32 v59, v59, v63
	s_nop 0
	v_readlane_b32 s20, v59, 63
	s_nop 1
	v_sub_f32_e32 v63, s20, v59
	v_fmac_f32_e32 v59, 0x3d800000, v58
	v_cndmask_b32_e64 v63, v59, v63, s[8:9]
	v_mov_b32_e32 v58, v112
	v_mov_b32_e32 v59, v116
	v_pk_mul_f32 v[58:59], v[58:59], v[206:207]
	v_mov_b32_e32 v116, v113
	v_add_f32_e32 v58, v60, v58
	v_add_f32_e32 v60, v58, v59
	v_mov_b32_e32 v58, v120
	v_mov_b32_e32 v59, v124
	v_pk_mul_f32 v[58:59], v[58:59], v[204:205]
	v_mov_b32_e32 v124, v121
	v_add_f32_e32 v58, v60, v58
	v_add_f32_e32 v58, v58, v59
	v_max_f32_e64 v59, -v58, 0
	v_mul_f32_e64 v58, |v58|, s93
	v_exp_f32_e32 v58, v58
	s_nop 0
	v_add_f32_e32 v58, 1.0, v58
	s_nop 0
	s_nop 1
	s_nop 0
	s_nop 0
	v_log_f32_e32 v58, v58
	s_nop 0
	v_mul_f32_e32 v60, 0x3f317217, v58
	v_fma_f32 v60, v58, s94, -v60
	v_fmac_f32_e32 v60, 0x3377d1cf, v58
	v_fmac_f32_e32 v60, 0x3f317217, v58
	v_cmp_lt_f32_e64 s[0:1], |v58|, s95
	s_nop 1
	v_cndmask_b32_e64 v58, v58, v60, s[0:1]
	s_nop 0
	s_nop 0
	v_add_f32_e32 v58, v59, v58
	v_mul_f32_e32 v59, 0xbd800000, v58
	v_mov_b32_e32 v60, v49
	s_nop 1
	v_mov_b32_dpp v60, v59 row_shr:1 row_mask:0xf bank_mask:0xf
	v_fmac_f32_e32 v60, 0xbd800000, v58
	s_nop 1
	v_add_f32_dpp v59, v60, v60 row_shr:2 row_mask:0xf bank_mask:0xf bound_ctrl:1
	v_mov_b32_e32 v60, v49
	s_nop 0
	v_add_f32_dpp v59, v59, v59 row_shr:4 row_mask:0xf bank_mask:0xf bound_ctrl:1
	s_nop 1
	v_add_f32_dpp v59, v59, v59 row_shr:8 row_mask:0xf bank_mask:0xf bound_ctrl:1
	s_nop 1
	v_mov_b32_dpp v60, v59 row_bcast:15 row_mask:0xa bank_mask:0xf
	v_add_f32_e32 v59, v59, v60
	v_mov_b32_e32 v60, v49
	s_nop 1
	v_mov_b32_dpp v60, v59 row_bcast:31 row_mask:0xc bank_mask:0xf
	v_add_f32_e32 v59, v59, v60
	s_nop 0
	v_readlane_b32 s21, v59, 63
	s_nop 1
	v_sub_f32_e32 v60, s21, v59
	v_fmac_f32_e32 v59, 0x3d800000, v58
	v_cndmask_b32_e64 v60, v59, v60, s[8:9]
	v_pk_mul_f32 v[58:59], v[116:117], v[206:207]
	s_nop 0
	v_add_f32_e32 v58, v61, v58
	v_add_f32_e32 v61, v58, v59
	v_pk_mul_f32 v[58:59], v[124:125], v[204:205]
	s_nop 0
	v_add_f32_e32 v58, v61, v58
	v_add_f32_e32 v58, v58, v59
	v_max_f32_e64 v59, -v58, 0
	v_mul_f32_e64 v58, |v58|, s93
	v_exp_f32_e32 v58, v58
	s_nop 0
	v_add_f32_e32 v58, 1.0, v58
	s_nop 0
	s_nop 1
	s_nop 0
	s_nop 0
	v_log_f32_e32 v58, v58
	s_nop 0
	v_mul_f32_e32 v61, 0x3f317217, v58
	v_fma_f32 v61, v58, s94, -v61
	v_fmac_f32_e32 v61, 0x3377d1cf, v58
	v_fmac_f32_e32 v61, 0x3f317217, v58
	v_cmp_lt_f32_e64 s[0:1], |v58|, s95
	s_nop 1
	v_cndmask_b32_e64 v58, v58, v61, s[0:1]
	s_nop 0
	s_nop 0
	v_add_f32_e32 v58, v59, v58
	v_mul_f32_e32 v59, 0xbd800000, v58
	v_mov_b32_e32 v61, v49
	v_readlane_b32 s0, v254, 0
	s_add_u32 s0, s90, s0
	v_mov_b32_dpp v61, v59 row_shr:1 row_mask:0xf bank_mask:0xf
	v_fmac_f32_e32 v61, 0xbd800000, v58
	v_readlane_b32 s1, v254, 1
	s_addc_u32 s1, s15, s1
	v_add_f32_dpp v59, v61, v61 row_shr:2 row_mask:0xf bank_mask:0xf bound_ctrl:1
	v_mov_b32_e32 v61, v49
	s_lshl_b64 s[0:1], s[0:1], 10
	v_add_f32_dpp v59, v59, v59 row_shr:4 row_mask:0xf bank_mask:0xf bound_ctrl:1
	s_nop 1
	v_add_f32_dpp v59, v59, v59 row_shr:8 row_mask:0xf bank_mask:0xf bound_ctrl:1
	s_nop 1
	v_mov_b32_dpp v61, v59 row_bcast:15 row_mask:0xa bank_mask:0xf
	v_add_f32_e32 v59, v59, v61
	v_mov_b32_e32 v61, v49
	s_nop 1
	v_mov_b32_dpp v61, v59 row_bcast:31 row_mask:0xc bank_mask:0xf
	v_add_f32_e32 v59, v59, v61
	s_nop 0
	v_readlane_b32 s18, v59, 63
	s_nop 1
	v_sub_f32_e32 v61, s18, v59
	v_fmac_f32_e32 v59, 0x3d800000, v58
	v_cndmask_b32_e64 v58, v59, v61, s[8:9]
	v_mul_f32_e32 v59, 0x3fb8aa3b, v126
	v_exp_f32_e32 v72, v59
	v_mul_f32_e32 v59, 0x3fb8aa3b, v127
	v_mul_f32_e32 v58, 0x3fb8aa3b, v58
	v_exp_f32_e32 v73, v59
	v_exp_f32_e32 v78, v58
	v_cvt_pk_bf16_f32 v58, v48, v72
	v_mul_f32_e32 v48, v48, v64
	v_mul_f32_e32 v59, 0x3fb8aa3b, v130
	v_cvt_pk_bf16_f32 v48, v48, s0
	v_exp_f32_e32 v74, v59
	ds_write_b16 v208, v48 offset:56448
	v_mul_f32_e32 v48, v72, v65
	v_mul_f32_e32 v59, 0x3fb8aa3b, v62
	v_cvt_pk_bf16_f32 v48, v48, s0
	v_exp_f32_e32 v75, v59
	ds_write_b16 v208, v48 offset:56592
	v_mul_f32_e32 v48, v73, v66
	v_mul_f32_e32 v59, 0x3fb8aa3b, v63
	v_cvt_pk_bf16_f32 v48, v48, s0
	v_exp_f32_e32 v76, v59
	ds_write_b16 v208, v48 offset:56736
	v_mul_f32_e32 v48, v74, v67
	v_mul_f32_e32 v59, 0x3fb8aa3b, v60
	v_cvt_pk_bf16_f32 v48, v48, s0
	v_exp_f32_e32 v77, v59
	ds_write_b16 v208, v48 offset:56880
	v_mul_f32_e32 v48, v75, v68
	v_cvt_pk_bf16_f32 v48, v48, s0
	ds_write_b16 v208, v48 offset:57024
	v_mul_f32_e32 v48, v76, v69
	v_cvt_pk_bf16_f32 v48, v48, s0
	ds_write_b16 v208, v48 offset:57168
	v_mul_f32_e32 v48, v77, v70
	v_cvt_pk_bf16_f32 v48, v48, s0
	ds_write_b16 v208, v48 offset:57312
	v_mul_f32_e32 v48, v78, v71
	v_cvt_pk_bf16_f32 v59, v73, v74
	v_cvt_pk_bf16_f32 v60, v75, v76
	v_cvt_pk_bf16_f32 v61, v77, v78
	v_lshl_add_u64 v[62:63], v[202:203], 0, s[0:1]
	v_cvt_pk_bf16_f32 v48, v48, s0
	global_store_dwordx4 v[62:63], v[58:61], off
	ds_write_b16 v208, v48 offset:57456
	s_and_saveexec_b64 s[0:1], s[10:11]
	s_cbranch_execz .LBB0_661
	v_mul_f32_e32 v48, s4, v240
	v_exp_f32_e32 v58, v48
	v_mul_f32_e32 v48, s5, v240
	v_exp_f32_e32 v59, v48
	v_mul_f32_e32 v48, s6, v240
	v_exp_f32_e32 v60, v48
	v_mul_f32_e32 v48, s7, v240
	v_exp_f32_e32 v61, v48
	v_mul_f32_e32 v48, s91, v240
	v_exp_f32_e32 v62, v48
	v_mul_f32_e32 v48, s20, v240
	v_exp_f32_e32 v63, v48
	v_mul_f32_e32 v48, s21, v240
	v_exp_f32_e32 v64, v48
	v_mul_f32_e32 v48, s18, v240
	v_exp_f32_e32 v65, v48
	s_add_u32 s4, s16, s88
	s_addc_u32 s5, s17, s89
	global_store_dwordx4 v49, v[58:61], s[4:5] offset:32
	global_store_dwordx4 v49, v[62:65], s[4:5] offset:48
.LBB0_661:
	s_or_b64 exec, exec, s[0:1]
	v_readlane_b32 s0, v254, 63
	v_readlane_b32 s1, v255, 0
	v_lshrrev_b32_e32 v182, 6, v198
	v_and_b32_e32 v183, 1, v182
	v_lshrrev_b32_e32 v182, 1, v182
	v_mul_u32_u24_e32 v183, 0x3000, v183
	v_lshl_add_u32 v183, v182, 7, v183
	v_lshl_add_u32 v182, v182, 6, v183
	v_add_u32_e32 v182, 0x1b000, v182
	ds_read_b128 v[58:61], v182 offset:24656
	ds_read_b128 v[126:129], v182 offset:24640
	ds_read_b128 v[62:65], v182 offset:80
	ds_read_b128 v[130:133], v182 offset:64
	ds_read_b128 v[66:69], v182 offset:848
	ds_read_b128 v[134:137], v182 offset:832
	ds_read_b128 v[70:73], v182 offset:1616
	ds_read_b128 v[138:141], v182 offset:1600
	ds_read_b128 v[74:77], v182 offset:2384
	ds_read_b128 v[142:145], v182 offset:2368
	ds_read_b128 v[78:81], v182 offset:3152
	ds_read_b128 v[146:149], v182 offset:3136
	s_waitcnt lgkmcnt(8)
	ds_read_b128 v[82:85], v182 offset:3920
	ds_read_b128 v[150:153], v182 offset:3904
	ds_read_b128 v[86:89], v182 offset:4688
	ds_read_b128 v[154:157], v182 offset:4672
	s_waitcnt lgkmcnt(8)
	v_readlane_b32 s0, v255, 1
	v_readlane_b32 s1, v255, 2
	s_nop 4
	ds_read_b128 v[90:93], v182 offset:5456
	ds_read_b128 v[158:161], v182 offset:5440
	v_readlane_b32 s0, v255, 3
	v_readlane_b32 s1, v255, 4
	s_nop 4
	ds_read_b128 v[94:97], v182 offset:6224
	ds_read_b128 v[162:165], v182 offset:6208
	s_waitcnt lgkmcnt(8)
	v_readlane_b32 s0, v255, 5
	v_readlane_b32 s1, v255, 6
	s_nop 4
	ds_read_b128 v[98:101], v182 offset:6992
	ds_read_b128 v[166:169], v182 offset:6976
	v_readlane_b32 s0, v255, 7
	v_readlane_b32 s1, v255, 8
	s_nop 4
	ds_read_b128 v[102:105], v182 offset:7760
	ds_read_b128 v[170:173], v182 offset:7744
	s_waitcnt lgkmcnt(8)
	v_readlane_b32 s0, v255, 9
	v_readlane_b32 s1, v255, 10
	s_nop 4
	ds_read_b128 v[106:109], v182 offset:8528
	ds_read_b128 v[174:177], v182 offset:8512
	v_readlane_b32 s0, v255, 11
	v_readlane_b32 s1, v255, 12
	s_nop 4
	ds_read_b128 v[110:113], v182 offset:9296
	ds_read_b128 v[178:181], v182 offset:9280
	s_waitcnt lgkmcnt(8)
	v_readlane_b32 s0, v255, 13
	v_readlane_b32 s1, v255, 14
	s_nop 4
	ds_read_b128 v[114:117], v182 offset:10064
	ds_read_b128 v[182:185], v182 offset:10048
	v_readlane_b32 s0, v255, 15
	v_readlane_b32 s1, v255, 16
	s_waitcnt lgkmcnt(14)
	v_fma_f32 v58, v62, v242, v58
	s_waitcnt lgkmcnt(14)
	v_fma_f32 v48, v130, v242, v126
	s_waitcnt lgkmcnt(14)
	v_fmac_f32_e32 v48, v134, v223
	s_waitcnt lgkmcnt(14)
	v_fmac_f32_e32 v48, v138, v222
	s_waitcnt lgkmcnt(14)
	v_fmac_f32_e32 v48, v142, v221
	s_waitcnt lgkmcnt(14)
	v_fmac_f32_e32 v48, v146, v220
	s_waitcnt lgkmcnt(14)
	v_fmac_f32_e32 v48, v150, v219
	s_waitcnt lgkmcnt(14)
	v_fmac_f32_e32 v48, v154, v218
	v_fmac_f32_e32 v129, v133, v242
	v_fmac_f32_e32 v129, v137, v223
	s_waitcnt lgkmcnt(12)
	v_fmac_f32_e32 v48, v158, v217
	v_fmac_f32_e32 v129, v141, v222
	v_fmac_f32_e32 v129, v145, v221
	s_waitcnt lgkmcnt(10)
	v_fmac_f32_e32 v48, v162, v216
	v_fmac_f32_e32 v129, v149, v220
	v_fmac_f32_e32 v129, v153, v219
	s_waitcnt lgkmcnt(8)
	v_fmac_f32_e32 v48, v166, v215
	v_fmac_f32_e32 v129, v157, v218
	v_fmac_f32_e32 v129, v161, v217
	s_waitcnt lgkmcnt(6)
	v_fmac_f32_e32 v48, v170, v214
	v_fmac_f32_e32 v129, v165, v216
	v_fmac_f32_e32 v129, v169, v215
	s_waitcnt lgkmcnt(4)
	v_fmac_f32_e32 v48, v174, v213
	v_fmac_f32_e32 v129, v173, v214
	v_fmac_f32_e32 v129, v177, v213
	s_waitcnt lgkmcnt(2)
	v_mov_b32_e32 v118, v178
	v_fmac_f32_e32 v58, v66, v223
	v_fmac_f32_e32 v58, v70, v222
	s_waitcnt lgkmcnt(0)
	v_mov_b32_e32 v119, v182
	v_pk_mul_f32 v[118:119], v[118:119], v[206:207]
	v_mov_b32_e32 v182, v179
	v_add_f32_e32 v48, v48, v118
	v_add_f32_e32 v48, v48, v119
	v_lshrrev_b32_e32 v190, 6, v198
	v_and_b32_e32 v191, 1, v190
	v_lshrrev_b32_e32 v190, 1, v190
	v_mul_u32_u24_e32 v191, 0x3000, v191
	v_lshl_add_u32 v191, v190, 7, v191
	v_lshl_add_u32 v190, v190, 6, v191
	v_add_u32_e32 v190, 0x1b000, v190
	ds_read_b128 v[118:121], v190 offset:10832
	ds_read_b128 v[186:189], v190 offset:10816
	v_readlane_b32 s0, v255, 17
	v_readlane_b32 s1, v255, 18
	s_nop 4
	ds_read_b128 v[122:125], v190 offset:11600
	ds_read_b128 v[190:193], v190 offset:11584
	v_fmac_f32_e32 v58, v74, v221
	v_fmac_f32_e32 v58, v78, v220
	v_fmac_f32_e32 v58, v82, v219
	v_fmac_f32_e32 v58, v86, v218
	v_fmac_f32_e32 v58, v90, v217
	v_fmac_f32_e32 v58, v94, v216
	v_fmac_f32_e32 v58, v98, v215
	v_fmac_f32_e32 v58, v102, v214
	v_fmac_f32_e32 v58, v106, v213
	v_fma_f32 v63, v63, v242, v59
	v_fmac_f32_e32 v63, v67, v223
	v_fmac_f32_e32 v63, v71, v222
	v_fmac_f32_e32 v63, v75, v221
	v_fmac_f32_e32 v63, v79, v220
	v_fmac_f32_e32 v63, v83, v219
	v_fmac_f32_e32 v63, v87, v218
	v_fmac_f32_e32 v63, v91, v217
	v_fmac_f32_e32 v63, v95, v216
	v_fmac_f32_e32 v63, v99, v215
	v_fmac_f32_e32 v63, v103, v214
	v_fmac_f32_e32 v63, v107, v213
	v_fma_f32 v60, v64, v242, v60
	v_fmac_f32_e32 v60, v68, v223
	v_fmac_f32_e32 v60, v72, v222
	v_fmac_f32_e32 v60, v76, v221
	v_fmac_f32_e32 v60, v80, v220
	v_fmac_f32_e32 v60, v84, v219
	v_fmac_f32_e32 v60, v88, v218
	v_fmac_f32_e32 v60, v92, v217
	v_fmac_f32_e32 v60, v96, v216
	v_fmac_f32_e32 v60, v100, v215
	v_fmac_f32_e32 v60, v104, v214
	v_fmac_f32_e32 v60, v108, v213
	v_fmac_f32_e32 v61, v65, v242
	v_fmac_f32_e32 v61, v69, v223
	v_fmac_f32_e32 v61, v73, v222
	v_fmac_f32_e32 v61, v77, v221
	v_fmac_f32_e32 v61, v81, v220
	v_fmac_f32_e32 v61, v85, v219
	v_fmac_f32_e32 v61, v89, v218
	v_fmac_f32_e32 v61, v93, v217
	v_fmac_f32_e32 v61, v97, v216
	v_fmac_f32_e32 v61, v101, v215
	v_fmac_f32_e32 v61, v105, v214
	v_fmac_f32_e32 v61, v109, v213
	v_lshlrev_b32_e32 v64, 16, v40
	v_and_b32_e32 v65, 0xffff0000, v40
	v_and_b32_e32 v67, 0xffff0000, v41
	v_lshlrev_b32_e32 v68, 16, v42
	v_and_b32_e32 v69, 0xffff0000, v42
	v_lshlrev_b32_e32 v70, 16, v43
	v_and_b32_e32 v71, 0xffff0000, v43
	s_waitcnt lgkmcnt(2)
	v_mov_b32_e32 v244, v186
	s_waitcnt lgkmcnt(0)
	v_mov_b32_e32 v245, v190
	v_pk_mul_f32 v[244:245], v[244:245], v[204:205]
	v_mov_b32_e32 v190, v187
	v_add_f32_e32 v48, v48, v244
	v_add_f32_e32 v48, v48, v245
	v_max_f32_e64 v126, -v48, 0
	v_mul_f32_e64 v48, |v48|, s93
	v_exp_f32_e32 v48, v48
	s_nop 0
	v_add_f32_e32 v48, 1.0, v48
	s_nop 0
	s_nop 1
	s_nop 0
	s_nop 0
	v_log_f32_e32 v48, v48
	s_nop 0
	v_mul_f32_e32 v130, 0x3f317217, v48
	v_fma_f32 v130, v48, s94, -v130
	v_fmac_f32_e32 v130, 0x3377d1cf, v48
	v_fmac_f32_e32 v130, 0x3f317217, v48
	v_cmp_lt_f32_e64 s[0:1], |v48|, s95
	s_nop 1
	v_cndmask_b32_e64 v48, v48, v130, s[0:1]
	s_nop 0
	s_nop 0
	v_add_f32_e32 v48, v126, v48
	v_mul_f32_e32 v126, 0xbd800000, v48
	v_mov_b32_e32 v130, v49
	s_nop 1
	v_mov_b32_dpp v130, v126 row_shr:1 row_mask:0xf bank_mask:0xf
	v_fmac_f32_e32 v130, 0xbd800000, v48
	s_nop 1
	v_add_f32_dpp v126, v130, v130 row_shr:2 row_mask:0xf bank_mask:0xf bound_ctrl:1
	v_mov_b32_e32 v130, v49
	s_nop 0
	v_add_f32_dpp v126, v126, v126 row_shr:4 row_mask:0xf bank_mask:0xf bound_ctrl:1
	s_nop 1
	v_add_f32_dpp v126, v126, v126 row_shr:8 row_mask:0xf bank_mask:0xf bound_ctrl:1
	s_nop 1
	v_mov_b32_dpp v130, v126 row_bcast:15 row_mask:0xa bank_mask:0xf
	v_add_f32_e32 v126, v126, v130
	v_mov_b32_e32 v130, v49
	s_nop 1
	v_mov_b32_dpp v130, v126 row_bcast:31 row_mask:0xc bank_mask:0xf
	v_add_f32_e32 v126, v126, v130
	s_nop 0
	v_readlane_b32 s4, v126, 63
	s_nop 1
	v_sub_f32_e32 v130, s4, v126
	v_fmac_f32_e32 v126, 0x3d800000, v48
	v_cndmask_b32_e64 v48, v126, v130, s[8:9]
	v_fma_f32 v130, v131, v242, v127
	v_fmac_f32_e32 v130, v135, v223
	v_fmac_f32_e32 v130, v139, v222
	v_fmac_f32_e32 v130, v143, v221
	v_fmac_f32_e32 v130, v147, v220
	v_fmac_f32_e32 v130, v151, v219
	v_fmac_f32_e32 v130, v155, v218
	v_fmac_f32_e32 v130, v159, v217
	v_fmac_f32_e32 v130, v163, v216
	v_fmac_f32_e32 v130, v167, v215
	v_fmac_f32_e32 v130, v171, v214
	v_fmac_f32_e32 v130, v175, v213
	v_pk_mul_f32 v[126:127], v[182:183], v[206:207]
	v_mov_b32_e32 v131, v184
	v_add_f32_e32 v126, v130, v126
	v_add_f32_e32 v130, v126, v127
	v_pk_mul_f32 v[126:127], v[190:191], v[204:205]
	v_mov_b32_e32 v184, v181
	v_add_f32_e32 v126, v130, v126
	v_add_f32_e32 v126, v126, v127
	v_max_f32_e64 v127, -v126, 0
	v_mul_f32_e64 v126, |v126|, s93
	v_exp_f32_e32 v126, v126
	v_mul_f32_e32 v48, 0x3fb8aa3b, v48
	v_exp_f32_e32 v48, v48
	v_add_f32_e32 v126, 1.0, v126
	s_nop 0
	s_nop 1
	s_nop 0
	s_nop 0
	v_log_f32_e32 v126, v126
	s_nop 0
	v_mul_f32_e32 v130, 0x3f317217, v126
	v_fma_f32 v130, v126, s94, -v130
	v_fmac_f32_e32 v130, 0x3377d1cf, v126
	v_fmac_f32_e32 v130, 0x3f317217, v126
	v_cmp_lt_f32_e64 s[0:1], |v126|, s95
	s_nop 1
	v_cndmask_b32_e64 v126, v126, v130, s[0:1]
	s_nop 0
	s_nop 0
	v_add_f32_e32 v126, v127, v126
	v_mul_f32_e32 v127, 0xbd800000, v126
	v_mov_b32_e32 v130, v49
	s_nop 1
	v_mov_b32_dpp v130, v127 row_shr:1 row_mask:0xf bank_mask:0xf
	v_fmac_f32_e32 v130, 0xbd800000, v126
	s_nop 1
	v_add_f32_dpp v127, v130, v130 row_shr:2 row_mask:0xf bank_mask:0xf bound_ctrl:1
	v_mov_b32_e32 v130, v49
	s_nop 0
	v_add_f32_dpp v127, v127, v127 row_shr:4 row_mask:0xf bank_mask:0xf bound_ctrl:1
	s_nop 1
	v_add_f32_dpp v127, v127, v127 row_shr:8 row_mask:0xf bank_mask:0xf bound_ctrl:1
	s_nop 1
	v_mov_b32_dpp v130, v127 row_bcast:15 row_mask:0xa bank_mask:0xf
	v_add_f32_e32 v127, v127, v130
	v_mov_b32_e32 v130, v49
	s_nop 1
	v_mov_b32_dpp v130, v127 row_bcast:31 row_mask:0xc bank_mask:0xf
	v_add_f32_e32 v127, v127, v130
	s_nop 0
	v_readlane_b32 s5, v127, 63
	s_nop 1
	v_sub_f32_e32 v130, s5, v127
	v_fmac_f32_e32 v127, 0x3d800000, v126
	v_cndmask_b32_e64 v126, v127, v130, s[8:9]
	v_fma_f32 v127, v132, v242, v128
	v_fmac_f32_e32 v127, v136, v223
	v_fmac_f32_e32 v127, v140, v222
	v_fmac_f32_e32 v127, v144, v221
	v_fmac_f32_e32 v127, v148, v220
	v_fmac_f32_e32 v127, v152, v219
	v_fmac_f32_e32 v127, v156, v218
	v_fmac_f32_e32 v127, v160, v217
	v_fmac_f32_e32 v127, v164, v216
	v_fmac_f32_e32 v127, v168, v215
	v_fmac_f32_e32 v127, v172, v214
	v_mov_b32_e32 v130, v180
	v_fmac_f32_e32 v127, v176, v213
	v_pk_mul_f32 v[130:131], v[130:131], v[206:207]
	s_nop 0
	v_add_f32_e32 v127, v127, v130
	v_add_f32_e32 v127, v127, v131
	v_mov_b32_e32 v130, v188
	v_mov_b32_e32 v131, v192
	v_pk_mul_f32 v[130:131], v[130:131], v[204:205]
	v_mov_b32_e32 v192, v189
	v_add_f32_e32 v127, v127, v130
	v_add_f32_e32 v127, v127, v131
	v_max_f32_e64 v128, -v127, 0
	v_mul_f32_e64 v127, |v127|, s93
	v_exp_f32_e32 v127, v127
	s_nop 0
	v_add_f32_e32 v127, 1.0, v127
	s_nop 0
	s_nop 1
	s_nop 0
	s_nop 0
	v_log_f32_e32 v127, v127
	s_nop 0
	v_mul_f32_e32 v130, 0x3f317217, v127
	v_fma_f32 v130, v127, s94, -v130
	v_fmac_f32_e32 v130, 0x3377d1cf, v127
	v_fmac_f32_e32 v130, 0x3f317217, v127
	v_cmp_lt_f32_e64 s[0:1], |v127|, s95
	s_nop 1
	v_cndmask_b32_e64 v127, v127, v130, s[0:1]
	s_nop 0
	s_nop 0
	v_add_f32_e32 v127, v128, v127
	v_mul_f32_e32 v128, 0xbd800000, v127
	v_mov_b32_e32 v130, v49
	s_nop 1
	v_mov_b32_dpp v130, v128 row_shr:1 row_mask:0xf bank_mask:0xf
	v_fmac_f32_e32 v130, 0xbd800000, v127
	s_nop 1
	v_add_f32_dpp v128, v130, v130 row_shr:2 row_mask:0xf bank_mask:0xf bound_ctrl:1
	v_mov_b32_e32 v130, v49
	s_nop 0
	v_add_f32_dpp v128, v128, v128 row_shr:4 row_mask:0xf bank_mask:0xf bound_ctrl:1
	s_nop 1
	v_add_f32_dpp v128, v128, v128 row_shr:8 row_mask:0xf bank_mask:0xf bound_ctrl:1
	s_nop 1
	v_mov_b32_dpp v130, v128 row_bcast:15 row_mask:0xa bank_mask:0xf
	v_add_f32_e32 v128, v128, v130
	v_mov_b32_e32 v130, v49
	s_nop 1
	v_mov_b32_dpp v130, v128 row_bcast:31 row_mask:0xc bank_mask:0xf
	v_add_f32_e32 v128, v128, v130
	s_nop 0
	v_readlane_b32 s6, v128, 63
	s_nop 1
	v_sub_f32_e32 v130, s6, v128
	v_fmac_f32_e32 v128, 0x3d800000, v127
	v_cndmask_b32_e64 v127, v128, v130, s[8:9]
	v_pk_mul_f32 v[130:131], v[184:185], v[206:207]
	s_nop 0
	v_add_f32_e32 v128, v129, v130
	v_add_f32_e32 v130, v128, v131
	v_pk_mul_f32 v[128:129], v[192:193], v[204:205]
	s_nop 0
	v_add_f32_e32 v128, v130, v128
	v_add_f32_e32 v128, v128, v129
	v_max_f32_e64 v129, -v128, 0
	v_mul_f32_e64 v128, |v128|, s93
	v_exp_f32_e32 v128, v128
	s_nop 0
	v_add_f32_e32 v128, 1.0, v128
	s_nop 0
	s_nop 1
	s_nop 0
	s_nop 0
	v_log_f32_e32 v128, v128
	s_nop 0
	v_mul_f32_e32 v130, 0x3f317217, v128
	v_fma_f32 v130, v128, s94, -v130
	v_fmac_f32_e32 v130, 0x3377d1cf, v128
	v_fmac_f32_e32 v130, 0x3f317217, v128
	v_cmp_lt_f32_e64 s[0:1], |v128|, s95
	s_nop 1
	v_cndmask_b32_e64 v128, v128, v130, s[0:1]
	s_nop 0
	s_nop 0
	v_add_f32_e32 v128, v129, v128
	v_mul_f32_e32 v129, 0xbd800000, v128
	v_mov_b32_e32 v130, v49
	s_nop 1
	v_mov_b32_dpp v130, v129 row_shr:1 row_mask:0xf bank_mask:0xf
	v_fmac_f32_e32 v130, 0xbd800000, v128
	s_nop 1
	v_add_f32_dpp v129, v130, v130 row_shr:2 row_mask:0xf bank_mask:0xf bound_ctrl:1
	v_mov_b32_e32 v130, v49
	s_nop 0
	v_add_f32_dpp v129, v129, v129 row_shr:4 row_mask:0xf bank_mask:0xf bound_ctrl:1
	s_nop 1
	v_add_f32_dpp v129, v129, v129 row_shr:8 row_mask:0xf bank_mask:0xf bound_ctrl:1
	s_nop 1
	v_mov_b32_dpp v130, v129 row_bcast:15 row_mask:0xa bank_mask:0xf
	v_add_f32_e32 v129, v129, v130
	v_mov_b32_e32 v130, v49
	s_nop 1
	v_mov_b32_dpp v130, v129 row_bcast:31 row_mask:0xc bank_mask:0xf
	v_add_f32_e32 v129, v129, v130
	s_nop 0
	v_readlane_b32 s7, v129, 63
	s_nop 1
	v_sub_f32_e32 v130, s7, v129
	v_fmac_f32_e32 v129, 0x3d800000, v128
	v_cndmask_b32_e64 v130, v129, v130, s[8:9]
	v_mov_b32_e32 v128, v110
	v_mov_b32_e32 v129, v114
	v_pk_mul_f32 v[128:129], v[128:129], v[206:207]
	v_mov_b32_e32 v114, v111
	v_add_f32_e32 v58, v58, v128
	v_add_f32_e32 v58, v58, v129
	v_mov_b32_e32 v128, v118
	v_mov_b32_e32 v129, v122
	v_pk_mul_f32 v[128:129], v[128:129], v[204:205]
	v_mov_b32_e32 v122, v119
	v_add_f32_e32 v58, v58, v128
	v_add_f32_e32 v58, v58, v129
	v_max_f32_e64 v62, -v58, 0
	v_mul_f32_e64 v58, |v58|, s93
	v_exp_f32_e32 v58, v58
	s_nop 0
	v_add_f32_e32 v58, 1.0, v58
	s_nop 0
	s_nop 1
	s_nop 0
	s_nop 0
	v_log_f32_e32 v58, v58
	s_nop 0
	v_mul_f32_e32 v66, 0x3f317217, v58
	v_fma_f32 v66, v58, s94, -v66
	v_fmac_f32_e32 v66, 0x3377d1cf, v58
	v_fmac_f32_e32 v66, 0x3f317217, v58
	v_cmp_lt_f32_e64 s[0:1], |v58|, s95
	s_nop 1
	v_cndmask_b32_e64 v58, v58, v66, s[0:1]
	s_nop 0
	s_nop 0
	v_add_f32_e32 v58, v62, v58
	v_mul_f32_e32 v62, 0xbd800000, v58
	v_mov_b32_e32 v66, v49
	s_nop 1
	v_mov_b32_dpp v66, v62 row_shr:1 row_mask:0xf bank_mask:0xf
	v_fmac_f32_e32 v66, 0xbd800000, v58
	s_nop 1
	v_add_f32_dpp v62, v66, v66 row_shr:2 row_mask:0xf bank_mask:0xf bound_ctrl:1
	v_mov_b32_e32 v66, v49
	s_nop 0
	v_add_f32_dpp v62, v62, v62 row_shr:4 row_mask:0xf bank_mask:0xf bound_ctrl:1
	s_nop 1
	v_add_f32_dpp v62, v62, v62 row_shr:8 row_mask:0xf bank_mask:0xf bound_ctrl:1
	s_nop 1
	v_mov_b32_dpp v66, v62 row_bcast:15 row_mask:0xa bank_mask:0xf
	v_add_f32_e32 v62, v62, v66
	v_mov_b32_e32 v66, v49
	s_nop 1
	v_mov_b32_dpp v66, v62 row_bcast:31 row_mask:0xc bank_mask:0xf
	v_add_f32_e32 v62, v62, v66
	s_nop 0
	v_readlane_b32 s91, v62, 63
	s_nop 1
	v_sub_f32_e32 v66, s91, v62
	v_fmac_f32_e32 v62, 0x3d800000, v58
	v_pk_mul_f32 v[58:59], v[114:115], v[206:207]
	v_cndmask_b32_e64 v62, v62, v66, s[8:9]
	v_add_f32_e32 v58, v63, v58
	v_add_f32_e32 v63, v58, v59
	v_pk_mul_f32 v[58:59], v[122:123], v[204:205]
	v_lshlrev_b32_e32 v66, 16, v41
	v_add_f32_e32 v58, v63, v58
	v_add_f32_e32 v58, v58, v59
	v_max_f32_e64 v59, -v58, 0
	v_mul_f32_e64 v58, |v58|, s93
	v_exp_f32_e32 v58, v58
	s_nop 0
	v_add_f32_e32 v58, 1.0, v58
	s_nop 0
	s_nop 1
	s_nop 0
	s_nop 0
	v_log_f32_e32 v58, v58
	s_nop 0
	v_mul_f32_e32 v63, 0x3f317217, v58
	v_fma_f32 v63, v58, s94, -v63
	v_fmac_f32_e32 v63, 0x3377d1cf, v58
	v_fmac_f32_e32 v63, 0x3f317217, v58
	v_cmp_lt_f32_e64 s[0:1], |v58|, s95
	s_nop 1
	v_cndmask_b32_e64 v58, v58, v63, s[0:1]
	s_nop 0
	s_nop 0
	v_add_f32_e32 v58, v59, v58
	v_mul_f32_e32 v59, 0xbd800000, v58
	v_mov_b32_e32 v63, v49
	s_nop 1
	v_mov_b32_dpp v63, v59 row_shr:1 row_mask:0xf bank_mask:0xf
	v_fmac_f32_e32 v63, 0xbd800000, v58
	s_nop 1
	v_add_f32_dpp v59, v63, v63 row_shr:2 row_mask:0xf bank_mask:0xf bound_ctrl:1
	v_mov_b32_e32 v63, v49
	s_nop 0
	v_add_f32_dpp v59, v59, v59 row_shr:4 row_mask:0xf bank_mask:0xf bound_ctrl:1
	s_nop 1
	v_add_f32_dpp v59, v59, v59 row_shr:8 row_mask:0xf bank_mask:0xf bound_ctrl:1
	s_nop 1
	v_mov_b32_dpp v63, v59 row_bcast:15 row_mask:0xa bank_mask:0xf
	v_add_f32_e32 v59, v59, v63
	v_mov_b32_e32 v63, v49
	s_nop 1
	v_mov_b32_dpp v63, v59 row_bcast:31 row_mask:0xc bank_mask:0xf
	v_add_f32_e32 v59, v59, v63
	s_nop 0
	v_readlane_b32 s20, v59, 63
	s_nop 1
	v_sub_f32_e32 v63, s20, v59
	v_fmac_f32_e32 v59, 0x3d800000, v58
	v_cndmask_b32_e64 v63, v59, v63, s[8:9]
	v_mov_b32_e32 v58, v112
	v_mov_b32_e32 v59, v116
	v_pk_mul_f32 v[58:59], v[58:59], v[206:207]
	v_mov_b32_e32 v116, v113
	v_add_f32_e32 v58, v60, v58
	v_add_f32_e32 v60, v58, v59
	v_mov_b32_e32 v58, v120
	v_mov_b32_e32 v59, v124
	v_pk_mul_f32 v[58:59], v[58:59], v[204:205]
	v_mov_b32_e32 v124, v121
	v_add_f32_e32 v58, v60, v58
	v_add_f32_e32 v58, v58, v59
	v_max_f32_e64 v59, -v58, 0
	v_mul_f32_e64 v58, |v58|, s93
	v_exp_f32_e32 v58, v58
	s_nop 0
	v_add_f32_e32 v58, 1.0, v58
	s_nop 0
	s_nop 1
	s_nop 0
	s_nop 0
	v_log_f32_e32 v58, v58
	s_nop 0
	v_mul_f32_e32 v60, 0x3f317217, v58
	v_fma_f32 v60, v58, s94, -v60
	v_fmac_f32_e32 v60, 0x3377d1cf, v58
	v_fmac_f32_e32 v60, 0x3f317217, v58
	v_cmp_lt_f32_e64 s[0:1], |v58|, s95
	s_nop 1
	v_cndmask_b32_e64 v58, v58, v60, s[0:1]
	s_nop 0
	s_nop 0
	v_add_f32_e32 v58, v59, v58
	v_mul_f32_e32 v59, 0xbd800000, v58
	v_mov_b32_e32 v60, v49
	s_nop 1
	v_mov_b32_dpp v60, v59 row_shr:1 row_mask:0xf bank_mask:0xf
	v_fmac_f32_e32 v60, 0xbd800000, v58
	s_nop 1
	v_add_f32_dpp v59, v60, v60 row_shr:2 row_mask:0xf bank_mask:0xf bound_ctrl:1
	v_mov_b32_e32 v60, v49
	s_nop 0
	v_add_f32_dpp v59, v59, v59 row_shr:4 row_mask:0xf bank_mask:0xf bound_ctrl:1
	s_nop 1
	v_add_f32_dpp v59, v59, v59 row_shr:8 row_mask:0xf bank_mask:0xf bound_ctrl:1
	s_nop 1
	v_mov_b32_dpp v60, v59 row_bcast:15 row_mask:0xa bank_mask:0xf
	v_add_f32_e32 v59, v59, v60
	v_mov_b32_e32 v60, v49
	s_nop 1
	v_mov_b32_dpp v60, v59 row_bcast:31 row_mask:0xc bank_mask:0xf
	v_add_f32_e32 v59, v59, v60
	s_nop 0
	v_readlane_b32 s21, v59, 63
	s_nop 1
	v_sub_f32_e32 v60, s21, v59
	v_fmac_f32_e32 v59, 0x3d800000, v58
	v_cndmask_b32_e64 v60, v59, v60, s[8:9]
	v_pk_mul_f32 v[58:59], v[116:117], v[206:207]
	s_nop 0
	v_add_f32_e32 v58, v61, v58
	v_add_f32_e32 v61, v58, v59
	v_pk_mul_f32 v[58:59], v[124:125], v[204:205]
	s_nop 0
	v_add_f32_e32 v58, v61, v58
	v_add_f32_e32 v58, v58, v59
	v_max_f32_e64 v59, -v58, 0
	v_mul_f32_e64 v58, |v58|, s93
	v_exp_f32_e32 v58, v58
	s_nop 0
	v_add_f32_e32 v58, 1.0, v58
	s_nop 0
	s_nop 1
	s_nop 0
	s_nop 0
	v_log_f32_e32 v58, v58
	s_nop 0
	v_mul_f32_e32 v61, 0x3f317217, v58
	v_fma_f32 v61, v58, s94, -v61
	v_fmac_f32_e32 v61, 0x3377d1cf, v58
	v_fmac_f32_e32 v61, 0x3f317217, v58
	v_cmp_lt_f32_e64 s[0:1], |v58|, s95
	s_nop 1
	v_cndmask_b32_e64 v58, v58, v61, s[0:1]
	s_nop 0
	s_nop 0
	v_add_f32_e32 v58, v59, v58
	v_mul_f32_e32 v59, 0xbd800000, v58
	v_mov_b32_e32 v61, v49
	v_readlane_b32 s0, v254, 2
	s_add_u32 s0, s90, s0
	v_mov_b32_dpp v61, v59 row_shr:1 row_mask:0xf bank_mask:0xf
	v_fmac_f32_e32 v61, 0xbd800000, v58
	v_readlane_b32 s1, v254, 4
	s_addc_u32 s1, s15, s1
	v_add_f32_dpp v59, v61, v61 row_shr:2 row_mask:0xf bank_mask:0xf bound_ctrl:1
	v_mov_b32_e32 v61, v49
	s_lshl_b64 s[0:1], s[0:1], 10
	v_add_f32_dpp v59, v59, v59 row_shr:4 row_mask:0xf bank_mask:0xf bound_ctrl:1
	s_nop 1
	v_add_f32_dpp v59, v59, v59 row_shr:8 row_mask:0xf bank_mask:0xf bound_ctrl:1
	s_nop 1
	v_mov_b32_dpp v61, v59 row_bcast:15 row_mask:0xa bank_mask:0xf
	v_add_f32_e32 v59, v59, v61
	v_mov_b32_e32 v61, v49
	s_nop 1
	v_mov_b32_dpp v61, v59 row_bcast:31 row_mask:0xc bank_mask:0xf
	v_add_f32_e32 v59, v59, v61
	s_nop 0
	v_readlane_b32 s18, v59, 63
	s_nop 1
	v_sub_f32_e32 v61, s18, v59
	v_fmac_f32_e32 v59, 0x3d800000, v58
	v_cndmask_b32_e64 v58, v59, v61, s[8:9]
	v_mul_f32_e32 v59, 0x3fb8aa3b, v126
	v_exp_f32_e32 v72, v59
	v_mul_f32_e32 v59, 0x3fb8aa3b, v127
	v_mul_f32_e32 v58, 0x3fb8aa3b, v58
	v_exp_f32_e32 v73, v59
	v_exp_f32_e32 v78, v58
	v_cvt_pk_bf16_f32 v58, v48, v72
	v_mul_f32_e32 v48, v48, v64
	v_mul_f32_e32 v59, 0x3fb8aa3b, v130
	v_cvt_pk_bf16_f32 v48, v48, s0
	v_exp_f32_e32 v74, v59
	ds_write_b16 v208, v48 offset:57600
	v_mul_f32_e32 v48, v72, v65
	v_mul_f32_e32 v59, 0x3fb8aa3b, v62
	v_cvt_pk_bf16_f32 v48, v48, s0
	v_exp_f32_e32 v75, v59
	ds_write_b16 v208, v48 offset:57744
	v_mul_f32_e32 v48, v73, v66
	v_mul_f32_e32 v59, 0x3fb8aa3b, v63
	v_cvt_pk_bf16_f32 v48, v48, s0
	v_exp_f32_e32 v76, v59
	ds_write_b16 v208, v48 offset:57888
	v_mul_f32_e32 v48, v74, v67
	v_mul_f32_e32 v59, 0x3fb8aa3b, v60
	v_cvt_pk_bf16_f32 v48, v48, s0
	v_exp_f32_e32 v77, v59
	ds_write_b16 v208, v48 offset:58032
	v_mul_f32_e32 v48, v75, v68
	v_cvt_pk_bf16_f32 v48, v48, s0
	ds_write_b16 v208, v48 offset:58176
	v_mul_f32_e32 v48, v76, v69
	v_cvt_pk_bf16_f32 v48, v48, s0
	ds_write_b16 v208, v48 offset:58320
	v_mul_f32_e32 v48, v77, v70
	v_cvt_pk_bf16_f32 v48, v48, s0
	ds_write_b16 v208, v48 offset:58464
	v_mul_f32_e32 v48, v78, v71
	v_cvt_pk_bf16_f32 v59, v73, v74
	v_cvt_pk_bf16_f32 v60, v75, v76
	v_cvt_pk_bf16_f32 v61, v77, v78
	v_lshl_add_u64 v[62:63], v[202:203], 0, s[0:1]
	v_cvt_pk_bf16_f32 v48, v48, s0
	global_store_dwordx4 v[62:63], v[58:61], off
	ds_write_b16 v208, v48 offset:58608
	s_and_saveexec_b64 s[0:1], s[10:11]
	s_cbranch_execz .LBB0_663
	v_mul_f32_e32 v48, s4, v240
	v_exp_f32_e32 v58, v48
	v_mul_f32_e32 v48, s5, v240
	v_exp_f32_e32 v59, v48
	v_mul_f32_e32 v48, s6, v240
	v_exp_f32_e32 v60, v48
	v_mul_f32_e32 v48, s7, v240
	v_exp_f32_e32 v61, v48
	v_mul_f32_e32 v48, s91, v240
	v_exp_f32_e32 v62, v48
	v_mul_f32_e32 v48, s20, v240
	v_exp_f32_e32 v63, v48
	v_mul_f32_e32 v48, s21, v240
	v_exp_f32_e32 v64, v48
	v_mul_f32_e32 v48, s18, v240
	v_exp_f32_e32 v65, v48
	s_add_u32 s4, s16, s88
	s_addc_u32 s5, s17, s89
	global_store_dwordx4 v49, v[58:61], s[4:5] offset:64
	global_store_dwordx4 v49, v[62:65], s[4:5] offset:80
.LBB0_663:
	s_or_b64 exec, exec, s[0:1]
	v_readlane_b32 s0, v255, 19
	v_readlane_b32 s1, v255, 20
	v_lshrrev_b32_e32 v182, 6, v198
	v_and_b32_e32 v183, 1, v182
	v_lshrrev_b32_e32 v182, 1, v182
	v_mul_u32_u24_e32 v183, 0x3000, v183
	v_lshl_add_u32 v183, v182, 7, v183
	v_lshl_add_u32 v182, v182, 6, v183
	v_add_u32_e32 v182, 0x1b000, v182
	ds_read_b128 v[58:61], v182 offset:24688
	ds_read_b128 v[126:129], v182 offset:24672
	ds_read_b128 v[62:65], v182 offset:112
	ds_read_b128 v[130:133], v182 offset:96
	ds_read_b128 v[66:69], v182 offset:880
	ds_read_b128 v[134:137], v182 offset:864
	ds_read_b128 v[70:73], v182 offset:1648
	ds_read_b128 v[138:141], v182 offset:1632
	ds_read_b128 v[74:77], v182 offset:2416
	ds_read_b128 v[142:145], v182 offset:2400
	ds_read_b128 v[78:81], v182 offset:3184
	ds_read_b128 v[146:149], v182 offset:3168
	s_waitcnt lgkmcnt(8)
	ds_read_b128 v[82:85], v182 offset:3952
	ds_read_b128 v[150:153], v182 offset:3936
	ds_read_b128 v[86:89], v182 offset:4720
	ds_read_b128 v[154:157], v182 offset:4704
	s_waitcnt lgkmcnt(8)
	v_readlane_b32 s0, v255, 21
	v_readlane_b32 s1, v255, 22
	s_nop 4
	ds_read_b128 v[90:93], v182 offset:5488
	ds_read_b128 v[158:161], v182 offset:5472
	v_readlane_b32 s0, v255, 23
	v_readlane_b32 s1, v255, 24
	s_nop 4
	ds_read_b128 v[94:97], v182 offset:6256
	ds_read_b128 v[162:165], v182 offset:6240
	s_waitcnt lgkmcnt(8)
	v_readlane_b32 s0, v255, 25
	v_readlane_b32 s1, v255, 26
	s_nop 4
	ds_read_b128 v[98:101], v182 offset:7024
	ds_read_b128 v[166:169], v182 offset:7008
	v_readlane_b32 s0, v255, 27
	v_readlane_b32 s1, v255, 28
	s_nop 4
	ds_read_b128 v[102:105], v182 offset:7792
	ds_read_b128 v[170:173], v182 offset:7776
	s_waitcnt lgkmcnt(8)
	v_readlane_b32 s0, v255, 29
	v_readlane_b32 s1, v255, 30
	s_nop 4
	ds_read_b128 v[106:109], v182 offset:8560
	ds_read_b128 v[174:177], v182 offset:8544
	v_readlane_b32 s0, v255, 31
	v_readlane_b32 s1, v255, 32
	s_nop 4
	ds_read_b128 v[110:113], v182 offset:9328
	ds_read_b128 v[178:181], v182 offset:9312
	s_waitcnt lgkmcnt(8)
	v_readlane_b32 s0, v255, 33
	v_readlane_b32 s1, v255, 34
	s_nop 4
	ds_read_b128 v[114:117], v182 offset:10096
	ds_read_b128 v[182:185], v182 offset:10080
	v_readlane_b32 s0, v255, 35
	v_readlane_b32 s1, v255, 36
	s_waitcnt lgkmcnt(14)
	v_fma_f32 v58, v62, v242, v58
	s_waitcnt lgkmcnt(14)
	v_fma_f32 v48, v130, v242, v126
	s_waitcnt lgkmcnt(14)
	v_fmac_f32_e32 v48, v134, v223
	s_waitcnt lgkmcnt(14)
	v_fmac_f32_e32 v48, v138, v222
	s_waitcnt lgkmcnt(14)
	v_fmac_f32_e32 v48, v142, v221
	s_waitcnt lgkmcnt(14)
	v_fmac_f32_e32 v48, v146, v220
	s_waitcnt lgkmcnt(14)
	v_fmac_f32_e32 v48, v150, v219
	s_waitcnt lgkmcnt(14)
	v_fmac_f32_e32 v48, v154, v218
	v_fmac_f32_e32 v129, v133, v242
	v_fmac_f32_e32 v129, v137, v223
	s_waitcnt lgkmcnt(12)
	v_fmac_f32_e32 v48, v158, v217
	v_fmac_f32_e32 v129, v141, v222
	v_fmac_f32_e32 v129, v145, v221
	s_waitcnt lgkmcnt(10)
	v_fmac_f32_e32 v48, v162, v216
	v_fmac_f32_e32 v129, v149, v220
	v_fmac_f32_e32 v129, v153, v219
	s_waitcnt lgkmcnt(8)
	v_fmac_f32_e32 v48, v166, v215
	v_fmac_f32_e32 v129, v157, v218
	v_fmac_f32_e32 v129, v161, v217
	s_waitcnt lgkmcnt(6)
	v_fmac_f32_e32 v48, v170, v214
	v_fmac_f32_e32 v129, v165, v216
	v_fmac_f32_e32 v129, v169, v215
	s_waitcnt lgkmcnt(4)
	v_fmac_f32_e32 v48, v174, v213
	v_fmac_f32_e32 v129, v173, v214
	v_fmac_f32_e32 v129, v177, v213
	s_waitcnt lgkmcnt(2)
	v_mov_b32_e32 v118, v178
	v_fmac_f32_e32 v58, v66, v223
	v_fmac_f32_e32 v58, v70, v222
	s_waitcnt lgkmcnt(0)
	v_mov_b32_e32 v119, v182
	v_pk_mul_f32 v[118:119], v[118:119], v[206:207]
	v_mov_b32_e32 v182, v179
	v_add_f32_e32 v48, v48, v118
	v_add_f32_e32 v48, v48, v119
	v_lshrrev_b32_e32 v190, 6, v198
	v_and_b32_e32 v191, 1, v190
	v_lshrrev_b32_e32 v190, 1, v190
	v_mul_u32_u24_e32 v191, 0x3000, v191
	v_lshl_add_u32 v191, v190, 7, v191
	v_lshl_add_u32 v190, v190, 6, v191
	v_add_u32_e32 v190, 0x1b000, v190
	ds_read_b128 v[118:121], v190 offset:10864
	ds_read_b128 v[186:189], v190 offset:10848
	v_readlane_b32 s0, v255, 37
	v_readlane_b32 s1, v255, 38
	s_nop 4
	ds_read_b128 v[122:125], v190 offset:11632
	ds_read_b128 v[190:193], v190 offset:11616
	v_fmac_f32_e32 v58, v74, v221
	v_fmac_f32_e32 v58, v78, v220
	v_fmac_f32_e32 v58, v82, v219
	v_fmac_f32_e32 v58, v86, v218
	v_fmac_f32_e32 v58, v90, v217
	v_fmac_f32_e32 v58, v94, v216
	v_fmac_f32_e32 v58, v98, v215
	v_fmac_f32_e32 v58, v102, v214
	v_fmac_f32_e32 v58, v106, v213
	v_fma_f32 v63, v63, v242, v59
	v_fmac_f32_e32 v63, v67, v223
	v_fmac_f32_e32 v63, v71, v222
	v_fmac_f32_e32 v63, v75, v221
	v_fmac_f32_e32 v63, v79, v220
	v_fmac_f32_e32 v63, v83, v219
	v_fmac_f32_e32 v63, v87, v218
	v_fmac_f32_e32 v63, v91, v217
	v_fmac_f32_e32 v63, v95, v216
	v_fmac_f32_e32 v63, v99, v215
	v_fmac_f32_e32 v63, v103, v214
	v_fmac_f32_e32 v63, v107, v213
	v_fma_f32 v60, v64, v242, v60
	v_fmac_f32_e32 v60, v68, v223
	v_fmac_f32_e32 v60, v72, v222
	v_fmac_f32_e32 v60, v76, v221
	v_fmac_f32_e32 v60, v80, v220
	v_fmac_f32_e32 v60, v84, v219
	v_fmac_f32_e32 v60, v88, v218
	v_fmac_f32_e32 v60, v92, v217
	v_fmac_f32_e32 v60, v96, v216
	v_fmac_f32_e32 v60, v100, v215
	v_fmac_f32_e32 v60, v104, v214
	v_fmac_f32_e32 v60, v108, v213
	v_fmac_f32_e32 v61, v65, v242
	v_fmac_f32_e32 v61, v69, v223
	v_fmac_f32_e32 v61, v73, v222
	v_fmac_f32_e32 v61, v77, v221
	v_fmac_f32_e32 v61, v81, v220
	v_fmac_f32_e32 v61, v85, v219
	v_fmac_f32_e32 v61, v89, v218
	v_fmac_f32_e32 v61, v93, v217
	v_fmac_f32_e32 v61, v97, v216
	v_fmac_f32_e32 v61, v101, v215
	v_fmac_f32_e32 v61, v105, v214
	v_fmac_f32_e32 v61, v109, v213
	v_lshlrev_b32_e32 v64, 16, v44
	v_and_b32_e32 v65, 0xffff0000, v44
	v_and_b32_e32 v67, 0xffff0000, v45
	v_lshlrev_b32_e32 v68, 16, v46
	v_and_b32_e32 v69, 0xffff0000, v46
	v_lshlrev_b32_e32 v70, 16, v47
	v_and_b32_e32 v71, 0xffff0000, v47
	s_waitcnt lgkmcnt(2)
	v_mov_b32_e32 v244, v186
	s_waitcnt lgkmcnt(0)
	v_mov_b32_e32 v245, v190
	v_pk_mul_f32 v[244:245], v[244:245], v[204:205]
	v_mov_b32_e32 v190, v187
	v_add_f32_e32 v48, v48, v244
	v_add_f32_e32 v48, v48, v245
	v_max_f32_e64 v126, -v48, 0
	v_mul_f32_e64 v48, |v48|, s93
	v_exp_f32_e32 v48, v48
	s_nop 0
	v_add_f32_e32 v48, 1.0, v48
	s_nop 0
	s_nop 1
	s_nop 0
	s_nop 0
	v_log_f32_e32 v48, v48
	s_nop 0
	v_mul_f32_e32 v130, 0x3f317217, v48
	v_fma_f32 v130, v48, s94, -v130
	v_fmac_f32_e32 v130, 0x3377d1cf, v48
	v_fmac_f32_e32 v130, 0x3f317217, v48
	v_cmp_lt_f32_e64 s[0:1], |v48|, s95
	s_nop 1
	v_cndmask_b32_e64 v48, v48, v130, s[0:1]
	s_nop 0
	s_nop 0
	v_add_f32_e32 v48, v126, v48
	v_mul_f32_e32 v126, 0xbd800000, v48
	v_mov_b32_e32 v130, v49
	s_nop 1
	v_mov_b32_dpp v130, v126 row_shr:1 row_mask:0xf bank_mask:0xf
	v_fmac_f32_e32 v130, 0xbd800000, v48
	s_nop 1
	v_add_f32_dpp v126, v130, v130 row_shr:2 row_mask:0xf bank_mask:0xf bound_ctrl:1
	v_mov_b32_e32 v130, v49
	s_nop 0
	v_add_f32_dpp v126, v126, v126 row_shr:4 row_mask:0xf bank_mask:0xf bound_ctrl:1
	s_nop 1
	v_add_f32_dpp v126, v126, v126 row_shr:8 row_mask:0xf bank_mask:0xf bound_ctrl:1
	s_nop 1
	v_mov_b32_dpp v130, v126 row_bcast:15 row_mask:0xa bank_mask:0xf
	v_add_f32_e32 v126, v126, v130
	v_mov_b32_e32 v130, v49
	s_nop 1
	v_mov_b32_dpp v130, v126 row_bcast:31 row_mask:0xc bank_mask:0xf
	v_add_f32_e32 v126, v126, v130
	s_nop 0
	v_readlane_b32 s4, v126, 63
	s_nop 1
	v_sub_f32_e32 v130, s4, v126
	v_fmac_f32_e32 v126, 0x3d800000, v48
	v_cndmask_b32_e64 v48, v126, v130, s[8:9]
	v_fma_f32 v130, v131, v242, v127
	v_fmac_f32_e32 v130, v135, v223
	v_fmac_f32_e32 v130, v139, v222
	v_fmac_f32_e32 v130, v143, v221
	v_fmac_f32_e32 v130, v147, v220
	v_fmac_f32_e32 v130, v151, v219
	v_fmac_f32_e32 v130, v155, v218
	v_fmac_f32_e32 v130, v159, v217
	v_fmac_f32_e32 v130, v163, v216
	v_fmac_f32_e32 v130, v167, v215
	v_fmac_f32_e32 v130, v171, v214
	v_fmac_f32_e32 v130, v175, v213
	v_pk_mul_f32 v[126:127], v[182:183], v[206:207]
	v_mov_b32_e32 v131, v184
	v_add_f32_e32 v126, v130, v126
	v_add_f32_e32 v130, v126, v127
	v_pk_mul_f32 v[126:127], v[190:191], v[204:205]
	v_mov_b32_e32 v184, v181
	v_add_f32_e32 v126, v130, v126
	v_add_f32_e32 v126, v126, v127
	v_max_f32_e64 v127, -v126, 0
	v_mul_f32_e64 v126, |v126|, s93
	v_exp_f32_e32 v126, v126
	v_mul_f32_e32 v48, 0x3fb8aa3b, v48
	v_exp_f32_e32 v48, v48
	v_add_f32_e32 v126, 1.0, v126
	s_nop 0
	s_nop 1
	s_nop 0
	s_nop 0
	v_log_f32_e32 v126, v126
	s_nop 0
	v_mul_f32_e32 v130, 0x3f317217, v126
	v_fma_f32 v130, v126, s94, -v130
	v_fmac_f32_e32 v130, 0x3377d1cf, v126
	v_fmac_f32_e32 v130, 0x3f317217, v126
	v_cmp_lt_f32_e64 s[0:1], |v126|, s95
	s_nop 1
	v_cndmask_b32_e64 v126, v126, v130, s[0:1]
	s_nop 0
	s_nop 0
	v_add_f32_e32 v126, v127, v126
	v_mul_f32_e32 v127, 0xbd800000, v126
	v_mov_b32_e32 v130, v49
	s_nop 1
	v_mov_b32_dpp v130, v127 row_shr:1 row_mask:0xf bank_mask:0xf
	v_fmac_f32_e32 v130, 0xbd800000, v126
	s_nop 1
	v_add_f32_dpp v127, v130, v130 row_shr:2 row_mask:0xf bank_mask:0xf bound_ctrl:1
	v_mov_b32_e32 v130, v49
	s_nop 0
	v_add_f32_dpp v127, v127, v127 row_shr:4 row_mask:0xf bank_mask:0xf bound_ctrl:1
	s_nop 1
	v_add_f32_dpp v127, v127, v127 row_shr:8 row_mask:0xf bank_mask:0xf bound_ctrl:1
	s_nop 1
	v_mov_b32_dpp v130, v127 row_bcast:15 row_mask:0xa bank_mask:0xf
	v_add_f32_e32 v127, v127, v130
	v_mov_b32_e32 v130, v49
	s_nop 1
	v_mov_b32_dpp v130, v127 row_bcast:31 row_mask:0xc bank_mask:0xf
	v_add_f32_e32 v127, v127, v130
	s_nop 0
	v_readlane_b32 s5, v127, 63
	s_nop 1
	v_sub_f32_e32 v130, s5, v127
	v_fmac_f32_e32 v127, 0x3d800000, v126
	v_cndmask_b32_e64 v126, v127, v130, s[8:9]
	v_fma_f32 v127, v132, v242, v128
	v_fmac_f32_e32 v127, v136, v223
	v_fmac_f32_e32 v127, v140, v222
	v_fmac_f32_e32 v127, v144, v221
	v_fmac_f32_e32 v127, v148, v220
	v_fmac_f32_e32 v127, v152, v219
	v_fmac_f32_e32 v127, v156, v218
	v_fmac_f32_e32 v127, v160, v217
	v_fmac_f32_e32 v127, v164, v216
	v_fmac_f32_e32 v127, v168, v215
	v_fmac_f32_e32 v127, v172, v214
	v_mov_b32_e32 v130, v180
	v_fmac_f32_e32 v127, v176, v213
	v_pk_mul_f32 v[130:131], v[130:131], v[206:207]
	s_nop 0
	v_add_f32_e32 v127, v127, v130
	v_add_f32_e32 v127, v127, v131
	v_mov_b32_e32 v130, v188
	v_mov_b32_e32 v131, v192
	v_pk_mul_f32 v[130:131], v[130:131], v[204:205]
	v_mov_b32_e32 v192, v189
	v_add_f32_e32 v127, v127, v130
	v_add_f32_e32 v127, v127, v131
	v_max_f32_e64 v128, -v127, 0
	v_mul_f32_e64 v127, |v127|, s93
	v_exp_f32_e32 v127, v127
	s_nop 0
	v_add_f32_e32 v127, 1.0, v127
	s_nop 0
	s_nop 1
	s_nop 0
	s_nop 0
	v_log_f32_e32 v127, v127
	s_nop 0
	v_mul_f32_e32 v130, 0x3f317217, v127
	v_fma_f32 v130, v127, s94, -v130
	v_fmac_f32_e32 v130, 0x3377d1cf, v127
	v_fmac_f32_e32 v130, 0x3f317217, v127
	v_cmp_lt_f32_e64 s[0:1], |v127|, s95
	s_nop 1
	v_cndmask_b32_e64 v127, v127, v130, s[0:1]
	s_nop 0
	s_nop 0
	v_add_f32_e32 v127, v128, v127
	v_mul_f32_e32 v128, 0xbd800000, v127
	v_mov_b32_e32 v130, v49
	s_nop 1
	v_mov_b32_dpp v130, v128 row_shr:1 row_mask:0xf bank_mask:0xf
	v_fmac_f32_e32 v130, 0xbd800000, v127
	s_nop 1
	v_add_f32_dpp v128, v130, v130 row_shr:2 row_mask:0xf bank_mask:0xf bound_ctrl:1
	v_mov_b32_e32 v130, v49
	s_nop 0
	v_add_f32_dpp v128, v128, v128 row_shr:4 row_mask:0xf bank_mask:0xf bound_ctrl:1
	s_nop 1
	v_add_f32_dpp v128, v128, v128 row_shr:8 row_mask:0xf bank_mask:0xf bound_ctrl:1
	s_nop 1
	v_mov_b32_dpp v130, v128 row_bcast:15 row_mask:0xa bank_mask:0xf
	v_add_f32_e32 v128, v128, v130
	v_mov_b32_e32 v130, v49
	s_nop 1
	v_mov_b32_dpp v130, v128 row_bcast:31 row_mask:0xc bank_mask:0xf
	v_add_f32_e32 v128, v128, v130
	s_nop 0
	v_readlane_b32 s6, v128, 63
	s_nop 1
	v_sub_f32_e32 v130, s6, v128
	v_fmac_f32_e32 v128, 0x3d800000, v127
	v_cndmask_b32_e64 v127, v128, v130, s[8:9]
	v_pk_mul_f32 v[130:131], v[184:185], v[206:207]
	s_nop 0
	v_add_f32_e32 v128, v129, v130
	v_add_f32_e32 v130, v128, v131
	v_pk_mul_f32 v[128:129], v[192:193], v[204:205]
	s_nop 0
	v_add_f32_e32 v128, v130, v128
	v_add_f32_e32 v128, v128, v129
	v_max_f32_e64 v129, -v128, 0
	v_mul_f32_e64 v128, |v128|, s93
	v_exp_f32_e32 v128, v128
	s_nop 0
	v_add_f32_e32 v128, 1.0, v128
	s_nop 0
	s_nop 1
	s_nop 0
	s_nop 0
	v_log_f32_e32 v128, v128
	s_nop 0
	v_mul_f32_e32 v130, 0x3f317217, v128
	v_fma_f32 v130, v128, s94, -v130
	v_fmac_f32_e32 v130, 0x3377d1cf, v128
	v_fmac_f32_e32 v130, 0x3f317217, v128
	v_cmp_lt_f32_e64 s[0:1], |v128|, s95
	s_nop 1
	v_cndmask_b32_e64 v128, v128, v130, s[0:1]
	s_nop 0
	s_nop 0
	v_add_f32_e32 v128, v129, v128
	v_mul_f32_e32 v129, 0xbd800000, v128
	v_mov_b32_e32 v130, v49
	s_nop 1
	v_mov_b32_dpp v130, v129 row_shr:1 row_mask:0xf bank_mask:0xf
	v_fmac_f32_e32 v130, 0xbd800000, v128
	s_nop 1
	v_add_f32_dpp v129, v130, v130 row_shr:2 row_mask:0xf bank_mask:0xf bound_ctrl:1
	v_mov_b32_e32 v130, v49
	s_nop 0
	v_add_f32_dpp v129, v129, v129 row_shr:4 row_mask:0xf bank_mask:0xf bound_ctrl:1
	s_nop 1
	v_add_f32_dpp v129, v129, v129 row_shr:8 row_mask:0xf bank_mask:0xf bound_ctrl:1
	s_nop 1
	v_mov_b32_dpp v130, v129 row_bcast:15 row_mask:0xa bank_mask:0xf
	v_add_f32_e32 v129, v129, v130
	v_mov_b32_e32 v130, v49
	s_nop 1
	v_mov_b32_dpp v130, v129 row_bcast:31 row_mask:0xc bank_mask:0xf
	v_add_f32_e32 v129, v129, v130
	s_nop 0
	v_readlane_b32 s7, v129, 63
	s_nop 1
	v_sub_f32_e32 v130, s7, v129
	v_fmac_f32_e32 v129, 0x3d800000, v128
	v_cndmask_b32_e64 v130, v129, v130, s[8:9]
	v_mov_b32_e32 v128, v110
	v_mov_b32_e32 v129, v114
	v_pk_mul_f32 v[128:129], v[128:129], v[206:207]
	v_mov_b32_e32 v114, v111
	v_add_f32_e32 v58, v58, v128
	v_add_f32_e32 v58, v58, v129
	v_mov_b32_e32 v128, v118
	v_mov_b32_e32 v129, v122
	v_pk_mul_f32 v[128:129], v[128:129], v[204:205]
	v_mov_b32_e32 v122, v119
	v_add_f32_e32 v58, v58, v128
	v_add_f32_e32 v58, v58, v129
	v_max_f32_e64 v62, -v58, 0
	v_mul_f32_e64 v58, |v58|, s93
	v_exp_f32_e32 v58, v58
	s_nop 0
	v_add_f32_e32 v58, 1.0, v58
	s_nop 0
	s_nop 1
	s_nop 0
	s_nop 0
	v_log_f32_e32 v58, v58
	s_nop 0
	v_mul_f32_e32 v66, 0x3f317217, v58
	v_fma_f32 v66, v58, s94, -v66
	v_fmac_f32_e32 v66, 0x3377d1cf, v58
	v_fmac_f32_e32 v66, 0x3f317217, v58
	v_cmp_lt_f32_e64 s[0:1], |v58|, s95
	s_nop 1
	v_cndmask_b32_e64 v58, v58, v66, s[0:1]
	s_nop 0
	s_nop 0
	v_add_f32_e32 v58, v62, v58
	v_mul_f32_e32 v62, 0xbd800000, v58
	v_mov_b32_e32 v66, v49
	s_nop 1
	v_mov_b32_dpp v66, v62 row_shr:1 row_mask:0xf bank_mask:0xf
	v_fmac_f32_e32 v66, 0xbd800000, v58
	s_nop 1
	v_add_f32_dpp v62, v66, v66 row_shr:2 row_mask:0xf bank_mask:0xf bound_ctrl:1
	v_mov_b32_e32 v66, v49
	s_nop 0
	v_add_f32_dpp v62, v62, v62 row_shr:4 row_mask:0xf bank_mask:0xf bound_ctrl:1
	s_nop 1
	v_add_f32_dpp v62, v62, v62 row_shr:8 row_mask:0xf bank_mask:0xf bound_ctrl:1
	s_nop 1
	v_mov_b32_dpp v66, v62 row_bcast:15 row_mask:0xa bank_mask:0xf
	v_add_f32_e32 v62, v62, v66
	v_mov_b32_e32 v66, v49
	s_nop 1
	v_mov_b32_dpp v66, v62 row_bcast:31 row_mask:0xc bank_mask:0xf
	v_add_f32_e32 v62, v62, v66
	s_nop 0
	v_readlane_b32 s91, v62, 63
	s_nop 1
	v_sub_f32_e32 v66, s91, v62
	v_fmac_f32_e32 v62, 0x3d800000, v58
	v_pk_mul_f32 v[58:59], v[114:115], v[206:207]
	v_cndmask_b32_e64 v62, v62, v66, s[8:9]
	v_add_f32_e32 v58, v63, v58
	v_add_f32_e32 v63, v58, v59
	v_pk_mul_f32 v[58:59], v[122:123], v[204:205]
	v_lshlrev_b32_e32 v66, 16, v45
	v_add_f32_e32 v58, v63, v58
	v_add_f32_e32 v58, v58, v59
	v_max_f32_e64 v59, -v58, 0
	v_mul_f32_e64 v58, |v58|, s93
	v_exp_f32_e32 v58, v58
	s_nop 0
	v_add_f32_e32 v58, 1.0, v58
	s_nop 0
	s_nop 1
	s_nop 0
	s_nop 0
	v_log_f32_e32 v58, v58
	s_nop 0
	v_mul_f32_e32 v63, 0x3f317217, v58
	v_fma_f32 v63, v58, s94, -v63
	v_fmac_f32_e32 v63, 0x3377d1cf, v58
	v_fmac_f32_e32 v63, 0x3f317217, v58
	v_cmp_lt_f32_e64 s[0:1], |v58|, s95
	s_nop 1
	v_cndmask_b32_e64 v58, v58, v63, s[0:1]
	s_nop 0
	s_nop 0
	v_add_f32_e32 v58, v59, v58
	v_mul_f32_e32 v59, 0xbd800000, v58
	v_mov_b32_e32 v63, v49
	s_nop 1
	v_mov_b32_dpp v63, v59 row_shr:1 row_mask:0xf bank_mask:0xf
	v_fmac_f32_e32 v63, 0xbd800000, v58
	s_nop 1
	v_add_f32_dpp v59, v63, v63 row_shr:2 row_mask:0xf bank_mask:0xf bound_ctrl:1
	v_mov_b32_e32 v63, v49
	s_nop 0
	v_add_f32_dpp v59, v59, v59 row_shr:4 row_mask:0xf bank_mask:0xf bound_ctrl:1
	s_nop 1
	v_add_f32_dpp v59, v59, v59 row_shr:8 row_mask:0xf bank_mask:0xf bound_ctrl:1
	s_nop 1
	v_mov_b32_dpp v63, v59 row_bcast:15 row_mask:0xa bank_mask:0xf
	v_add_f32_e32 v59, v59, v63
	v_mov_b32_e32 v63, v49
	s_nop 1
	v_mov_b32_dpp v63, v59 row_bcast:31 row_mask:0xc bank_mask:0xf
	v_add_f32_e32 v59, v59, v63
	s_nop 0
	v_readlane_b32 s20, v59, 63
	s_nop 1
	v_sub_f32_e32 v63, s20, v59
	v_fmac_f32_e32 v59, 0x3d800000, v58
	v_cndmask_b32_e64 v63, v59, v63, s[8:9]
	v_mov_b32_e32 v58, v112
	v_mov_b32_e32 v59, v116
	v_pk_mul_f32 v[58:59], v[58:59], v[206:207]
	v_mov_b32_e32 v116, v113
	v_add_f32_e32 v58, v60, v58
	v_add_f32_e32 v60, v58, v59
	v_mov_b32_e32 v58, v120
	v_mov_b32_e32 v59, v124
	v_pk_mul_f32 v[58:59], v[58:59], v[204:205]
	v_mov_b32_e32 v124, v121
	v_add_f32_e32 v58, v60, v58
	v_add_f32_e32 v58, v58, v59
	v_max_f32_e64 v59, -v58, 0
	v_mul_f32_e64 v58, |v58|, s93
	v_exp_f32_e32 v58, v58
	s_nop 0
	v_add_f32_e32 v58, 1.0, v58
	s_nop 0
	s_nop 1
	s_nop 0
	s_nop 0
	v_log_f32_e32 v58, v58
	s_nop 0
	v_mul_f32_e32 v60, 0x3f317217, v58
	v_fma_f32 v60, v58, s94, -v60
	v_fmac_f32_e32 v60, 0x3377d1cf, v58
	v_fmac_f32_e32 v60, 0x3f317217, v58
	v_cmp_lt_f32_e64 s[0:1], |v58|, s95
	s_nop 1
	v_cndmask_b32_e64 v58, v58, v60, s[0:1]
	s_nop 0
	s_nop 0
	v_add_f32_e32 v58, v59, v58
	v_mul_f32_e32 v59, 0xbd800000, v58
	v_mov_b32_e32 v60, v49
	s_nop 1
	v_mov_b32_dpp v60, v59 row_shr:1 row_mask:0xf bank_mask:0xf
	v_fmac_f32_e32 v60, 0xbd800000, v58
	s_nop 1
	v_add_f32_dpp v59, v60, v60 row_shr:2 row_mask:0xf bank_mask:0xf bound_ctrl:1
	v_mov_b32_e32 v60, v49
	s_nop 0
	v_add_f32_dpp v59, v59, v59 row_shr:4 row_mask:0xf bank_mask:0xf bound_ctrl:1
	s_nop 1
	v_add_f32_dpp v59, v59, v59 row_shr:8 row_mask:0xf bank_mask:0xf bound_ctrl:1
	s_nop 1
	v_mov_b32_dpp v60, v59 row_bcast:15 row_mask:0xa bank_mask:0xf
	v_add_f32_e32 v59, v59, v60
	v_mov_b32_e32 v60, v49
	s_nop 1
	v_mov_b32_dpp v60, v59 row_bcast:31 row_mask:0xc bank_mask:0xf
	v_add_f32_e32 v59, v59, v60
	s_nop 0
	v_readlane_b32 s21, v59, 63
	s_nop 1
	v_sub_f32_e32 v60, s21, v59
	v_fmac_f32_e32 v59, 0x3d800000, v58
	v_cndmask_b32_e64 v60, v59, v60, s[8:9]
	v_pk_mul_f32 v[58:59], v[116:117], v[206:207]
	s_nop 0
	v_add_f32_e32 v58, v61, v58
	v_add_f32_e32 v61, v58, v59
	v_pk_mul_f32 v[58:59], v[124:125], v[204:205]
	s_nop 0
	v_add_f32_e32 v58, v61, v58
	v_add_f32_e32 v58, v58, v59
	v_max_f32_e64 v59, -v58, 0
	v_mul_f32_e64 v58, |v58|, s93
	v_exp_f32_e32 v58, v58
	s_nop 0
	v_add_f32_e32 v58, 1.0, v58
	s_nop 0
	s_nop 1
	s_nop 0
	s_nop 0
	v_log_f32_e32 v58, v58
	s_nop 0
	v_mul_f32_e32 v61, 0x3f317217, v58
	v_fma_f32 v61, v58, s94, -v61
	v_fmac_f32_e32 v61, 0x3377d1cf, v58
	v_fmac_f32_e32 v61, 0x3f317217, v58
	v_cmp_lt_f32_e64 s[0:1], |v58|, s95
	s_nop 1
	v_cndmask_b32_e64 v58, v58, v61, s[0:1]
	s_nop 0
	s_nop 0
	v_add_f32_e32 v58, v59, v58
	v_mul_f32_e32 v59, 0xbd800000, v58
	v_mov_b32_e32 v61, v49
	v_readlane_b32 s0, v254, 6
	s_add_u32 s0, s90, s0
	v_mov_b32_dpp v61, v59 row_shr:1 row_mask:0xf bank_mask:0xf
	v_fmac_f32_e32 v61, 0xbd800000, v58
	v_readlane_b32 s1, v254, 8
	s_addc_u32 s1, s15, s1
	v_add_f32_dpp v59, v61, v61 row_shr:2 row_mask:0xf bank_mask:0xf bound_ctrl:1
	v_mov_b32_e32 v61, v49
	s_lshl_b64 s[0:1], s[0:1], 10
	v_add_f32_dpp v59, v59, v59 row_shr:4 row_mask:0xf bank_mask:0xf bound_ctrl:1
	s_nop 1
	v_add_f32_dpp v59, v59, v59 row_shr:8 row_mask:0xf bank_mask:0xf bound_ctrl:1
	s_nop 1
	v_mov_b32_dpp v61, v59 row_bcast:15 row_mask:0xa bank_mask:0xf
	v_add_f32_e32 v59, v59, v61
	v_mov_b32_e32 v61, v49
	s_nop 1
	v_mov_b32_dpp v61, v59 row_bcast:31 row_mask:0xc bank_mask:0xf
	v_add_f32_e32 v59, v59, v61
	s_nop 0
	v_readlane_b32 s18, v59, 63
	s_nop 1
	v_sub_f32_e32 v61, s18, v59
	v_fmac_f32_e32 v59, 0x3d800000, v58
	v_cndmask_b32_e64 v58, v59, v61, s[8:9]
	v_mul_f32_e32 v59, 0x3fb8aa3b, v126
	v_exp_f32_e32 v72, v59
	v_mul_f32_e32 v59, 0x3fb8aa3b, v127
	v_mul_f32_e32 v58, 0x3fb8aa3b, v58
	v_exp_f32_e32 v73, v59
	v_exp_f32_e32 v78, v58
	v_cvt_pk_bf16_f32 v58, v48, v72
	v_mul_f32_e32 v48, v48, v64
	v_mul_f32_e32 v59, 0x3fb8aa3b, v130
	v_cvt_pk_bf16_f32 v48, v48, s0
	v_exp_f32_e32 v74, v59
	ds_write_b16 v208, v48 offset:58752
	v_mul_f32_e32 v48, v72, v65
	v_mul_f32_e32 v59, 0x3fb8aa3b, v62
	v_cvt_pk_bf16_f32 v48, v48, s0
	v_exp_f32_e32 v75, v59
	ds_write_b16 v208, v48 offset:58896
	v_mul_f32_e32 v48, v73, v66
	v_mul_f32_e32 v59, 0x3fb8aa3b, v63
	v_cvt_pk_bf16_f32 v48, v48, s0
	v_exp_f32_e32 v76, v59
	ds_write_b16 v208, v48 offset:59040
	v_mul_f32_e32 v48, v74, v67
	v_mul_f32_e32 v59, 0x3fb8aa3b, v60
	v_cvt_pk_bf16_f32 v48, v48, s0
	v_exp_f32_e32 v77, v59
	ds_write_b16 v208, v48 offset:59184
	v_mul_f32_e32 v48, v75, v68
	v_cvt_pk_bf16_f32 v48, v48, s0
	ds_write_b16 v208, v48 offset:59328
	v_mul_f32_e32 v48, v76, v69
	v_cvt_pk_bf16_f32 v48, v48, s0
	ds_write_b16 v208, v48 offset:59472
	v_mul_f32_e32 v48, v77, v70
	v_cvt_pk_bf16_f32 v48, v48, s0
	ds_write_b16 v208, v48 offset:59616
	v_mul_f32_e32 v48, v78, v71
	v_cvt_pk_bf16_f32 v59, v73, v74
	v_cvt_pk_bf16_f32 v60, v75, v76
	v_cvt_pk_bf16_f32 v61, v77, v78
	v_lshl_add_u64 v[62:63], v[202:203], 0, s[0:1]
	v_cvt_pk_bf16_f32 v48, v48, s0
	global_store_dwordx4 v[62:63], v[58:61], off
	ds_write_b16 v208, v48 offset:59760
	s_and_saveexec_b64 s[0:1], s[10:11]
	s_cbranch_execz .LBB0_665
	v_mul_f32_e32 v48, s4, v240
	v_exp_f32_e32 v58, v48
	v_mul_f32_e32 v48, s5, v240
	v_exp_f32_e32 v59, v48
	v_mul_f32_e32 v48, s6, v240
	v_exp_f32_e32 v60, v48
	v_mul_f32_e32 v48, s7, v240
	v_exp_f32_e32 v61, v48
	v_mul_f32_e32 v48, s91, v240
	v_exp_f32_e32 v62, v48
	v_mul_f32_e32 v48, s20, v240
	v_exp_f32_e32 v63, v48
	v_mul_f32_e32 v48, s21, v240
	v_exp_f32_e32 v64, v48
	v_mul_f32_e32 v48, s18, v240
	v_exp_f32_e32 v65, v48
	s_add_u32 s4, s16, s88
	s_addc_u32 s5, s17, s89
	global_store_dwordx4 v49, v[58:61], s[4:5] offset:96
	global_store_dwordx4 v49, v[62:65], s[4:5] offset:112
.LBB0_665:
	s_or_b64 exec, exec, s[0:1]
	v_lshrrev_b32_e32 v182, 6, v198
	v_and_b32_e32 v183, 1, v182
	v_lshrrev_b32_e32 v182, 1, v182
	v_mul_u32_u24_e32 v183, 0x3000, v183
	v_lshl_add_u32 v183, v182, 7, v183
	v_lshl_add_u32 v182, v182, 6, v183
	v_add_u32_e32 v182, 0x1b000, v182
	ds_read_b128 v[58:61], v182 offset:24720
	ds_read_b128 v[126:129], v182 offset:24704
	ds_read_b128 v[62:65], v182 offset:144
	ds_read_b128 v[130:133], v182 offset:128
	ds_read_b128 v[66:69], v182 offset:912
	ds_read_b128 v[134:137], v182 offset:896
	ds_read_b128 v[70:73], v182 offset:1680
	ds_read_b128 v[138:141], v182 offset:1664
	ds_read_b128 v[74:77], v182 offset:2448
	ds_read_b128 v[142:145], v182 offset:2432
	v_readlane_b32 s0, v255, 39
	ds_read_b128 v[78:81], v182 offset:3216
	ds_read_b128 v[146:149], v182 offset:3200
	s_waitcnt lgkmcnt(8)
	v_readlane_b32 s1, v255, 40
	ds_read_b128 v[82:85], v182 offset:3984
	ds_read_b128 v[150:153], v182 offset:3968
	s_nop 2
	ds_read_b128 v[86:89], v182 offset:4752
	ds_read_b128 v[154:157], v182 offset:4736
	s_waitcnt lgkmcnt(8)
	v_readlane_b32 s0, v255, 41
	v_readlane_b32 s1, v255, 42
	s_nop 4
	ds_read_b128 v[90:93], v182 offset:5520
	ds_read_b128 v[158:161], v182 offset:5504
	ds_read_b128 v[94:97], v182 offset:6288
	ds_read_b128 v[162:165], v182 offset:6272
	s_waitcnt lgkmcnt(8)
	ds_read_b128 v[98:101], v182 offset:7056
	ds_read_b128 v[166:169], v182 offset:7040
	ds_read_b128 v[102:105], v182 offset:7824
	ds_read_b128 v[170:173], v182 offset:7808
	s_waitcnt lgkmcnt(8)
	ds_read_b128 v[106:109], v182 offset:8592
	ds_read_b128 v[174:177], v182 offset:8576
	ds_read_b128 v[110:113], v182 offset:9360
	ds_read_b128 v[178:181], v182 offset:9344
	s_waitcnt lgkmcnt(8)
	ds_read_b128 v[114:117], v182 offset:10128
	ds_read_b128 v[182:185], v182 offset:10112
	s_waitcnt lgkmcnt(14)
	v_fma_f32 v58, v62, v242, v58
	s_waitcnt lgkmcnt(14)
	v_fma_f32 v48, v130, v242, v126
	s_waitcnt lgkmcnt(14)
	v_fmac_f32_e32 v48, v134, v223
	s_waitcnt lgkmcnt(14)
	v_fmac_f32_e32 v48, v138, v222
	s_waitcnt lgkmcnt(14)
	v_fmac_f32_e32 v48, v142, v221
	v_fmac_f32_e32 v129, v133, v242
	s_waitcnt lgkmcnt(14)
	v_fmac_f32_e32 v48, v146, v220
	v_fmac_f32_e32 v129, v137, v223
	s_waitcnt lgkmcnt(14)
	v_fmac_f32_e32 v48, v150, v219
	s_waitcnt lgkmcnt(14)
	v_fmac_f32_e32 v48, v154, v218
	v_fmac_f32_e32 v129, v141, v222
	v_fmac_f32_e32 v129, v145, v221
	s_waitcnt lgkmcnt(12)
	v_fmac_f32_e32 v48, v158, v217
	s_waitcnt lgkmcnt(10)
	v_fmac_f32_e32 v48, v162, v216
	s_waitcnt lgkmcnt(8)
	v_fmac_f32_e32 v48, v166, v215
	s_waitcnt lgkmcnt(6)
	v_fmac_f32_e32 v48, v170, v214
	s_waitcnt lgkmcnt(2)
	v_mov_b32_e32 v118, v178
	s_waitcnt lgkmcnt(0)
	v_mov_b32_e32 v119, v182
	v_fmac_f32_e32 v48, v174, v213
	v_pk_mul_f32 v[118:119], v[118:119], v[206:207]
	v_mov_b32_e32 v182, v179
	v_add_f32_e32 v48, v48, v118
	v_add_f32_e32 v48, v48, v119
	v_lshrrev_b32_e32 v190, 6, v198
	v_and_b32_e32 v191, 1, v190
	v_lshrrev_b32_e32 v190, 1, v190
	v_mul_u32_u24_e32 v191, 0x3000, v191
	v_lshl_add_u32 v191, v190, 7, v191
	v_lshl_add_u32 v190, v190, 6, v191
	v_add_u32_e32 v190, 0x1b000, v190
	ds_read_b128 v[118:121], v190 offset:10896
	ds_read_b128 v[186:189], v190 offset:10880
	ds_read_b128 v[122:125], v190 offset:11664
	ds_read_b128 v[190:193], v190 offset:11648
	v_fmac_f32_e32 v129, v149, v220
	v_fmac_f32_e32 v129, v153, v219
	v_fmac_f32_e32 v129, v157, v218
	v_fmac_f32_e32 v129, v161, v217
	v_fmac_f32_e32 v129, v165, v216
	v_fmac_f32_e32 v129, v169, v215
	v_fmac_f32_e32 v129, v173, v214
	v_fmac_f32_e32 v129, v177, v213
	v_fmac_f32_e32 v58, v66, v223
	v_fmac_f32_e32 v58, v70, v222
	v_fmac_f32_e32 v58, v74, v221
	v_fmac_f32_e32 v58, v78, v220
	v_fmac_f32_e32 v58, v82, v219
	v_fmac_f32_e32 v58, v86, v218
	v_fmac_f32_e32 v58, v90, v217
	v_fmac_f32_e32 v58, v94, v216
	v_fmac_f32_e32 v58, v98, v215
	v_fmac_f32_e32 v58, v102, v214
	v_fmac_f32_e32 v58, v106, v213
	v_fma_f32 v63, v63, v242, v59
	v_fmac_f32_e32 v63, v67, v223
	v_fmac_f32_e32 v63, v71, v222
	v_fmac_f32_e32 v63, v75, v221
	v_fmac_f32_e32 v63, v79, v220
	v_fmac_f32_e32 v63, v83, v219
	v_fmac_f32_e32 v63, v87, v218
	v_fmac_f32_e32 v63, v91, v217
	v_fmac_f32_e32 v63, v95, v216
	v_fmac_f32_e32 v63, v99, v215
	v_fmac_f32_e32 v63, v103, v214
	v_fmac_f32_e32 v63, v107, v213
	v_fma_f32 v60, v64, v242, v60
	v_fmac_f32_e32 v60, v68, v223
	v_fmac_f32_e32 v60, v72, v222
	v_fmac_f32_e32 v60, v76, v221
	v_fmac_f32_e32 v60, v80, v220
	v_fmac_f32_e32 v60, v84, v219
	v_fmac_f32_e32 v60, v88, v218
	v_fmac_f32_e32 v60, v92, v217
	v_fmac_f32_e32 v60, v96, v216
	v_fmac_f32_e32 v60, v100, v215
	v_fmac_f32_e32 v60, v104, v214
	v_fmac_f32_e32 v60, v108, v213
	v_fmac_f32_e32 v61, v65, v242
	v_fmac_f32_e32 v61, v69, v223
	v_fmac_f32_e32 v61, v73, v222
	v_fmac_f32_e32 v61, v77, v221
	v_fmac_f32_e32 v61, v81, v220
	v_fmac_f32_e32 v61, v85, v219
	v_fmac_f32_e32 v61, v89, v218
	v_fmac_f32_e32 v61, v93, v217
	v_fmac_f32_e32 v61, v97, v216
	v_fmac_f32_e32 v61, v101, v215
	v_fmac_f32_e32 v61, v105, v214
	v_fmac_f32_e32 v61, v109, v213
	v_lshlrev_b32_e32 v64, 16, v50
	v_and_b32_e32 v65, 0xffff0000, v50
	v_and_b32_e32 v67, 0xffff0000, v51
	v_lshlrev_b32_e32 v68, 16, v52
	v_and_b32_e32 v69, 0xffff0000, v52
	v_lshlrev_b32_e32 v70, 16, v53
	v_and_b32_e32 v71, 0xffff0000, v53
	s_waitcnt lgkmcnt(2)
	v_mov_b32_e32 v244, v186
	s_waitcnt lgkmcnt(0)
	v_mov_b32_e32 v245, v190
	v_pk_mul_f32 v[244:245], v[244:245], v[204:205]
	v_mov_b32_e32 v190, v187
	v_add_f32_e32 v48, v48, v244
	v_add_f32_e32 v48, v48, v245
	v_max_f32_e64 v126, -v48, 0
	v_mul_f32_e64 v48, |v48|, s93
	v_exp_f32_e32 v48, v48
	s_nop 0
	v_add_f32_e32 v48, 1.0, v48
	s_nop 0
	s_nop 1
	s_nop 0
	s_nop 0
	v_log_f32_e32 v48, v48
	s_nop 0
	v_mul_f32_e32 v130, 0x3f317217, v48
	v_fma_f32 v130, v48, s94, -v130
	v_fmac_f32_e32 v130, 0x3377d1cf, v48
	v_fmac_f32_e32 v130, 0x3f317217, v48
	v_cmp_lt_f32_e64 s[0:1], |v48|, s95
	s_nop 1
	v_cndmask_b32_e64 v48, v48, v130, s[0:1]
	s_nop 0
	s_nop 0
	v_add_f32_e32 v48, v126, v48
	v_mul_f32_e32 v126, 0xbd800000, v48
	v_mov_b32_e32 v130, v49
	s_nop 1
	v_mov_b32_dpp v130, v126 row_shr:1 row_mask:0xf bank_mask:0xf
	v_fmac_f32_e32 v130, 0xbd800000, v48
	s_nop 1
	v_add_f32_dpp v126, v130, v130 row_shr:2 row_mask:0xf bank_mask:0xf bound_ctrl:1
	v_mov_b32_e32 v130, v49
	s_nop 0
	v_add_f32_dpp v126, v126, v126 row_shr:4 row_mask:0xf bank_mask:0xf bound_ctrl:1
	s_nop 1
	v_add_f32_dpp v126, v126, v126 row_shr:8 row_mask:0xf bank_mask:0xf bound_ctrl:1
	s_nop 1
	v_mov_b32_dpp v130, v126 row_bcast:15 row_mask:0xa bank_mask:0xf
	v_add_f32_e32 v126, v126, v130
	v_mov_b32_e32 v130, v49
	s_nop 1
	v_mov_b32_dpp v130, v126 row_bcast:31 row_mask:0xc bank_mask:0xf
	v_add_f32_e32 v126, v126, v130
	s_nop 0
	v_readlane_b32 s4, v126, 63
	s_nop 1
	v_sub_f32_e32 v130, s4, v126
	v_fmac_f32_e32 v126, 0x3d800000, v48
	v_cndmask_b32_e64 v48, v126, v130, s[8:9]
	v_fma_f32 v130, v131, v242, v127
	v_fmac_f32_e32 v130, v135, v223
	v_fmac_f32_e32 v130, v139, v222
	v_fmac_f32_e32 v130, v143, v221
	v_fmac_f32_e32 v130, v147, v220
	v_fmac_f32_e32 v130, v151, v219
	v_fmac_f32_e32 v130, v155, v218
	v_fmac_f32_e32 v130, v159, v217
	v_fmac_f32_e32 v130, v163, v216
	v_fmac_f32_e32 v130, v167, v215
	v_fmac_f32_e32 v130, v171, v214
	v_fmac_f32_e32 v130, v175, v213
	v_pk_mul_f32 v[126:127], v[182:183], v[206:207]
	v_mov_b32_e32 v131, v184
	v_add_f32_e32 v126, v130, v126
	v_add_f32_e32 v130, v126, v127
	v_pk_mul_f32 v[126:127], v[190:191], v[204:205]
	v_mov_b32_e32 v184, v181
	v_add_f32_e32 v126, v130, v126
	v_add_f32_e32 v126, v126, v127
	v_max_f32_e64 v127, -v126, 0
	v_mul_f32_e64 v126, |v126|, s93
	v_exp_f32_e32 v126, v126
	v_mul_f32_e32 v48, 0x3fb8aa3b, v48
	v_exp_f32_e32 v48, v48
	v_add_f32_e32 v126, 1.0, v126
	s_nop 0
	s_nop 1
	s_nop 0
	s_nop 0
	v_log_f32_e32 v126, v126
	s_nop 0
	v_mul_f32_e32 v130, 0x3f317217, v126
	v_fma_f32 v130, v126, s94, -v130
	v_fmac_f32_e32 v130, 0x3377d1cf, v126
	v_fmac_f32_e32 v130, 0x3f317217, v126
	v_cmp_lt_f32_e64 s[0:1], |v126|, s95
	s_nop 1
	v_cndmask_b32_e64 v126, v126, v130, s[0:1]
	s_nop 0
	s_nop 0
	v_add_f32_e32 v126, v127, v126
	v_mul_f32_e32 v127, 0xbd800000, v126
	v_mov_b32_e32 v130, v49
	s_nop 1
	v_mov_b32_dpp v130, v127 row_shr:1 row_mask:0xf bank_mask:0xf
	v_fmac_f32_e32 v130, 0xbd800000, v126
	s_nop 1
	v_add_f32_dpp v127, v130, v130 row_shr:2 row_mask:0xf bank_mask:0xf bound_ctrl:1
	v_mov_b32_e32 v130, v49
	s_nop 0
	v_add_f32_dpp v127, v127, v127 row_shr:4 row_mask:0xf bank_mask:0xf bound_ctrl:1
	s_nop 1
	v_add_f32_dpp v127, v127, v127 row_shr:8 row_mask:0xf bank_mask:0xf bound_ctrl:1
	s_nop 1
	v_mov_b32_dpp v130, v127 row_bcast:15 row_mask:0xa bank_mask:0xf
	v_add_f32_e32 v127, v127, v130
	v_mov_b32_e32 v130, v49
	s_nop 1
	v_mov_b32_dpp v130, v127 row_bcast:31 row_mask:0xc bank_mask:0xf
	v_add_f32_e32 v127, v127, v130
	s_nop 0
	v_readlane_b32 s5, v127, 63
	s_nop 1
	v_sub_f32_e32 v130, s5, v127
	v_fmac_f32_e32 v127, 0x3d800000, v126
	v_cndmask_b32_e64 v126, v127, v130, s[8:9]
	v_fma_f32 v127, v132, v242, v128
	v_fmac_f32_e32 v127, v136, v223
	v_fmac_f32_e32 v127, v140, v222
	v_fmac_f32_e32 v127, v144, v221
	v_fmac_f32_e32 v127, v148, v220
	v_fmac_f32_e32 v127, v152, v219
	v_fmac_f32_e32 v127, v156, v218
	v_fmac_f32_e32 v127, v160, v217
	v_fmac_f32_e32 v127, v164, v216
	v_fmac_f32_e32 v127, v168, v215
	v_fmac_f32_e32 v127, v172, v214
	v_mov_b32_e32 v130, v180
	v_fmac_f32_e32 v127, v176, v213
	v_pk_mul_f32 v[130:131], v[130:131], v[206:207]
	s_nop 0
	v_add_f32_e32 v127, v127, v130
	v_add_f32_e32 v127, v127, v131
	v_mov_b32_e32 v130, v188
	v_mov_b32_e32 v131, v192
	v_pk_mul_f32 v[130:131], v[130:131], v[204:205]
	v_mov_b32_e32 v192, v189
	v_add_f32_e32 v127, v127, v130
	v_add_f32_e32 v127, v127, v131
	v_max_f32_e64 v128, -v127, 0
	v_mul_f32_e64 v127, |v127|, s93
	v_exp_f32_e32 v127, v127
	s_nop 0
	v_add_f32_e32 v127, 1.0, v127
	s_nop 0
	s_nop 1
	s_nop 0
	s_nop 0
	v_log_f32_e32 v127, v127
	s_nop 0
	v_mul_f32_e32 v130, 0x3f317217, v127
	v_fma_f32 v130, v127, s94, -v130
	v_fmac_f32_e32 v130, 0x3377d1cf, v127
	v_fmac_f32_e32 v130, 0x3f317217, v127
	v_cmp_lt_f32_e64 s[0:1], |v127|, s95
	s_nop 1
	v_cndmask_b32_e64 v127, v127, v130, s[0:1]
	s_nop 0
	s_nop 0
	v_add_f32_e32 v127, v128, v127
	v_mul_f32_e32 v128, 0xbd800000, v127
	v_mov_b32_e32 v130, v49
	s_nop 1
	v_mov_b32_dpp v130, v128 row_shr:1 row_mask:0xf bank_mask:0xf
	v_fmac_f32_e32 v130, 0xbd800000, v127
	s_nop 1
	v_add_f32_dpp v128, v130, v130 row_shr:2 row_mask:0xf bank_mask:0xf bound_ctrl:1
	v_mov_b32_e32 v130, v49
	s_nop 0
	v_add_f32_dpp v128, v128, v128 row_shr:4 row_mask:0xf bank_mask:0xf bound_ctrl:1
	s_nop 1
	v_add_f32_dpp v128, v128, v128 row_shr:8 row_mask:0xf bank_mask:0xf bound_ctrl:1
	s_nop 1
	v_mov_b32_dpp v130, v128 row_bcast:15 row_mask:0xa bank_mask:0xf
	v_add_f32_e32 v128, v128, v130
	v_mov_b32_e32 v130, v49
	s_nop 1
	v_mov_b32_dpp v130, v128 row_bcast:31 row_mask:0xc bank_mask:0xf
	v_add_f32_e32 v128, v128, v130
	s_nop 0
	v_readlane_b32 s6, v128, 63
	s_nop 1
	v_sub_f32_e32 v130, s6, v128
	v_fmac_f32_e32 v128, 0x3d800000, v127
	v_cndmask_b32_e64 v127, v128, v130, s[8:9]
	v_pk_mul_f32 v[130:131], v[184:185], v[206:207]
	s_nop 0
	v_add_f32_e32 v128, v129, v130
	v_add_f32_e32 v130, v128, v131
	v_pk_mul_f32 v[128:129], v[192:193], v[204:205]
	s_nop 0
	v_add_f32_e32 v128, v130, v128
	v_add_f32_e32 v128, v128, v129
	v_max_f32_e64 v129, -v128, 0
	v_mul_f32_e64 v128, |v128|, s93
	v_exp_f32_e32 v128, v128
	s_nop 0
	v_add_f32_e32 v128, 1.0, v128
	s_nop 0
	s_nop 1
	s_nop 0
	s_nop 0
	v_log_f32_e32 v128, v128
	s_nop 0
	v_mul_f32_e32 v130, 0x3f317217, v128
	v_fma_f32 v130, v128, s94, -v130
	v_fmac_f32_e32 v130, 0x3377d1cf, v128
	v_fmac_f32_e32 v130, 0x3f317217, v128
	v_cmp_lt_f32_e64 s[0:1], |v128|, s95
	s_nop 1
	v_cndmask_b32_e64 v128, v128, v130, s[0:1]
	s_nop 0
	s_nop 0
	v_add_f32_e32 v128, v129, v128
	v_mul_f32_e32 v129, 0xbd800000, v128
	v_mov_b32_e32 v130, v49
	s_nop 1
	v_mov_b32_dpp v130, v129 row_shr:1 row_mask:0xf bank_mask:0xf
	v_fmac_f32_e32 v130, 0xbd800000, v128
	s_nop 1
	v_add_f32_dpp v129, v130, v130 row_shr:2 row_mask:0xf bank_mask:0xf bound_ctrl:1
	v_mov_b32_e32 v130, v49
	s_nop 0
	v_add_f32_dpp v129, v129, v129 row_shr:4 row_mask:0xf bank_mask:0xf bound_ctrl:1
	s_nop 1
	v_add_f32_dpp v129, v129, v129 row_shr:8 row_mask:0xf bank_mask:0xf bound_ctrl:1
	s_nop 1
	v_mov_b32_dpp v130, v129 row_bcast:15 row_mask:0xa bank_mask:0xf
	v_add_f32_e32 v129, v129, v130
	v_mov_b32_e32 v130, v49
	s_nop 1
	v_mov_b32_dpp v130, v129 row_bcast:31 row_mask:0xc bank_mask:0xf
	v_add_f32_e32 v129, v129, v130
	s_nop 0
	v_readlane_b32 s7, v129, 63
	s_nop 1
	v_sub_f32_e32 v130, s7, v129
	v_fmac_f32_e32 v129, 0x3d800000, v128
	v_cndmask_b32_e64 v130, v129, v130, s[8:9]
	v_mov_b32_e32 v128, v110
	v_mov_b32_e32 v129, v114
	v_pk_mul_f32 v[128:129], v[128:129], v[206:207]
	v_mov_b32_e32 v114, v111
	v_add_f32_e32 v58, v58, v128
	v_add_f32_e32 v58, v58, v129
	v_mov_b32_e32 v128, v118
	v_mov_b32_e32 v129, v122
	v_pk_mul_f32 v[128:129], v[128:129], v[204:205]
	v_mov_b32_e32 v122, v119
	v_add_f32_e32 v58, v58, v128
	v_add_f32_e32 v58, v58, v129
	v_max_f32_e64 v62, -v58, 0
	v_mul_f32_e64 v58, |v58|, s93
	v_exp_f32_e32 v58, v58
	s_nop 0
	v_add_f32_e32 v58, 1.0, v58
	s_nop 0
	s_nop 1
	s_nop 0
	s_nop 0
	v_log_f32_e32 v58, v58
	s_nop 0
	v_mul_f32_e32 v66, 0x3f317217, v58
	v_fma_f32 v66, v58, s94, -v66
	v_fmac_f32_e32 v66, 0x3377d1cf, v58
	v_fmac_f32_e32 v66, 0x3f317217, v58
	v_cmp_lt_f32_e64 s[0:1], |v58|, s95
	s_nop 1
	v_cndmask_b32_e64 v58, v58, v66, s[0:1]
	s_nop 0
	s_nop 0
	v_add_f32_e32 v58, v62, v58
	v_mul_f32_e32 v62, 0xbd800000, v58
	v_mov_b32_e32 v66, v49
	s_nop 1
	v_mov_b32_dpp v66, v62 row_shr:1 row_mask:0xf bank_mask:0xf
	v_fmac_f32_e32 v66, 0xbd800000, v58
	s_nop 1
	v_add_f32_dpp v62, v66, v66 row_shr:2 row_mask:0xf bank_mask:0xf bound_ctrl:1
	v_mov_b32_e32 v66, v49
	s_nop 0
	v_add_f32_dpp v62, v62, v62 row_shr:4 row_mask:0xf bank_mask:0xf bound_ctrl:1
	s_nop 1
	v_add_f32_dpp v62, v62, v62 row_shr:8 row_mask:0xf bank_mask:0xf bound_ctrl:1
	s_nop 1
	v_mov_b32_dpp v66, v62 row_bcast:15 row_mask:0xa bank_mask:0xf
	v_add_f32_e32 v62, v62, v66
	v_mov_b32_e32 v66, v49
	s_nop 1
	v_mov_b32_dpp v66, v62 row_bcast:31 row_mask:0xc bank_mask:0xf
	v_add_f32_e32 v62, v62, v66
	s_nop 0
	v_readlane_b32 s91, v62, 63
	s_nop 1
	v_sub_f32_e32 v66, s91, v62
	v_fmac_f32_e32 v62, 0x3d800000, v58
	v_pk_mul_f32 v[58:59], v[114:115], v[206:207]
	v_cndmask_b32_e64 v62, v62, v66, s[8:9]
	v_add_f32_e32 v58, v63, v58
	v_add_f32_e32 v63, v58, v59
	v_pk_mul_f32 v[58:59], v[122:123], v[204:205]
	v_lshlrev_b32_e32 v66, 16, v51
	v_add_f32_e32 v58, v63, v58
	v_add_f32_e32 v58, v58, v59
	v_max_f32_e64 v59, -v58, 0
	v_mul_f32_e64 v58, |v58|, s93
	v_exp_f32_e32 v58, v58
	s_nop 0
	v_add_f32_e32 v58, 1.0, v58
	s_nop 0
	s_nop 1
	s_nop 0
	s_nop 0
	v_log_f32_e32 v58, v58
	s_nop 0
	v_mul_f32_e32 v63, 0x3f317217, v58
	v_fma_f32 v63, v58, s94, -v63
	v_fmac_f32_e32 v63, 0x3377d1cf, v58
	v_fmac_f32_e32 v63, 0x3f317217, v58
	v_cmp_lt_f32_e64 s[0:1], |v58|, s95
	s_nop 1
	v_cndmask_b32_e64 v58, v58, v63, s[0:1]
	s_nop 0
	s_nop 0
	v_add_f32_e32 v58, v59, v58
	v_mul_f32_e32 v59, 0xbd800000, v58
	v_mov_b32_e32 v63, v49
	s_nop 1
	v_mov_b32_dpp v63, v59 row_shr:1 row_mask:0xf bank_mask:0xf
	v_fmac_f32_e32 v63, 0xbd800000, v58
	s_nop 1
	v_add_f32_dpp v59, v63, v63 row_shr:2 row_mask:0xf bank_mask:0xf bound_ctrl:1
	v_mov_b32_e32 v63, v49
	s_nop 0
	v_add_f32_dpp v59, v59, v59 row_shr:4 row_mask:0xf bank_mask:0xf bound_ctrl:1
	s_nop 1
	v_add_f32_dpp v59, v59, v59 row_shr:8 row_mask:0xf bank_mask:0xf bound_ctrl:1
	s_nop 1
	v_mov_b32_dpp v63, v59 row_bcast:15 row_mask:0xa bank_mask:0xf
	v_add_f32_e32 v59, v59, v63
	v_mov_b32_e32 v63, v49
	s_nop 1
	v_mov_b32_dpp v63, v59 row_bcast:31 row_mask:0xc bank_mask:0xf
	v_add_f32_e32 v59, v59, v63
	s_nop 0
	v_readlane_b32 s20, v59, 63
	s_nop 1
	v_sub_f32_e32 v63, s20, v59
	v_fmac_f32_e32 v59, 0x3d800000, v58
	v_cndmask_b32_e64 v63, v59, v63, s[8:9]
	v_mov_b32_e32 v58, v112
	v_mov_b32_e32 v59, v116
	v_pk_mul_f32 v[58:59], v[58:59], v[206:207]
	v_mov_b32_e32 v116, v113
	v_add_f32_e32 v58, v60, v58
	v_add_f32_e32 v60, v58, v59
	v_mov_b32_e32 v58, v120
	v_mov_b32_e32 v59, v124
	v_pk_mul_f32 v[58:59], v[58:59], v[204:205]
	v_mov_b32_e32 v124, v121
	v_add_f32_e32 v58, v60, v58
	v_add_f32_e32 v58, v58, v59
	v_max_f32_e64 v59, -v58, 0
	v_mul_f32_e64 v58, |v58|, s93
	v_exp_f32_e32 v58, v58
	s_nop 0
	v_add_f32_e32 v58, 1.0, v58
	s_nop 0
	s_nop 1
	s_nop 0
	s_nop 0
	v_log_f32_e32 v58, v58
	s_nop 0
	v_mul_f32_e32 v60, 0x3f317217, v58
	v_fma_f32 v60, v58, s94, -v60
	v_fmac_f32_e32 v60, 0x3377d1cf, v58
	v_fmac_f32_e32 v60, 0x3f317217, v58
	v_cmp_lt_f32_e64 s[0:1], |v58|, s95
	s_nop 1
	v_cndmask_b32_e64 v58, v58, v60, s[0:1]
	s_nop 0
	s_nop 0
	v_add_f32_e32 v58, v59, v58
	v_mul_f32_e32 v59, 0xbd800000, v58
	v_mov_b32_e32 v60, v49
	s_nop 1
	v_mov_b32_dpp v60, v59 row_shr:1 row_mask:0xf bank_mask:0xf
	v_fmac_f32_e32 v60, 0xbd800000, v58
	s_nop 1
	v_add_f32_dpp v59, v60, v60 row_shr:2 row_mask:0xf bank_mask:0xf bound_ctrl:1
	v_mov_b32_e32 v60, v49
	s_nop 0
	v_add_f32_dpp v59, v59, v59 row_shr:4 row_mask:0xf bank_mask:0xf bound_ctrl:1
	s_nop 1
	v_add_f32_dpp v59, v59, v59 row_shr:8 row_mask:0xf bank_mask:0xf bound_ctrl:1
	s_nop 1
	v_mov_b32_dpp v60, v59 row_bcast:15 row_mask:0xa bank_mask:0xf
	v_add_f32_e32 v59, v59, v60
	v_mov_b32_e32 v60, v49
	s_nop 1
	v_mov_b32_dpp v60, v59 row_bcast:31 row_mask:0xc bank_mask:0xf
	v_add_f32_e32 v59, v59, v60
	s_nop 0
	v_readlane_b32 s21, v59, 63
	s_nop 1
	v_sub_f32_e32 v60, s21, v59
	v_fmac_f32_e32 v59, 0x3d800000, v58
	v_cndmask_b32_e64 v60, v59, v60, s[8:9]
	v_pk_mul_f32 v[58:59], v[116:117], v[206:207]
	s_nop 0
	v_add_f32_e32 v58, v61, v58
	v_add_f32_e32 v61, v58, v59
	v_pk_mul_f32 v[58:59], v[124:125], v[204:205]
	s_nop 0
	v_add_f32_e32 v58, v61, v58
	v_add_f32_e32 v58, v58, v59
	v_max_f32_e64 v59, -v58, 0
	v_mul_f32_e64 v58, |v58|, s93
	v_exp_f32_e32 v58, v58
	s_nop 0
	v_add_f32_e32 v58, 1.0, v58
	s_nop 0
	s_nop 1
	s_nop 0
	s_nop 0
	v_log_f32_e32 v58, v58
	s_nop 0
	v_mul_f32_e32 v61, 0x3f317217, v58
	v_fma_f32 v61, v58, s94, -v61
	v_fmac_f32_e32 v61, 0x3377d1cf, v58
	v_fmac_f32_e32 v61, 0x3f317217, v58
	v_cmp_lt_f32_e64 s[0:1], |v58|, s95
	s_nop 1
	v_cndmask_b32_e64 v58, v58, v61, s[0:1]
	s_nop 0
	s_nop 0
	v_add_f32_e32 v58, v59, v58
	v_mul_f32_e32 v59, 0xbd800000, v58
	v_mov_b32_e32 v61, v49
	v_readlane_b32 s0, v254, 10
	s_add_u32 s0, s90, s0
	v_mov_b32_dpp v61, v59 row_shr:1 row_mask:0xf bank_mask:0xf
	v_fmac_f32_e32 v61, 0xbd800000, v58
	v_readlane_b32 s1, v254, 12
	s_addc_u32 s1, s15, s1
	v_add_f32_dpp v59, v61, v61 row_shr:2 row_mask:0xf bank_mask:0xf bound_ctrl:1
	v_mov_b32_e32 v61, v49
	s_lshl_b64 s[0:1], s[0:1], 10
	v_add_f32_dpp v59, v59, v59 row_shr:4 row_mask:0xf bank_mask:0xf bound_ctrl:1
	s_nop 1
	v_add_f32_dpp v59, v59, v59 row_shr:8 row_mask:0xf bank_mask:0xf bound_ctrl:1
	s_nop 1
	v_mov_b32_dpp v61, v59 row_bcast:15 row_mask:0xa bank_mask:0xf
	v_add_f32_e32 v59, v59, v61
	v_mov_b32_e32 v61, v49
	s_nop 1
	v_mov_b32_dpp v61, v59 row_bcast:31 row_mask:0xc bank_mask:0xf
	v_add_f32_e32 v59, v59, v61
	s_nop 0
	v_readlane_b32 s18, v59, 63
	s_nop 1
	v_sub_f32_e32 v61, s18, v59
	v_fmac_f32_e32 v59, 0x3d800000, v58
	v_cndmask_b32_e64 v58, v59, v61, s[8:9]
	v_mul_f32_e32 v59, 0x3fb8aa3b, v126
	v_exp_f32_e32 v72, v59
	v_mul_f32_e32 v59, 0x3fb8aa3b, v127
	v_mul_f32_e32 v58, 0x3fb8aa3b, v58
	v_exp_f32_e32 v73, v59
	v_exp_f32_e32 v78, v58
	v_cvt_pk_bf16_f32 v58, v48, v72
	v_mul_f32_e32 v48, v48, v64
	v_mul_f32_e32 v59, 0x3fb8aa3b, v130
	v_cvt_pk_bf16_f32 v48, v48, s0
	v_exp_f32_e32 v74, v59
	ds_write_b16 v208, v48 offset:59904
	v_mul_f32_e32 v48, v72, v65
	v_mul_f32_e32 v59, 0x3fb8aa3b, v62
	v_cvt_pk_bf16_f32 v48, v48, s0
	v_exp_f32_e32 v75, v59
	ds_write_b16 v208, v48 offset:60048
	v_mul_f32_e32 v48, v73, v66
	v_mul_f32_e32 v59, 0x3fb8aa3b, v63
	v_cvt_pk_bf16_f32 v48, v48, s0
	v_exp_f32_e32 v76, v59
	ds_write_b16 v208, v48 offset:60192
	v_mul_f32_e32 v48, v74, v67
	v_mul_f32_e32 v59, 0x3fb8aa3b, v60
	v_cvt_pk_bf16_f32 v48, v48, s0
	v_exp_f32_e32 v77, v59
	ds_write_b16 v208, v48 offset:60336
	v_mul_f32_e32 v48, v75, v68
	v_cvt_pk_bf16_f32 v48, v48, s0
	ds_write_b16 v208, v48 offset:60480
	v_mul_f32_e32 v48, v76, v69
	v_cvt_pk_bf16_f32 v48, v48, s0
	ds_write_b16 v208, v48 offset:60624
	v_mul_f32_e32 v48, v77, v70
	v_cvt_pk_bf16_f32 v48, v48, s0
	ds_write_b16 v208, v48 offset:60768
	v_mul_f32_e32 v48, v78, v71
	v_cvt_pk_bf16_f32 v59, v73, v74
	v_cvt_pk_bf16_f32 v60, v75, v76
	v_cvt_pk_bf16_f32 v61, v77, v78
	v_lshl_add_u64 v[62:63], v[202:203], 0, s[0:1]
	v_cvt_pk_bf16_f32 v48, v48, s0
	global_store_dwordx4 v[62:63], v[58:61], off
	ds_write_b16 v208, v48 offset:60912
	s_and_saveexec_b64 s[0:1], s[10:11]
	s_cbranch_execz .LBB0_667
	v_mul_f32_e32 v48, s4, v240
	v_exp_f32_e32 v58, v48
	v_mul_f32_e32 v48, s5, v240
	v_exp_f32_e32 v59, v48
	v_mul_f32_e32 v48, s6, v240
	v_exp_f32_e32 v60, v48
	v_mul_f32_e32 v48, s7, v240
	v_exp_f32_e32 v61, v48
	v_mul_f32_e32 v48, s91, v240
	v_exp_f32_e32 v62, v48
	v_mul_f32_e32 v48, s20, v240
	v_exp_f32_e32 v63, v48
	v_mul_f32_e32 v48, s21, v240
	v_exp_f32_e32 v64, v48
	v_mul_f32_e32 v48, s18, v240
	v_exp_f32_e32 v65, v48
	s_add_u32 s4, s16, s88
	s_addc_u32 s5, s17, s89
	global_store_dwordx4 v49, v[58:61], s[4:5] offset:128
	global_store_dwordx4 v49, v[62:65], s[4:5] offset:144
.LBB0_667:
	s_or_b64 exec, exec, s[0:1]
	v_lshrrev_b32_e32 v182, 6, v198
	v_and_b32_e32 v183, 1, v182
	v_lshrrev_b32_e32 v182, 1, v182
	v_mul_u32_u24_e32 v183, 0x3000, v183
	v_lshl_add_u32 v183, v182, 7, v183
	v_lshl_add_u32 v182, v182, 6, v183
	v_add_u32_e32 v182, 0x1b000, v182
	ds_read_b128 v[58:61], v182 offset:24752
	ds_read_b128 v[126:129], v182 offset:24736
	ds_read_b128 v[62:65], v182 offset:176
	ds_read_b128 v[130:133], v182 offset:160
	ds_read_b128 v[66:69], v182 offset:944
	ds_read_b128 v[134:137], v182 offset:928
	ds_read_b128 v[70:73], v182 offset:1712
	ds_read_b128 v[138:141], v182 offset:1696
	ds_read_b128 v[74:77], v182 offset:2480
	ds_read_b128 v[142:145], v182 offset:2464
	ds_read_b128 v[78:81], v182 offset:3248
	ds_read_b128 v[146:149], v182 offset:3232
	s_waitcnt lgkmcnt(8)
	ds_read_b128 v[82:85], v182 offset:4016
	ds_read_b128 v[150:153], v182 offset:4000
	ds_read_b128 v[86:89], v182 offset:4784
	ds_read_b128 v[154:157], v182 offset:4768
	s_waitcnt lgkmcnt(8)
	ds_read_b128 v[90:93], v182 offset:5552
	ds_read_b128 v[158:161], v182 offset:5536
	ds_read_b128 v[94:97], v182 offset:6320
	ds_read_b128 v[162:165], v182 offset:6304
	s_waitcnt lgkmcnt(8)
	ds_read_b128 v[98:101], v182 offset:7088
	ds_read_b128 v[166:169], v182 offset:7072
	ds_read_b128 v[102:105], v182 offset:7856
	ds_read_b128 v[170:173], v182 offset:7840
	s_waitcnt lgkmcnt(8)
	ds_read_b128 v[106:109], v182 offset:8624
	ds_read_b128 v[174:177], v182 offset:8608
	ds_read_b128 v[110:113], v182 offset:9392
	ds_read_b128 v[178:181], v182 offset:9376
	s_waitcnt lgkmcnt(8)
	ds_read_b128 v[114:117], v182 offset:10160
	ds_read_b128 v[182:185], v182 offset:10144
	s_waitcnt lgkmcnt(14)
	v_fma_f32 v58, v62, v242, v58
	s_waitcnt lgkmcnt(14)
	v_fma_f32 v48, v130, v242, v126
	s_waitcnt lgkmcnt(14)
	v_fmac_f32_e32 v48, v134, v223
	s_waitcnt lgkmcnt(14)
	v_fmac_f32_e32 v48, v138, v222
	s_waitcnt lgkmcnt(14)
	v_fmac_f32_e32 v48, v142, v221
	s_waitcnt lgkmcnt(14)
	v_fmac_f32_e32 v48, v146, v220
	s_waitcnt lgkmcnt(14)
	v_fmac_f32_e32 v48, v150, v219
	s_waitcnt lgkmcnt(14)
	v_fmac_f32_e32 v48, v154, v218
	s_waitcnt lgkmcnt(12)
	v_fmac_f32_e32 v48, v158, v217
	s_waitcnt lgkmcnt(10)
	v_fmac_f32_e32 v48, v162, v216
	s_waitcnt lgkmcnt(8)
	v_fmac_f32_e32 v48, v166, v215
	s_waitcnt lgkmcnt(6)
	v_fmac_f32_e32 v48, v170, v214
	s_waitcnt lgkmcnt(2)
	v_mov_b32_e32 v118, v178
	s_waitcnt lgkmcnt(0)
	v_mov_b32_e32 v119, v182
	v_fmac_f32_e32 v48, v174, v213
	v_pk_mul_f32 v[118:119], v[118:119], v[206:207]
	v_mov_b32_e32 v182, v179
	v_add_f32_e32 v48, v48, v118
	v_add_f32_e32 v48, v48, v119
	v_lshrrev_b32_e32 v190, 6, v198
	v_and_b32_e32 v191, 1, v190
	v_lshrrev_b32_e32 v190, 1, v190
	v_mul_u32_u24_e32 v191, 0x3000, v191
	v_lshl_add_u32 v191, v190, 7, v191
	v_lshl_add_u32 v190, v190, 6, v191
	v_add_u32_e32 v190, 0x1b000, v190
	ds_read_b128 v[118:121], v190 offset:10928
	ds_read_b128 v[186:189], v190 offset:10912
	ds_read_b128 v[122:125], v190 offset:11696
	ds_read_b128 v[190:193], v190 offset:11680
	v_fmac_f32_e32 v129, v133, v242
	v_fmac_f32_e32 v129, v137, v223
	v_fmac_f32_e32 v129, v141, v222
	v_fmac_f32_e32 v129, v145, v221
	v_fmac_f32_e32 v129, v149, v220
	v_fmac_f32_e32 v129, v153, v219
	v_fmac_f32_e32 v129, v157, v218
	v_fmac_f32_e32 v129, v161, v217
	v_fmac_f32_e32 v129, v165, v216
	v_fmac_f32_e32 v129, v169, v215
	v_fmac_f32_e32 v129, v173, v214
	v_fmac_f32_e32 v129, v177, v213
	v_fmac_f32_e32 v58, v66, v223
	v_fmac_f32_e32 v58, v70, v222
	v_fmac_f32_e32 v58, v74, v221
	v_fmac_f32_e32 v58, v78, v220
	v_fmac_f32_e32 v58, v82, v219
	v_fmac_f32_e32 v58, v86, v218
	v_fmac_f32_e32 v58, v90, v217
	v_fmac_f32_e32 v58, v94, v216
	v_fmac_f32_e32 v58, v98, v215
	v_fmac_f32_e32 v58, v102, v214
	v_fmac_f32_e32 v58, v106, v213
	v_fma_f32 v63, v63, v242, v59
	v_fmac_f32_e32 v63, v67, v223
	v_fmac_f32_e32 v63, v71, v222
	v_fmac_f32_e32 v63, v75, v221
	v_fmac_f32_e32 v63, v79, v220
	v_fmac_f32_e32 v63, v83, v219
	v_fmac_f32_e32 v63, v87, v218
	v_fmac_f32_e32 v63, v91, v217
	v_fmac_f32_e32 v63, v95, v216
	v_fmac_f32_e32 v63, v99, v215
	v_fmac_f32_e32 v63, v103, v214
	v_fmac_f32_e32 v63, v107, v213
	v_fma_f32 v60, v64, v242, v60
	v_fmac_f32_e32 v60, v68, v223
	v_fmac_f32_e32 v60, v72, v222
	v_fmac_f32_e32 v60, v76, v221
	v_fmac_f32_e32 v60, v80, v220
	v_fmac_f32_e32 v60, v84, v219
	v_fmac_f32_e32 v60, v88, v218
	v_fmac_f32_e32 v60, v92, v217
	v_fmac_f32_e32 v60, v96, v216
	v_fmac_f32_e32 v60, v100, v215
	v_fmac_f32_e32 v60, v104, v214
	v_fmac_f32_e32 v60, v108, v213
	v_fmac_f32_e32 v61, v65, v242
	v_fmac_f32_e32 v61, v69, v223
	v_fmac_f32_e32 v61, v73, v222
	v_fmac_f32_e32 v61, v77, v221
	v_fmac_f32_e32 v61, v81, v220
	v_fmac_f32_e32 v61, v85, v219
	v_fmac_f32_e32 v61, v89, v218
	v_fmac_f32_e32 v61, v93, v217
	v_fmac_f32_e32 v61, v97, v216
	v_fmac_f32_e32 v61, v101, v215
	v_fmac_f32_e32 v61, v105, v214
	v_fmac_f32_e32 v61, v109, v213
	v_lshlrev_b32_e32 v64, 16, v54
	v_and_b32_e32 v65, 0xffff0000, v54
	v_and_b32_e32 v67, 0xffff0000, v55
	v_lshlrev_b32_e32 v68, 16, v56
	v_and_b32_e32 v69, 0xffff0000, v56
	v_lshlrev_b32_e32 v70, 16, v57
	v_and_b32_e32 v71, 0xffff0000, v57
	s_waitcnt lgkmcnt(2)
	v_mov_b32_e32 v244, v186
	s_waitcnt lgkmcnt(0)
	v_mov_b32_e32 v245, v190
	v_pk_mul_f32 v[244:245], v[244:245], v[204:205]
	v_mov_b32_e32 v190, v187
	v_add_f32_e32 v48, v48, v244
	v_add_f32_e32 v48, v48, v245
	v_max_f32_e64 v126, -v48, 0
	v_mul_f32_e64 v48, |v48|, s93
	v_exp_f32_e32 v48, v48
	s_nop 0
	v_add_f32_e32 v48, 1.0, v48
	s_nop 0
	s_nop 1
	s_nop 0
	s_nop 0
	v_log_f32_e32 v48, v48
	s_nop 0
	v_mul_f32_e32 v130, 0x3f317217, v48
	v_fma_f32 v130, v48, s94, -v130
	v_fmac_f32_e32 v130, 0x3377d1cf, v48
	v_fmac_f32_e32 v130, 0x3f317217, v48
	v_cmp_lt_f32_e64 s[0:1], |v48|, s95
	s_nop 1
	v_cndmask_b32_e64 v48, v48, v130, s[0:1]
	s_nop 0
	s_nop 0
	v_add_f32_e32 v48, v126, v48
	v_mul_f32_e32 v126, 0xbd800000, v48
	v_mov_b32_e32 v130, v49
	s_nop 1
	v_mov_b32_dpp v130, v126 row_shr:1 row_mask:0xf bank_mask:0xf
	v_fmac_f32_e32 v130, 0xbd800000, v48
	s_nop 1
	v_add_f32_dpp v126, v130, v130 row_shr:2 row_mask:0xf bank_mask:0xf bound_ctrl:1
	v_mov_b32_e32 v130, v49
	s_nop 0
	v_add_f32_dpp v126, v126, v126 row_shr:4 row_mask:0xf bank_mask:0xf bound_ctrl:1
	s_nop 1
	v_add_f32_dpp v126, v126, v126 row_shr:8 row_mask:0xf bank_mask:0xf bound_ctrl:1
	s_nop 1
	v_mov_b32_dpp v130, v126 row_bcast:15 row_mask:0xa bank_mask:0xf
	v_add_f32_e32 v126, v126, v130
	v_mov_b32_e32 v130, v49
	s_nop 1
	v_mov_b32_dpp v130, v126 row_bcast:31 row_mask:0xc bank_mask:0xf
	v_add_f32_e32 v126, v126, v130
	s_nop 0
	v_readlane_b32 s4, v126, 63
	s_nop 1
	v_sub_f32_e32 v130, s4, v126
	v_fmac_f32_e32 v126, 0x3d800000, v48
	v_cndmask_b32_e64 v48, v126, v130, s[8:9]
	v_fma_f32 v130, v131, v242, v127
	v_fmac_f32_e32 v130, v135, v223
	v_fmac_f32_e32 v130, v139, v222
	v_fmac_f32_e32 v130, v143, v221
	v_fmac_f32_e32 v130, v147, v220
	v_fmac_f32_e32 v130, v151, v219
	v_fmac_f32_e32 v130, v155, v218
	v_fmac_f32_e32 v130, v159, v217
	v_fmac_f32_e32 v130, v163, v216
	v_fmac_f32_e32 v130, v167, v215
	v_fmac_f32_e32 v130, v171, v214
	v_fmac_f32_e32 v130, v175, v213
	v_pk_mul_f32 v[126:127], v[182:183], v[206:207]
	v_mov_b32_e32 v131, v184
	v_add_f32_e32 v126, v130, v126
	v_add_f32_e32 v130, v126, v127
	v_pk_mul_f32 v[126:127], v[190:191], v[204:205]
	v_mov_b32_e32 v184, v181
	v_add_f32_e32 v126, v130, v126
	v_add_f32_e32 v126, v126, v127
	v_max_f32_e64 v127, -v126, 0
	v_mul_f32_e64 v126, |v126|, s93
	v_exp_f32_e32 v126, v126
	v_mul_f32_e32 v48, 0x3fb8aa3b, v48
	v_exp_f32_e32 v48, v48
	v_add_f32_e32 v126, 1.0, v126
	s_nop 0
	s_nop 1
	s_nop 0
	s_nop 0
	v_log_f32_e32 v126, v126
	s_nop 0
	v_mul_f32_e32 v130, 0x3f317217, v126
	v_fma_f32 v130, v126, s94, -v130
	v_fmac_f32_e32 v130, 0x3377d1cf, v126
	v_fmac_f32_e32 v130, 0x3f317217, v126
	v_cmp_lt_f32_e64 s[0:1], |v126|, s95
	s_nop 1
	v_cndmask_b32_e64 v126, v126, v130, s[0:1]
	s_nop 0
	s_nop 0
	v_add_f32_e32 v126, v127, v126
	v_mul_f32_e32 v127, 0xbd800000, v126
	v_mov_b32_e32 v130, v49
	s_nop 1
	v_mov_b32_dpp v130, v127 row_shr:1 row_mask:0xf bank_mask:0xf
	v_fmac_f32_e32 v130, 0xbd800000, v126
	s_nop 1
	v_add_f32_dpp v127, v130, v130 row_shr:2 row_mask:0xf bank_mask:0xf bound_ctrl:1
	v_mov_b32_e32 v130, v49
	s_nop 0
	v_add_f32_dpp v127, v127, v127 row_shr:4 row_mask:0xf bank_mask:0xf bound_ctrl:1
	s_nop 1
	v_add_f32_dpp v127, v127, v127 row_shr:8 row_mask:0xf bank_mask:0xf bound_ctrl:1
	s_nop 1
	v_mov_b32_dpp v130, v127 row_bcast:15 row_mask:0xa bank_mask:0xf
	v_add_f32_e32 v127, v127, v130
	v_mov_b32_e32 v130, v49
	s_nop 1
	v_mov_b32_dpp v130, v127 row_bcast:31 row_mask:0xc bank_mask:0xf
	v_add_f32_e32 v127, v127, v130
	s_nop 0
	v_readlane_b32 s5, v127, 63
	s_nop 1
	v_sub_f32_e32 v130, s5, v127
	v_fmac_f32_e32 v127, 0x3d800000, v126
	v_cndmask_b32_e64 v126, v127, v130, s[8:9]
	v_fma_f32 v127, v132, v242, v128
	v_fmac_f32_e32 v127, v136, v223
	v_fmac_f32_e32 v127, v140, v222
	v_fmac_f32_e32 v127, v144, v221
	v_fmac_f32_e32 v127, v148, v220
	v_fmac_f32_e32 v127, v152, v219
	v_fmac_f32_e32 v127, v156, v218
	v_fmac_f32_e32 v127, v160, v217
	v_fmac_f32_e32 v127, v164, v216
	v_fmac_f32_e32 v127, v168, v215
	v_fmac_f32_e32 v127, v172, v214
	v_mov_b32_e32 v130, v180
	v_fmac_f32_e32 v127, v176, v213
	v_pk_mul_f32 v[130:131], v[130:131], v[206:207]
	s_nop 0
	v_add_f32_e32 v127, v127, v130
	v_add_f32_e32 v127, v127, v131
	v_mov_b32_e32 v130, v188
	v_mov_b32_e32 v131, v192
	v_pk_mul_f32 v[130:131], v[130:131], v[204:205]
	v_mov_b32_e32 v192, v189
	v_add_f32_e32 v127, v127, v130
	v_add_f32_e32 v127, v127, v131
	v_max_f32_e64 v128, -v127, 0
	v_mul_f32_e64 v127, |v127|, s93
	v_exp_f32_e32 v127, v127
	s_nop 0
	v_add_f32_e32 v127, 1.0, v127
	s_nop 0
	s_nop 1
	s_nop 0
	s_nop 0
	v_log_f32_e32 v127, v127
	s_nop 0
	v_mul_f32_e32 v130, 0x3f317217, v127
	v_fma_f32 v130, v127, s94, -v130
	v_fmac_f32_e32 v130, 0x3377d1cf, v127
	v_fmac_f32_e32 v130, 0x3f317217, v127
	v_cmp_lt_f32_e64 s[0:1], |v127|, s95
	s_nop 1
	v_cndmask_b32_e64 v127, v127, v130, s[0:1]
	s_nop 0
	s_nop 0
	v_add_f32_e32 v127, v128, v127
	v_mul_f32_e32 v128, 0xbd800000, v127
	v_mov_b32_e32 v130, v49
	s_nop 1
	v_mov_b32_dpp v130, v128 row_shr:1 row_mask:0xf bank_mask:0xf
	v_fmac_f32_e32 v130, 0xbd800000, v127
	s_nop 1
	v_add_f32_dpp v128, v130, v130 row_shr:2 row_mask:0xf bank_mask:0xf bound_ctrl:1
	v_mov_b32_e32 v130, v49
	s_nop 0
	v_add_f32_dpp v128, v128, v128 row_shr:4 row_mask:0xf bank_mask:0xf bound_ctrl:1
	s_nop 1
	v_add_f32_dpp v128, v128, v128 row_shr:8 row_mask:0xf bank_mask:0xf bound_ctrl:1
	s_nop 1
	v_mov_b32_dpp v130, v128 row_bcast:15 row_mask:0xa bank_mask:0xf
	v_add_f32_e32 v128, v128, v130
	v_mov_b32_e32 v130, v49
	s_nop 1
	v_mov_b32_dpp v130, v128 row_bcast:31 row_mask:0xc bank_mask:0xf
	v_add_f32_e32 v128, v128, v130
	s_nop 0
	v_readlane_b32 s6, v128, 63
	s_nop 1
	v_sub_f32_e32 v130, s6, v128
	v_fmac_f32_e32 v128, 0x3d800000, v127
	v_cndmask_b32_e64 v127, v128, v130, s[8:9]
	v_pk_mul_f32 v[130:131], v[184:185], v[206:207]
	s_nop 0
	v_add_f32_e32 v128, v129, v130
	v_add_f32_e32 v130, v128, v131
	v_pk_mul_f32 v[128:129], v[192:193], v[204:205]
	s_nop 0
	v_add_f32_e32 v128, v130, v128
	v_add_f32_e32 v128, v128, v129
	v_max_f32_e64 v129, -v128, 0
	v_mul_f32_e64 v128, |v128|, s93
	v_exp_f32_e32 v128, v128
	s_nop 0
	v_add_f32_e32 v128, 1.0, v128
	s_nop 0
	s_nop 1
	s_nop 0
	s_nop 0
	v_log_f32_e32 v128, v128
	s_nop 0
	v_mul_f32_e32 v130, 0x3f317217, v128
	v_fma_f32 v130, v128, s94, -v130
	v_fmac_f32_e32 v130, 0x3377d1cf, v128
	v_fmac_f32_e32 v130, 0x3f317217, v128
	v_cmp_lt_f32_e64 s[0:1], |v128|, s95
	s_nop 1
	v_cndmask_b32_e64 v128, v128, v130, s[0:1]
	s_nop 0
	s_nop 0
	v_add_f32_e32 v128, v129, v128
	v_mul_f32_e32 v129, 0xbd800000, v128
	v_mov_b32_e32 v130, v49
	s_nop 1
	v_mov_b32_dpp v130, v129 row_shr:1 row_mask:0xf bank_mask:0xf
	v_fmac_f32_e32 v130, 0xbd800000, v128
	s_nop 1
	v_add_f32_dpp v129, v130, v130 row_shr:2 row_mask:0xf bank_mask:0xf bound_ctrl:1
	v_mov_b32_e32 v130, v49
	s_nop 0
	v_add_f32_dpp v129, v129, v129 row_shr:4 row_mask:0xf bank_mask:0xf bound_ctrl:1
	s_nop 1
	v_add_f32_dpp v129, v129, v129 row_shr:8 row_mask:0xf bank_mask:0xf bound_ctrl:1
	s_nop 1
	v_mov_b32_dpp v130, v129 row_bcast:15 row_mask:0xa bank_mask:0xf
	v_add_f32_e32 v129, v129, v130
	v_mov_b32_e32 v130, v49
	s_nop 1
	v_mov_b32_dpp v130, v129 row_bcast:31 row_mask:0xc bank_mask:0xf
	v_add_f32_e32 v129, v129, v130
	s_nop 0
	v_readlane_b32 s7, v129, 63
	s_nop 1
	v_sub_f32_e32 v130, s7, v129
	v_fmac_f32_e32 v129, 0x3d800000, v128
	v_cndmask_b32_e64 v130, v129, v130, s[8:9]
	v_mov_b32_e32 v128, v110
	v_mov_b32_e32 v129, v114
	v_pk_mul_f32 v[128:129], v[128:129], v[206:207]
	v_mov_b32_e32 v114, v111
	v_add_f32_e32 v58, v58, v128
	v_add_f32_e32 v58, v58, v129
	v_mov_b32_e32 v128, v118
	v_mov_b32_e32 v129, v122
	v_pk_mul_f32 v[128:129], v[128:129], v[204:205]
	v_mov_b32_e32 v122, v119
	v_add_f32_e32 v58, v58, v128
	v_add_f32_e32 v58, v58, v129
	v_max_f32_e64 v62, -v58, 0
	v_mul_f32_e64 v58, |v58|, s93
	v_exp_f32_e32 v58, v58
	s_nop 0
	v_add_f32_e32 v58, 1.0, v58
	s_nop 0
	s_nop 1
	s_nop 0
	s_nop 0
	v_log_f32_e32 v58, v58
	s_nop 0
	v_mul_f32_e32 v66, 0x3f317217, v58
	v_fma_f32 v66, v58, s94, -v66
	v_fmac_f32_e32 v66, 0x3377d1cf, v58
	v_fmac_f32_e32 v66, 0x3f317217, v58
	v_cmp_lt_f32_e64 s[0:1], |v58|, s95
	s_nop 1
	v_cndmask_b32_e64 v58, v58, v66, s[0:1]
	s_nop 0
	s_nop 0
	v_add_f32_e32 v58, v62, v58
	v_mul_f32_e32 v62, 0xbd800000, v58
	v_mov_b32_e32 v66, v49
	s_nop 1
	v_mov_b32_dpp v66, v62 row_shr:1 row_mask:0xf bank_mask:0xf
	v_fmac_f32_e32 v66, 0xbd800000, v58
	s_nop 1
	v_add_f32_dpp v62, v66, v66 row_shr:2 row_mask:0xf bank_mask:0xf bound_ctrl:1
	v_mov_b32_e32 v66, v49
	s_nop 0
	v_add_f32_dpp v62, v62, v62 row_shr:4 row_mask:0xf bank_mask:0xf bound_ctrl:1
	s_nop 1
	v_add_f32_dpp v62, v62, v62 row_shr:8 row_mask:0xf bank_mask:0xf bound_ctrl:1
	s_nop 1
	v_mov_b32_dpp v66, v62 row_bcast:15 row_mask:0xa bank_mask:0xf
	v_add_f32_e32 v62, v62, v66
	v_mov_b32_e32 v66, v49
	s_nop 1
	v_mov_b32_dpp v66, v62 row_bcast:31 row_mask:0xc bank_mask:0xf
	v_add_f32_e32 v62, v62, v66
	s_nop 0
	v_readlane_b32 s20, v62, 63
	s_nop 1
	v_sub_f32_e32 v66, s20, v62
	v_fmac_f32_e32 v62, 0x3d800000, v58
	v_pk_mul_f32 v[58:59], v[114:115], v[206:207]
	v_cndmask_b32_e64 v62, v62, v66, s[8:9]
	v_add_f32_e32 v58, v63, v58
	v_add_f32_e32 v63, v58, v59
	v_pk_mul_f32 v[58:59], v[122:123], v[204:205]
	v_lshlrev_b32_e32 v66, 16, v55
	v_add_f32_e32 v58, v63, v58
	v_add_f32_e32 v58, v58, v59
	v_max_f32_e64 v59, -v58, 0
	v_mul_f32_e64 v58, |v58|, s93
	v_exp_f32_e32 v58, v58
	s_nop 0
	v_add_f32_e32 v58, 1.0, v58
	s_nop 0
	s_nop 1
	s_nop 0
	s_nop 0
	v_log_f32_e32 v58, v58
	s_nop 0
	v_mul_f32_e32 v63, 0x3f317217, v58
	v_fma_f32 v63, v58, s94, -v63
	v_fmac_f32_e32 v63, 0x3377d1cf, v58
	v_fmac_f32_e32 v63, 0x3f317217, v58
	v_cmp_lt_f32_e64 s[0:1], |v58|, s95
	s_nop 1
	v_cndmask_b32_e64 v58, v58, v63, s[0:1]
	s_nop 0
	s_nop 0
	v_add_f32_e32 v58, v59, v58
	v_mul_f32_e32 v59, 0xbd800000, v58
	v_mov_b32_e32 v63, v49
	s_nop 1
	v_mov_b32_dpp v63, v59 row_shr:1 row_mask:0xf bank_mask:0xf
	v_fmac_f32_e32 v63, 0xbd800000, v58
	s_nop 1
	v_add_f32_dpp v59, v63, v63 row_shr:2 row_mask:0xf bank_mask:0xf bound_ctrl:1
	v_mov_b32_e32 v63, v49
	s_nop 0
	v_add_f32_dpp v59, v59, v59 row_shr:4 row_mask:0xf bank_mask:0xf bound_ctrl:1
	s_nop 1
	v_add_f32_dpp v59, v59, v59 row_shr:8 row_mask:0xf bank_mask:0xf bound_ctrl:1
	s_nop 1
	v_mov_b32_dpp v63, v59 row_bcast:15 row_mask:0xa bank_mask:0xf
	v_add_f32_e32 v59, v59, v63
	v_mov_b32_e32 v63, v49
	s_nop 1
	v_mov_b32_dpp v63, v59 row_bcast:31 row_mask:0xc bank_mask:0xf
	v_add_f32_e32 v59, v59, v63
	s_nop 0
	v_readlane_b32 s21, v59, 63
	s_nop 1
	v_sub_f32_e32 v63, s21, v59
	v_fmac_f32_e32 v59, 0x3d800000, v58
	v_cndmask_b32_e64 v63, v59, v63, s[8:9]
	v_mov_b32_e32 v58, v112
	v_mov_b32_e32 v59, v116
	v_pk_mul_f32 v[58:59], v[58:59], v[206:207]
	v_mov_b32_e32 v116, v113
	v_add_f32_e32 v58, v60, v58
	v_add_f32_e32 v60, v58, v59
	v_mov_b32_e32 v58, v120
	v_mov_b32_e32 v59, v124
	v_pk_mul_f32 v[58:59], v[58:59], v[204:205]
	v_mov_b32_e32 v124, v121
	v_add_f32_e32 v58, v60, v58
	v_add_f32_e32 v58, v58, v59
	v_max_f32_e64 v59, -v58, 0
	v_mul_f32_e64 v58, |v58|, s93
	v_exp_f32_e32 v58, v58
	s_nop 0
	v_add_f32_e32 v58, 1.0, v58
	s_nop 0
	s_nop 1
	s_nop 0
	s_nop 0
	v_log_f32_e32 v58, v58
	s_nop 0
	v_mul_f32_e32 v60, 0x3f317217, v58
	v_fma_f32 v60, v58, s94, -v60
	v_fmac_f32_e32 v60, 0x3377d1cf, v58
	v_fmac_f32_e32 v60, 0x3f317217, v58
	v_cmp_lt_f32_e64 s[0:1], |v58|, s95
	s_nop 1
	v_cndmask_b32_e64 v58, v58, v60, s[0:1]
	s_nop 0
	s_nop 0
	v_add_f32_e32 v58, v59, v58
	v_mul_f32_e32 v59, 0xbd800000, v58
	v_mov_b32_e32 v60, v49
	s_nop 1
	v_mov_b32_dpp v60, v59 row_shr:1 row_mask:0xf bank_mask:0xf
	v_fmac_f32_e32 v60, 0xbd800000, v58
	s_nop 1
	v_add_f32_dpp v59, v60, v60 row_shr:2 row_mask:0xf bank_mask:0xf bound_ctrl:1
	v_mov_b32_e32 v60, v49
	s_nop 0
	v_add_f32_dpp v59, v59, v59 row_shr:4 row_mask:0xf bank_mask:0xf bound_ctrl:1
	s_nop 1
	v_add_f32_dpp v59, v59, v59 row_shr:8 row_mask:0xf bank_mask:0xf bound_ctrl:1
	s_nop 1
	v_mov_b32_dpp v60, v59 row_bcast:15 row_mask:0xa bank_mask:0xf
	v_add_f32_e32 v59, v59, v60
	v_mov_b32_e32 v60, v49
	s_nop 1
	v_mov_b32_dpp v60, v59 row_bcast:31 row_mask:0xc bank_mask:0xf
	v_add_f32_e32 v59, v59, v60
	s_nop 0
	v_readlane_b32 s18, v59, 63
	s_nop 1
	v_sub_f32_e32 v60, s18, v59
	v_fmac_f32_e32 v59, 0x3d800000, v58
	v_cndmask_b32_e64 v60, v59, v60, s[8:9]
	v_pk_mul_f32 v[58:59], v[116:117], v[206:207]
	s_nop 0
	v_add_f32_e32 v58, v61, v58
	v_add_f32_e32 v61, v58, v59
	v_pk_mul_f32 v[58:59], v[124:125], v[204:205]
	s_nop 0
	v_add_f32_e32 v58, v61, v58
	v_add_f32_e32 v58, v58, v59
	v_max_f32_e64 v59, -v58, 0
	v_mul_f32_e64 v58, |v58|, s93
	v_exp_f32_e32 v58, v58
	s_nop 0
	v_add_f32_e32 v58, 1.0, v58
	s_nop 0
	s_nop 1
	s_nop 0
	s_nop 0
	v_log_f32_e32 v58, v58
	s_nop 0
	v_mul_f32_e32 v61, 0x3f317217, v58
	v_fma_f32 v61, v58, s94, -v61
	v_fmac_f32_e32 v61, 0x3377d1cf, v58
	v_fmac_f32_e32 v61, 0x3f317217, v58
	v_cmp_lt_f32_e64 s[0:1], |v58|, s95
	s_nop 1
	v_cndmask_b32_e64 v58, v58, v61, s[0:1]
	s_nop 0
	s_nop 0
	v_add_f32_e32 v58, v59, v58
	v_mul_f32_e32 v59, 0xbd800000, v58
	v_mov_b32_e32 v61, v49
	v_readlane_b32 s0, v254, 14
	s_add_u32 s0, s90, s0
	v_mov_b32_dpp v61, v59 row_shr:1 row_mask:0xf bank_mask:0xf
	v_fmac_f32_e32 v61, 0xbd800000, v58
	v_readlane_b32 s1, v254, 16
	s_addc_u32 s1, s15, s1
	v_add_f32_dpp v59, v61, v61 row_shr:2 row_mask:0xf bank_mask:0xf bound_ctrl:1
	v_mov_b32_e32 v61, v49
	s_lshl_b64 s[0:1], s[0:1], 10
	v_add_f32_dpp v59, v59, v59 row_shr:4 row_mask:0xf bank_mask:0xf bound_ctrl:1
	s_mov_b64 s[90:91], 0
	s_nop 0
	v_add_f32_dpp v59, v59, v59 row_shr:8 row_mask:0xf bank_mask:0xf bound_ctrl:1
	s_nop 1
	v_mov_b32_dpp v61, v59 row_bcast:15 row_mask:0xa bank_mask:0xf
	v_add_f32_e32 v59, v59, v61
	v_mov_b32_e32 v61, v49
	s_nop 1
	v_mov_b32_dpp v61, v59 row_bcast:31 row_mask:0xc bank_mask:0xf
	v_add_f32_e32 v59, v59, v61
	s_nop 0
	v_readlane_b32 s19, v59, 63
	s_nop 1
	v_sub_f32_e32 v61, s19, v59
	v_fmac_f32_e32 v59, 0x3d800000, v58
	v_cndmask_b32_e64 v58, v59, v61, s[8:9]
	v_mul_f32_e32 v59, 0x3fb8aa3b, v126
	v_exp_f32_e32 v72, v59
	v_mul_f32_e32 v59, 0x3fb8aa3b, v127
	v_mul_f32_e32 v58, 0x3fb8aa3b, v58
	v_exp_f32_e32 v73, v59
	v_exp_f32_e32 v78, v58
	v_cvt_pk_bf16_f32 v58, v48, v72
	v_mul_f32_e32 v48, v48, v64
	v_mul_f32_e32 v59, 0x3fb8aa3b, v130
	v_cvt_pk_bf16_f32 v48, v48, s0
	v_exp_f32_e32 v74, v59
	ds_write_b16 v208, v48 offset:61056
	v_mul_f32_e32 v48, v72, v65
	v_mul_f32_e32 v59, 0x3fb8aa3b, v62
	v_cvt_pk_bf16_f32 v48, v48, s0
	v_exp_f32_e32 v75, v59
	ds_write_b16 v208, v48 offset:61200
	v_mul_f32_e32 v48, v73, v66
	v_mul_f32_e32 v59, 0x3fb8aa3b, v63
	v_cvt_pk_bf16_f32 v48, v48, s0
	v_exp_f32_e32 v76, v59
	ds_write_b16 v208, v48 offset:61344
	v_mul_f32_e32 v48, v74, v67
	v_mul_f32_e32 v59, 0x3fb8aa3b, v60
	v_cvt_pk_bf16_f32 v48, v48, s0
	v_exp_f32_e32 v77, v59
	ds_write_b16 v208, v48 offset:61488
	v_mul_f32_e32 v48, v75, v68
	v_cvt_pk_bf16_f32 v48, v48, s0
	ds_write_b16 v208, v48 offset:61632
	v_mul_f32_e32 v48, v76, v69
	v_cvt_pk_bf16_f32 v48, v48, s0
	ds_write_b16 v208, v48 offset:61776
	v_mul_f32_e32 v48, v77, v70
	v_cvt_pk_bf16_f32 v48, v48, s0
	ds_write_b16 v208, v48 offset:61920
	v_mul_f32_e32 v48, v78, v71
	v_cvt_pk_bf16_f32 v59, v73, v74
	v_cvt_pk_bf16_f32 v60, v75, v76
	v_cvt_pk_bf16_f32 v61, v77, v78
	v_lshl_add_u64 v[62:63], v[202:203], 0, s[0:1]
	v_cvt_pk_bf16_f32 v48, v48, s0
	s_mov_b64 s[0:1], 0
	global_store_dwordx4 v[62:63], v[58:61], off
	ds_write_b16 v208, v48 offset:62064
	s_and_saveexec_b64 vcc, s[10:11]
	s_xor_b64 vcc, exec, vcc
	s_cbranch_execz .LBB0_669
	v_mul_f32_e32 v48, s4, v240
	v_exp_f32_e32 v58, v48
	v_mul_f32_e32 v48, s5, v240
	v_exp_f32_e32 v59, v48
	v_mul_f32_e32 v48, s6, v240
	v_exp_f32_e32 v60, v48
	v_mul_f32_e32 v48, s7, v240
	v_exp_f32_e32 v61, v48
	s_add_u32 s28, s16, s88
	s_addc_u32 s29, s17, s89
	v_mul_f32_e32 v48, s20, v240
	global_store_dwordx4 v49, v[58:61], s[28:29] offset:160
	s_mov_b64 s[90:91], exec
	s_nop 0
	v_exp_f32_e32 v58, v48
	v_mul_f32_e32 v48, s21, v240
	v_exp_f32_e32 v59, v48
	v_mul_f32_e32 v48, s18, v240
	v_exp_f32_e32 v60, v48
	v_mul_f32_e32 v48, s19, v240
	global_store_dwordx3 v49, v[58:60], s[28:29] offset:176
	s_nop 1
	v_exp_f32_e32 v58, v48
